# merged GEMM with LDS reads issued first in each load segment + MLA per-tile DMA block sunk below first QK MFMAs
# speedup vs baseline: 1.0057x; 1.0046x over previous
.LBB0_269:
	ds_read_b128 v[146:149], v152
	ds_read_b128 v[156:159], v152 offset:1024
	ds_read_b128 v[160:163], v152 offset:2048
	ds_read_b128 v[164:167], v152 offset:3072
	ds_read_b128 v[168:171], v153
	ds_read_b128 v[172:175], v153 offset:1024
	ds_read_b128 v[176:179], v153 offset:2048
	ds_read_b128 v[180:183], v153 offset:3072
	ds_read_b128 v[186:189], v153 offset:4096
	ds_read_b128 v[190:193], v153 offset:5120
	ds_read_b128 v[194:197], v153 offset:6144
	ds_read_b128 v[198:201], v153 offset:7168
	s_add_u32 s24, s22, 0xfff80080
	s_addc_u32 s25, s23, -1
	s_cmp_eq_u32 s61, 28
	s_cselect_b32 s27, s9, s25
	s_cselect_b32 s26, s53, s24
	s_cselect_b32 s25, s7, s60
	s_cselect_b32 s24, s58, s59
	v_lshl_add_u64 v[202:203], s[22:23], 0, v[138:139]
	s_add_i32 m0, s21, 0xc000
	global_load_lds_dwordx4 v[202:203], off
	v_lshl_add_u64 v[202:203], s[22:23], 0, v[140:141]
	s_add_i32 m0, s21, 0xe000
	s_nop 0
	global_load_lds_dwordx4 v[202:203], off
	ds_read_b128 v[202:205], v154
	ds_read_b128 v[206:209], v154 offset:1024
	ds_read_b128 v[210:213], v154 offset:2048
	ds_read_b128 v[214:217], v154 offset:3072
	s_waitcnt vmcnt(8)
	s_waitcnt lgkmcnt(0)
	s_barrier
	s_setprio 1
	v_mfma_f32_16x16x32_bf16 v[126:129], v[146:149], v[168:171], v[126:129]
	v_mfma_f32_16x16x32_bf16 v[122:125], v[160:163], v[168:171], v[122:125]
	v_mfma_f32_16x16x32_bf16 v[118:121], v[146:149], v[176:179], v[118:121]
	v_mfma_f32_16x16x32_bf16 v[110:113], v[160:163], v[176:179], v[110:113]
	v_mfma_f32_16x16x32_bf16 v[102:105], v[146:149], v[186:189], v[102:105]
	v_mfma_f32_16x16x32_bf16 v[94:97], v[160:163], v[186:189], v[94:97]
	v_mfma_f32_16x16x32_bf16 v[86:89], v[146:149], v[194:197], v[86:89]
	v_mfma_f32_16x16x32_bf16 v[78:81], v[160:163], v[194:197], v[78:81]
	v_mfma_f32_16x16x32_bf16 v[126:129], v[156:159], v[172:175], v[126:129]
	v_mfma_f32_16x16x32_bf16 v[122:125], v[164:167], v[172:175], v[122:125]
	v_mfma_f32_16x16x32_bf16 v[118:121], v[156:159], v[180:183], v[118:121]
	v_mfma_f32_16x16x32_bf16 v[110:113], v[164:167], v[180:183], v[110:113]
	v_mfma_f32_16x16x32_bf16 v[102:105], v[156:159], v[190:193], v[102:105]
	v_mfma_f32_16x16x32_bf16 v[94:97], v[164:167], v[190:193], v[94:97]
	v_mfma_f32_16x16x32_bf16 v[86:89], v[156:159], v[198:201], v[86:89]
	v_mfma_f32_16x16x32_bf16 v[78:81], v[164:167], v[198:201], v[78:81]
	v_mfma_f32_16x16x32_bf16 v[114:117], v[202:205], v[168:171], v[114:117]
	v_mfma_f32_16x16x32_bf16 v[106:109], v[210:213], v[168:171], v[106:109]
	v_mfma_f32_16x16x32_bf16 v[98:101], v[202:205], v[176:179], v[98:101]
	v_mfma_f32_16x16x32_bf16 v[90:93], v[210:213], v[176:179], v[90:93]
	v_mfma_f32_16x16x32_bf16 v[82:85], v[202:205], v[186:189], v[82:85]
	v_mfma_f32_16x16x32_bf16 v[74:77], v[210:213], v[186:189], v[74:77]
	v_mfma_f32_16x16x32_bf16 v[70:73], v[202:205], v[194:197], v[70:73]
	v_mfma_f32_16x16x32_bf16 v[66:69], v[210:213], v[194:197], v[66:69]
	v_mfma_f32_16x16x32_bf16 v[114:117], v[206:209], v[172:175], v[114:117]
	v_mfma_f32_16x16x32_bf16 v[106:109], v[214:217], v[172:175], v[106:109]
	v_mfma_f32_16x16x32_bf16 v[98:101], v[206:209], v[180:183], v[98:101]
	v_mfma_f32_16x16x32_bf16 v[90:93], v[214:217], v[180:183], v[90:93]
	v_mfma_f32_16x16x32_bf16 v[82:85], v[206:209], v[190:193], v[82:85]
	v_mfma_f32_16x16x32_bf16 v[74:77], v[214:217], v[190:193], v[74:77]
	v_mfma_f32_16x16x32_bf16 v[70:73], v[206:209], v[198:201], v[70:73]
	v_mfma_f32_16x16x32_bf16 v[66:69], v[214:217], v[198:201], v[66:69]
	s_setprio 0
	s_barrier
	ds_read_b128 v[168:171], v153 offset:16384
	ds_read_b128 v[172:175], v153 offset:17408
	ds_read_b128 v[176:179], v153 offset:18432
	ds_read_b128 v[180:183], v153 offset:19456
	ds_read_b128 v[186:189], v153 offset:20480
	ds_read_b128 v[190:193], v153 offset:21504
	ds_read_b128 v[194:197], v153 offset:22528
	ds_read_b128 v[198:201], v153 offset:23552
	s_add_i32 s68, s45, s29
	v_lshl_add_u64 v[218:219], s[24:25], 0, v[134:135]
	s_mov_b32 m0, s68
	global_load_lds_dwordx4 v[218:219], off
	v_lshl_add_u64 v[220:221], s[24:25], 0, v[130:131]
	s_add_i32 m0, s68, 0x2000
	s_nop 0
	global_load_lds_dwordx4 v[220:221], off
	s_mov_b32 m0, s21
	v_lshl_add_u64 v[222:223], s[26:27], 0, v[136:137]
	global_load_lds_dwordx4 v[222:223], off
	v_lshl_add_u64 v[224:225], s[26:27], 0, v[132:133]
	s_mov_b32 m0, s34
	s_nop 0
	global_load_lds_dwordx4 v[224:225], off
	s_waitcnt vmcnt(6)
	s_waitcnt lgkmcnt(0)
	s_barrier
	s_setprio 1
	v_mfma_f32_16x16x32_bf16 v[62:65], v[146:149], v[168:171], v[62:65]
	v_mfma_f32_16x16x32_bf16 v[58:61], v[160:163], v[168:171], v[58:61]
	v_mfma_f32_16x16x32_bf16 v[54:57], v[146:149], v[176:179], v[54:57]
	v_mfma_f32_16x16x32_bf16 v[46:49], v[160:163], v[176:179], v[46:49]
	v_mfma_f32_16x16x32_bf16 v[38:41], v[146:149], v[186:189], v[38:41]
	v_mfma_f32_16x16x32_bf16 v[30:33], v[160:163], v[186:189], v[30:33]
	v_mfma_f32_16x16x32_bf16 v[22:25], v[146:149], v[194:197], v[22:25]
	v_mfma_f32_16x16x32_bf16 v[14:17], v[160:163], v[194:197], v[14:17]
	v_mfma_f32_16x16x32_bf16 v[62:65], v[156:159], v[172:175], v[62:65]
	v_mfma_f32_16x16x32_bf16 v[58:61], v[164:167], v[172:175], v[58:61]
	v_mfma_f32_16x16x32_bf16 v[54:57], v[156:159], v[180:183], v[54:57]
	v_mfma_f32_16x16x32_bf16 v[46:49], v[164:167], v[180:183], v[46:49]
	v_mfma_f32_16x16x32_bf16 v[38:41], v[156:159], v[190:193], v[38:41]
	v_mfma_f32_16x16x32_bf16 v[30:33], v[164:167], v[190:193], v[30:33]
	v_mfma_f32_16x16x32_bf16 v[22:25], v[156:159], v[198:201], v[22:25]
	v_mfma_f32_16x16x32_bf16 v[14:17], v[164:167], v[198:201], v[14:17]
	v_mfma_f32_16x16x32_bf16 v[50:53], v[202:205], v[168:171], v[50:53]
	v_mfma_f32_16x16x32_bf16 v[42:45], v[210:213], v[168:171], v[42:45]
	v_mfma_f32_16x16x32_bf16 v[34:37], v[202:205], v[176:179], v[34:37]
	v_mfma_f32_16x16x32_bf16 v[26:29], v[210:213], v[176:179], v[26:29]
	v_mfma_f32_16x16x32_bf16 v[18:21], v[202:205], v[186:189], v[18:21]
	v_mfma_f32_16x16x32_bf16 v[10:13], v[210:213], v[186:189], v[10:13]
	v_mfma_f32_16x16x32_bf16 v[6:9], v[202:205], v[194:197], v[6:9]
	v_mfma_f32_16x16x32_bf16 v[2:5], v[210:213], v[194:197], v[2:5]
	v_mfma_f32_16x16x32_bf16 v[50:53], v[206:209], v[172:175], v[50:53]
	v_mfma_f32_16x16x32_bf16 v[42:45], v[214:217], v[172:175], v[42:45]
	v_mfma_f32_16x16x32_bf16 v[34:37], v[206:209], v[180:183], v[34:37]
	v_mfma_f32_16x16x32_bf16 v[26:29], v[214:217], v[180:183], v[26:29]
	v_mfma_f32_16x16x32_bf16 v[18:21], v[206:209], v[190:193], v[18:21]
	v_mfma_f32_16x16x32_bf16 v[10:13], v[214:217], v[190:193], v[10:13]
	v_mfma_f32_16x16x32_bf16 v[6:9], v[206:209], v[198:201], v[6:9]
	v_mfma_f32_16x16x32_bf16 v[2:5], v[214:217], v[198:201], v[2:5]
	s_setprio 0
	s_barrier
	s_add_u32 s68, s24, 0x80000
	s_addc_u32 s69, s25, 0
	s_add_i32 s70, s46, s29
	v_lshl_add_u64 v[146:147], s[68:69], 0, v[134:135]
	s_mov_b32 m0, s70
	s_nop 0
	global_load_lds_dwordx4 v[146:147], off
	v_lshl_add_u64 v[146:147], s[68:69], 0, v[130:131]
	s_add_i32 m0, s70, 0x2000
	s_nop 0
	global_load_lds_dwordx4 v[146:147], off
	s_add_i32 s68, 0, 0x18000
	v_add_u32_e32 v155, s68, v150
	ds_read_b128 v[146:149], v155
	ds_read_b128 v[156:159], v155 offset:1024
	ds_read_b128 v[160:163], v155 offset:2048
	ds_read_b128 v[164:167], v155 offset:3072
	ds_read_b128 v[168:171], v153 offset:32768
	ds_read_b128 v[172:175], v153 offset:33792
	ds_read_b128 v[176:179], v153 offset:34816
	ds_read_b128 v[180:183], v153 offset:35840
	ds_read_b128 v[186:189], v153 offset:36864
	ds_read_b128 v[190:193], v153 offset:37888
	ds_read_b128 v[194:197], v153 offset:38912
	ds_read_b128 v[198:201], v153 offset:39936
	s_add_u32 s26, s26, 0x80000
	s_addc_u32 s27, s27, 0
	s_mov_b32 m0, s35
	v_lshl_add_u64 v[202:203], s[26:27], 0, v[136:137]
	global_load_lds_dwordx4 v[202:203], off
	v_lshl_add_u64 v[202:203], s[26:27], 0, v[132:133]
	s_mov_b32 m0, s36
	s_nop 0
	global_load_lds_dwordx4 v[202:203], off
	v_add_u32_e32 v214, 0x1c000, v150
	ds_read_b128 v[202:205], v214
	ds_read_b128 v[206:209], v214 offset:1024
	ds_read_b128 v[210:213], v214 offset:2048
	ds_read_b128 v[214:217], v214 offset:3072
	s_waitcnt vmcnt(8)
	s_waitcnt lgkmcnt(0)
	s_barrier
	s_setprio 1
	v_mfma_f32_16x16x32_bf16 v[126:129], v[146:149], v[168:171], v[126:129]
	v_mfma_f32_16x16x32_bf16 v[122:125], v[160:163], v[168:171], v[122:125]
	v_mfma_f32_16x16x32_bf16 v[118:121], v[146:149], v[176:179], v[118:121]
	v_mfma_f32_16x16x32_bf16 v[110:113], v[160:163], v[176:179], v[110:113]
	v_mfma_f32_16x16x32_bf16 v[102:105], v[146:149], v[186:189], v[102:105]
	v_mfma_f32_16x16x32_bf16 v[94:97], v[160:163], v[186:189], v[94:97]
	v_mfma_f32_16x16x32_bf16 v[86:89], v[146:149], v[194:197], v[86:89]
	v_mfma_f32_16x16x32_bf16 v[78:81], v[160:163], v[194:197], v[78:81]
	v_mfma_f32_16x16x32_bf16 v[126:129], v[156:159], v[172:175], v[126:129]
	v_mfma_f32_16x16x32_bf16 v[122:125], v[164:167], v[172:175], v[122:125]
	v_mfma_f32_16x16x32_bf16 v[118:121], v[156:159], v[180:183], v[118:121]
	v_mfma_f32_16x16x32_bf16 v[110:113], v[164:167], v[180:183], v[110:113]
	v_mfma_f32_16x16x32_bf16 v[102:105], v[156:159], v[190:193], v[102:105]
	v_mfma_f32_16x16x32_bf16 v[94:97], v[164:167], v[190:193], v[94:97]
	v_mfma_f32_16x16x32_bf16 v[86:89], v[156:159], v[198:201], v[86:89]
	v_mfma_f32_16x16x32_bf16 v[78:81], v[164:167], v[198:201], v[78:81]
	v_mfma_f32_16x16x32_bf16 v[114:117], v[202:205], v[168:171], v[114:117]
	v_mfma_f32_16x16x32_bf16 v[106:109], v[210:213], v[168:171], v[106:109]
	v_mfma_f32_16x16x32_bf16 v[98:101], v[202:205], v[176:179], v[98:101]
	v_mfma_f32_16x16x32_bf16 v[90:93], v[210:213], v[176:179], v[90:93]
	v_mfma_f32_16x16x32_bf16 v[82:85], v[202:205], v[186:189], v[82:85]
	v_mfma_f32_16x16x32_bf16 v[74:77], v[210:213], v[186:189], v[74:77]
	v_mfma_f32_16x16x32_bf16 v[70:73], v[202:205], v[194:197], v[70:73]
	v_mfma_f32_16x16x32_bf16 v[66:69], v[210:213], v[194:197], v[66:69]
	v_mfma_f32_16x16x32_bf16 v[114:117], v[206:209], v[172:175], v[114:117]
	v_mfma_f32_16x16x32_bf16 v[106:109], v[214:217], v[172:175], v[106:109]
	v_mfma_f32_16x16x32_bf16 v[98:101], v[206:209], v[180:183], v[98:101]
	v_mfma_f32_16x16x32_bf16 v[90:93], v[214:217], v[180:183], v[90:93]
	v_mfma_f32_16x16x32_bf16 v[82:85], v[206:209], v[190:193], v[82:85]
	v_mfma_f32_16x16x32_bf16 v[74:77], v[214:217], v[190:193], v[74:77]
	v_mfma_f32_16x16x32_bf16 v[70:73], v[206:209], v[198:201], v[70:73]
	v_mfma_f32_16x16x32_bf16 v[66:69], v[214:217], v[198:201], v[66:69]
	s_setprio 0
	s_barrier
	ds_read_b128 v[168:171], v153 offset:49152
	ds_read_b128 v[172:175], v153 offset:50176
	ds_read_b128 v[176:179], v153 offset:51200
	ds_read_b128 v[180:183], v153 offset:52224
	ds_read_b128 v[186:189], v153 offset:53248
	ds_read_b128 v[190:193], v153 offset:54272
	ds_read_b128 v[194:197], v153 offset:55296
	ds_read_b128 v[198:201], v153 offset:56320
	s_add_i32 s26, 0, 0x1c000
	s_add_i32 s27, s68, s29
	v_lshl_add_u64 v[218:219], v[218:219], 0, s[4:5]
	s_mov_b32 m0, s27
	global_load_lds_dwordx4 v[218:219], off
	v_lshl_add_u64 v[218:219], v[220:221], 0, s[4:5]
	s_add_i32 m0, s27, 0x2000
	s_nop 0
	global_load_lds_dwordx4 v[218:219], off
	s_mov_b32 m0, s41
	v_lshl_add_u64 v[218:219], v[222:223], 0, s[4:5]
	global_load_lds_dwordx4 v[218:219], off
	v_lshl_add_u64 v[218:219], v[224:225], 0, s[4:5]
	s_mov_b32 m0, s42
	s_nop 0
	global_load_lds_dwordx4 v[218:219], off
	s_add_u32 s24, s24, 0x80080
	s_addc_u32 s25, s25, 0
	s_add_i32 s26, s26, s29
	v_lshl_add_u64 v[218:219], s[24:25], 0, v[134:135]
	s_mov_b32 m0, s26
	s_nop 0
	global_load_lds_dwordx4 v[218:219], off
	v_lshl_add_u64 v[218:219], s[24:25], 0, v[130:131]
	s_add_i32 m0, s26, 0x2000
	s_nop 0
	global_load_lds_dwordx4 v[218:219], off
	s_waitcnt vmcnt(8)
	s_waitcnt lgkmcnt(0)
	s_barrier
	s_setprio 1
	v_mfma_f32_16x16x32_bf16 v[62:65], v[146:149], v[168:171], v[62:65]
	v_mfma_f32_16x16x32_bf16 v[58:61], v[160:163], v[168:171], v[58:61]
	v_mfma_f32_16x16x32_bf16 v[54:57], v[146:149], v[176:179], v[54:57]
	v_mfma_f32_16x16x32_bf16 v[46:49], v[160:163], v[176:179], v[46:49]
	v_mfma_f32_16x16x32_bf16 v[38:41], v[146:149], v[186:189], v[38:41]
	v_mfma_f32_16x16x32_bf16 v[30:33], v[160:163], v[186:189], v[30:33]
	v_mfma_f32_16x16x32_bf16 v[22:25], v[146:149], v[194:197], v[22:25]
	v_mfma_f32_16x16x32_bf16 v[14:17], v[160:163], v[194:197], v[14:17]
	v_mfma_f32_16x16x32_bf16 v[62:65], v[156:159], v[172:175], v[62:65]
	v_mfma_f32_16x16x32_bf16 v[58:61], v[164:167], v[172:175], v[58:61]
	v_mfma_f32_16x16x32_bf16 v[54:57], v[156:159], v[180:183], v[54:57]
	v_mfma_f32_16x16x32_bf16 v[46:49], v[164:167], v[180:183], v[46:49]
	v_mfma_f32_16x16x32_bf16 v[38:41], v[156:159], v[190:193], v[38:41]
	v_mfma_f32_16x16x32_bf16 v[30:33], v[164:167], v[190:193], v[30:33]
	v_mfma_f32_16x16x32_bf16 v[22:25], v[156:159], v[198:201], v[22:25]
	v_mfma_f32_16x16x32_bf16 v[14:17], v[164:167], v[198:201], v[14:17]
	v_mfma_f32_16x16x32_bf16 v[50:53], v[202:205], v[168:171], v[50:53]
	v_mfma_f32_16x16x32_bf16 v[42:45], v[210:213], v[168:171], v[42:45]
	v_mfma_f32_16x16x32_bf16 v[34:37], v[202:205], v[176:179], v[34:37]
	v_mfma_f32_16x16x32_bf16 v[26:29], v[210:213], v[176:179], v[26:29]
	v_mfma_f32_16x16x32_bf16 v[18:21], v[202:205], v[186:189], v[18:21]
	v_mfma_f32_16x16x32_bf16 v[10:13], v[210:213], v[186:189], v[10:13]
	v_mfma_f32_16x16x32_bf16 v[6:9], v[202:205], v[194:197], v[6:9]
	v_mfma_f32_16x16x32_bf16 v[2:5], v[210:213], v[194:197], v[2:5]
	v_mfma_f32_16x16x32_bf16 v[50:53], v[206:209], v[172:175], v[50:53]
	v_mfma_f32_16x16x32_bf16 v[42:45], v[214:217], v[172:175], v[42:45]
	v_mfma_f32_16x16x32_bf16 v[34:37], v[206:209], v[180:183], v[34:37]
	v_mfma_f32_16x16x32_bf16 v[26:29], v[214:217], v[180:183], v[26:29]
	v_mfma_f32_16x16x32_bf16 v[18:21], v[206:209], v[190:193], v[18:21]
	v_mfma_f32_16x16x32_bf16 v[10:13], v[214:217], v[190:193], v[10:13]
	v_mfma_f32_16x16x32_bf16 v[6:9], v[206:209], v[198:201], v[6:9]
	v_mfma_f32_16x16x32_bf16 v[2:5], v[214:217], v[198:201], v[2:5]
	s_setprio 0
	s_add_i32 s61, s61, 2
	s_add_u32 s22, s22, 0x100
	s_addc_u32 s23, s23, 0
	s_add_u32 s59, s59, 0x100
	s_addc_u32 s60, s60, 0
	s_cmp_gt_u32 s61, 29
	s_barrier
	s_cbranch_scc0 .LBB0_269
	v_lshl_or_b32 v148, s52, 8, v151
	v_lshl_add_u32 v155, s20, 8, v1
	v_ashrrev_i32_e32 v149, 31, v148
	v_mov_b64_e32 v[146:147], s[54:55]
	v_mad_i64_i32 v[156:157], s[22:23], v155, s47, v[146:147]
	v_lshlrev_b64 v[148:149], 1, v[148:149]
	v_lshl_add_u64 v[156:157], v[156:157], 0, v[148:149]
	v_cvt_pk_bf16_f32 v126, v126, v127
	v_cvt_pk_bf16_f32 v127, v128, v129
	v_cvt_pk_bf16_f32 v128, v122, v123
	v_cvt_pk_bf16_f32 v129, v124, v125
	global_store_dwordx4 v[156:157], v[126:129], off
	v_cvt_pk_bf16_f32 v114, v114, v115
	v_cvt_pk_bf16_f32 v115, v116, v117
	v_cvt_pk_bf16_f32 v116, v106, v107
	v_or_b32_e32 v106, 16, v155
	v_mad_i64_i32 v[106:107], s[22:23], v106, s47, v[146:147]
	v_cvt_pk_bf16_f32 v117, v108, v109
	global_store_dwordx4 v[156:157], v[114:117], off offset:256
	s_and_b64 vcc, exec, s[2:3]
	s_mov_b32 s52, s6
	v_lshl_add_u64 v[114:115], v[106:107], 0, v[148:149]
	v_cvt_pk_bf16_f32 v106, v118, v119
	v_cvt_pk_bf16_f32 v107, v120, v121
	v_cvt_pk_bf16_f32 v108, v110, v111
	v_cvt_pk_bf16_f32 v109, v112, v113
	global_store_dwordx4 v[114:115], v[106:109], off
	v_cvt_pk_bf16_f32 v98, v98, v99
	v_cvt_pk_bf16_f32 v99, v100, v101
	v_cvt_pk_bf16_f32 v100, v90, v91
	v_or_b32_e32 v90, 32, v155
	v_mad_i64_i32 v[90:91], s[22:23], v90, s47, v[146:147]
	v_cvt_pk_bf16_f32 v101, v92, v93
	global_store_dwordx4 v[114:115], v[98:101], off offset:256
	s_mov_b32 s20, s8
	s_mov_b64 s[24:25], s[18:19]
	v_lshl_add_u64 v[98:99], v[90:91], 0, v[148:149]
	v_cvt_pk_bf16_f32 v90, v102, v103
	v_cvt_pk_bf16_f32 v91, v104, v105
	v_cvt_pk_bf16_f32 v92, v94, v95
	v_cvt_pk_bf16_f32 v93, v96, v97
	global_store_dwordx4 v[98:99], v[90:93], off
	v_cvt_pk_bf16_f32 v82, v82, v83
	v_cvt_pk_bf16_f32 v83, v84, v85
	v_cvt_pk_bf16_f32 v84, v74, v75
	v_or_b32_e32 v74, 48, v155
	v_mad_i64_i32 v[74:75], s[22:23], v74, s47, v[146:147]
	v_cvt_pk_bf16_f32 v85, v76, v77
	global_store_dwordx4 v[98:99], v[82:85], off offset:256
	s_nop 1
	v_lshl_add_u64 v[82:83], v[74:75], 0, v[148:149]
	v_cvt_pk_bf16_f32 v74, v86, v87
	v_cvt_pk_bf16_f32 v75, v88, v89
	v_cvt_pk_bf16_f32 v76, v78, v79
	v_cvt_pk_bf16_f32 v77, v80, v81
	global_store_dwordx4 v[82:83], v[74:77], off
	v_cvt_pk_bf16_f32 v70, v70, v71
	v_cvt_pk_bf16_f32 v71, v72, v73
	v_cvt_pk_bf16_f32 v72, v66, v67
	v_add_u32_e32 v66, 0x80, v155
	v_mad_i64_i32 v[66:67], s[22:23], v66, s47, v[146:147]
	v_lshl_add_u64 v[66:67], v[66:67], 0, v[148:149]
	v_cvt_pk_bf16_f32 v73, v68, v69
	global_store_dwordx4 v[82:83], v[70:73], off offset:256
	v_cvt_pk_bf16_f32 v62, v62, v63
	v_cvt_pk_bf16_f32 v63, v64, v65
	v_cvt_pk_bf16_f32 v64, v58, v59
	v_cvt_pk_bf16_f32 v65, v60, v61
	global_store_dwordx4 v[66:67], v[62:65], off
	v_cvt_pk_bf16_f32 v50, v50, v51
	v_cvt_pk_bf16_f32 v51, v52, v53
	v_cvt_pk_bf16_f32 v52, v42, v43
	v_add_u32_e32 v42, 0x90, v155
	v_mad_i64_i32 v[42:43], s[22:23], v42, s47, v[146:147]
	v_cvt_pk_bf16_f32 v53, v44, v45
	global_store_dwordx4 v[66:67], v[50:53], off offset:256
	s_nop 1
	v_lshl_add_u64 v[50:51], v[42:43], 0, v[148:149]
	v_cvt_pk_bf16_f32 v42, v54, v55
	v_cvt_pk_bf16_f32 v43, v56, v57
	v_cvt_pk_bf16_f32 v44, v46, v47
	v_cvt_pk_bf16_f32 v45, v48, v49
	global_store_dwordx4 v[50:51], v[42:45], off
	v_cvt_pk_bf16_f32 v34, v34, v35
	v_cvt_pk_bf16_f32 v35, v36, v37
	v_cvt_pk_bf16_f32 v36, v26, v27
	v_add_u32_e32 v26, 0xa0, v155
	v_mad_i64_i32 v[26:27], s[22:23], v26, s47, v[146:147]
	v_cvt_pk_bf16_f32 v37, v28, v29
	global_store_dwordx4 v[50:51], v[34:37], off offset:256
	s_nop 1
	v_lshl_add_u64 v[34:35], v[26:27], 0, v[148:149]
	v_cvt_pk_bf16_f32 v26, v38, v39
	v_cvt_pk_bf16_f32 v27, v40, v41
	v_cvt_pk_bf16_f32 v28, v30, v31
	v_cvt_pk_bf16_f32 v29, v32, v33
	global_store_dwordx4 v[34:35], v[26:29], off
	v_cvt_pk_bf16_f32 v18, v18, v19
	v_cvt_pk_bf16_f32 v19, v20, v21
	v_cvt_pk_bf16_f32 v20, v10, v11
	v_add_u32_e32 v10, 0xb0, v155
	v_mad_i64_i32 v[10:11], s[22:23], v10, s47, v[146:147]
	v_cvt_pk_bf16_f32 v21, v12, v13
	global_store_dwordx4 v[34:35], v[18:21], off offset:256
	s_mov_b64 s[22:23], s[16:17]
	s_nop 0
	v_lshl_add_u64 v[18:19], v[10:11], 0, v[148:149]
	v_cvt_pk_bf16_f32 v10, v22, v23
	v_cvt_pk_bf16_f32 v11, v24, v25
	v_cvt_pk_bf16_f32 v12, v14, v15
	v_cvt_pk_bf16_f32 v13, v16, v17
	global_store_dwordx4 v[18:19], v[10:13], off
	v_cvt_pk_bf16_f32 v6, v6, v7
	v_cvt_pk_bf16_f32 v7, v8, v9
	v_cvt_pk_bf16_f32 v8, v2, v3
	v_cvt_pk_bf16_f32 v9, v4, v5
	global_store_dwordx4 v[18:19], v[6:9], off offset:256
	s_cbranch_vccz .LBB0_266
	s_waitcnt vmcnt(0)
	s_cmpk_gt_u32 s28, 0xff
	s_cbranch_scc1 .LBB0_273
	s_barrier

.LBB0_457:
	ds_read_b128 v[154:157], v150
	ds_read_b128 v[158:161], v150 offset:1024
	ds_read_b128 v[162:165], v150 offset:2048
	ds_read_b128 v[166:169], v150 offset:3072
	ds_read_b128 v[170:173], v151
	ds_read_b128 v[174:177], v151 offset:1024
	ds_read_b128 v[178:181], v151 offset:2048
	ds_read_b128 v[186:189], v151 offset:3072
	ds_read_b128 v[190:193], v151 offset:4096
	ds_read_b128 v[194:197], v151 offset:5120
	ds_read_b128 v[198:201], v151 offset:6144
	ds_read_b128 v[202:205], v151 offset:7168
	s_add_u32 s4, s28, 0x100
	s_addc_u32 s5, s29, 0
	s_cmp_eq_u32 s81, 4
	s_cselect_b32 s35, s25, s5
	s_cselect_b32 s34, s24, s4
	s_cselect_b32 s31, s23, s80
	s_cselect_b32 s30, s78, s79
	v_lshl_add_u64 v[146:147], s[28:29], 0, v[138:139]
	s_add_i32 m0, s46, 0xc000
	global_load_lds_dwordx4 v[146:147], off
	v_lshl_add_u64 v[146:147], s[28:29], 0, v[140:141]
	s_add_i32 m0, s46, 0xe000
	s_nop 0
	global_load_lds_dwordx4 v[146:147], off
	ds_read_b128 v[206:209], v152
	ds_read_b128 v[210:213], v152 offset:1024
	ds_read_b128 v[214:217], v152 offset:2048
	ds_read_b128 v[218:221], v152 offset:3072
	s_waitcnt vmcnt(8)
	s_waitcnt lgkmcnt(0)
	s_barrier
	s_setprio 1
	v_mfma_f32_16x16x32_bf16 v[126:129], v[154:157], v[170:173], v[126:129]
	v_mfma_f32_16x16x32_bf16 v[122:125], v[162:165], v[170:173], v[122:125]
	v_mfma_f32_16x16x32_bf16 v[114:117], v[154:157], v[178:181], v[114:117]
	v_mfma_f32_16x16x32_bf16 v[106:109], v[162:165], v[178:181], v[106:109]
	v_mfma_f32_16x16x32_bf16 v[98:101], v[154:157], v[190:193], v[98:101]
	v_mfma_f32_16x16x32_bf16 v[90:93], v[162:165], v[190:193], v[90:93]
	v_mfma_f32_16x16x32_bf16 v[82:85], v[154:157], v[198:201], v[82:85]
	v_mfma_f32_16x16x32_bf16 v[74:77], v[162:165], v[198:201], v[74:77]
	v_mfma_f32_16x16x32_bf16 v[126:129], v[158:161], v[174:177], v[126:129]
	v_mfma_f32_16x16x32_bf16 v[122:125], v[166:169], v[174:177], v[122:125]
	v_mfma_f32_16x16x32_bf16 v[114:117], v[158:161], v[186:189], v[114:117]
	v_mfma_f32_16x16x32_bf16 v[106:109], v[166:169], v[186:189], v[106:109]
	v_mfma_f32_16x16x32_bf16 v[98:101], v[158:161], v[194:197], v[98:101]
	v_mfma_f32_16x16x32_bf16 v[90:93], v[166:169], v[194:197], v[90:93]
	v_mfma_f32_16x16x32_bf16 v[82:85], v[158:161], v[202:205], v[82:85]
	v_mfma_f32_16x16x32_bf16 v[74:77], v[166:169], v[202:205], v[74:77]
	v_mfma_f32_16x16x32_bf16 v[118:121], v[206:209], v[170:173], v[118:121]
	v_mfma_f32_16x16x32_bf16 v[110:113], v[214:217], v[170:173], v[110:113]
	v_mfma_f32_16x16x32_bf16 v[102:105], v[206:209], v[178:181], v[102:105]
	v_mfma_f32_16x16x32_bf16 v[94:97], v[214:217], v[178:181], v[94:97]
	v_mfma_f32_16x16x32_bf16 v[86:89], v[206:209], v[190:193], v[86:89]
	v_mfma_f32_16x16x32_bf16 v[78:81], v[214:217], v[190:193], v[78:81]
	v_mfma_f32_16x16x32_bf16 v[70:73], v[206:209], v[198:201], v[70:73]
	v_mfma_f32_16x16x32_bf16 v[66:69], v[214:217], v[198:201], v[66:69]
	v_mfma_f32_16x16x32_bf16 v[118:121], v[210:213], v[174:177], v[118:121]
	v_mfma_f32_16x16x32_bf16 v[110:113], v[218:221], v[174:177], v[110:113]
	v_mfma_f32_16x16x32_bf16 v[102:105], v[210:213], v[186:189], v[102:105]
	v_mfma_f32_16x16x32_bf16 v[94:97], v[218:221], v[186:189], v[94:97]
	v_mfma_f32_16x16x32_bf16 v[86:89], v[210:213], v[194:197], v[86:89]
	v_mfma_f32_16x16x32_bf16 v[78:81], v[218:221], v[194:197], v[78:81]
	v_mfma_f32_16x16x32_bf16 v[70:73], v[210:213], v[202:205], v[70:73]
	v_mfma_f32_16x16x32_bf16 v[66:69], v[218:221], v[202:205], v[66:69]
	s_setprio 0
	s_barrier
	ds_read_b128 v[170:173], v151 offset:16384
	ds_read_b128 v[174:177], v151 offset:17408
	ds_read_b128 v[178:181], v151 offset:18432
	ds_read_b128 v[186:189], v151 offset:19456
	ds_read_b128 v[190:193], v151 offset:20480
	ds_read_b128 v[194:197], v151 offset:21504
	ds_read_b128 v[198:201], v151 offset:22528
	ds_read_b128 v[202:205], v151 offset:23552
	s_add_i32 s28, s61, s45
	v_lshl_add_u64 v[146:147], s[30:31], 0, v[132:133]
	s_mov_b32 m0, s28
	global_load_lds_dwordx4 v[146:147], off
	v_lshl_add_u64 v[182:183], s[30:31], 0, v[136:137]
	s_add_i32 m0, s28, 0x2000
	s_nop 0
	global_load_lds_dwordx4 v[182:183], off
	s_mov_b32 m0, s46
	v_lshl_add_u64 v[222:223], s[34:35], 0, v[130:131]
	global_load_lds_dwordx4 v[222:223], off
	v_lshl_add_u64 v[224:225], s[34:35], 0, v[134:135]
	s_mov_b32 m0, s47
	s_nop 0
	global_load_lds_dwordx4 v[224:225], off
	s_waitcnt vmcnt(6)
	s_waitcnt lgkmcnt(0)
	s_barrier
	s_setprio 1
	v_mfma_f32_16x16x32_bf16 v[62:65], v[154:157], v[170:173], v[62:65]
	v_mfma_f32_16x16x32_bf16 v[58:61], v[162:165], v[170:173], v[58:61]
	v_mfma_f32_16x16x32_bf16 v[54:57], v[154:157], v[178:181], v[54:57]
	v_mfma_f32_16x16x32_bf16 v[46:49], v[162:165], v[178:181], v[46:49]
	v_mfma_f32_16x16x32_bf16 v[38:41], v[154:157], v[190:193], v[38:41]
	v_mfma_f32_16x16x32_bf16 v[30:33], v[162:165], v[190:193], v[30:33]
	v_mfma_f32_16x16x32_bf16 v[22:25], v[154:157], v[198:201], v[22:25]
	v_mfma_f32_16x16x32_bf16 v[14:17], v[162:165], v[198:201], v[14:17]
	v_mfma_f32_16x16x32_bf16 v[62:65], v[158:161], v[174:177], v[62:65]
	v_mfma_f32_16x16x32_bf16 v[58:61], v[166:169], v[174:177], v[58:61]
	v_mfma_f32_16x16x32_bf16 v[54:57], v[158:161], v[186:189], v[54:57]
	v_mfma_f32_16x16x32_bf16 v[46:49], v[166:169], v[186:189], v[46:49]
	v_mfma_f32_16x16x32_bf16 v[38:41], v[158:161], v[194:197], v[38:41]
	v_mfma_f32_16x16x32_bf16 v[30:33], v[166:169], v[194:197], v[30:33]
	v_mfma_f32_16x16x32_bf16 v[22:25], v[158:161], v[202:205], v[22:25]
	v_mfma_f32_16x16x32_bf16 v[14:17], v[166:169], v[202:205], v[14:17]
	v_mfma_f32_16x16x32_bf16 v[50:53], v[206:209], v[170:173], v[50:53]
	v_mfma_f32_16x16x32_bf16 v[42:45], v[214:217], v[170:173], v[42:45]
	v_mfma_f32_16x16x32_bf16 v[34:37], v[206:209], v[178:181], v[34:37]
	v_mfma_f32_16x16x32_bf16 v[26:29], v[214:217], v[178:181], v[26:29]
	v_mfma_f32_16x16x32_bf16 v[18:21], v[206:209], v[190:193], v[18:21]
	v_mfma_f32_16x16x32_bf16 v[10:13], v[214:217], v[190:193], v[10:13]
	v_mfma_f32_16x16x32_bf16 v[6:9], v[206:209], v[198:201], v[6:9]
	v_mfma_f32_16x16x32_bf16 v[2:5], v[214:217], v[198:201], v[2:5]
	v_mfma_f32_16x16x32_bf16 v[50:53], v[210:213], v[174:177], v[50:53]
	v_mfma_f32_16x16x32_bf16 v[42:45], v[218:221], v[174:177], v[42:45]
	v_mfma_f32_16x16x32_bf16 v[34:37], v[210:213], v[186:189], v[34:37]
	v_mfma_f32_16x16x32_bf16 v[26:29], v[218:221], v[186:189], v[26:29]
	v_mfma_f32_16x16x32_bf16 v[18:21], v[210:213], v[194:197], v[18:21]
	v_mfma_f32_16x16x32_bf16 v[10:13], v[218:221], v[194:197], v[10:13]
	v_mfma_f32_16x16x32_bf16 v[6:9], v[210:213], v[202:205], v[6:9]
	v_mfma_f32_16x16x32_bf16 v[2:5], v[218:221], v[202:205], v[2:5]
	s_setprio 0
	s_barrier
	s_add_u32 s28, s30, 0x20000
	s_addc_u32 s29, s31, 0
	s_add_i32 s82, s71, s45
	v_lshl_add_u64 v[154:155], s[28:29], 0, v[132:133]
	s_mov_b32 m0, s82
	s_nop 0
	global_load_lds_dwordx4 v[154:155], off
	v_lshl_add_u64 v[154:155], s[28:29], 0, v[136:137]
	s_add_i32 m0, s82, 0x2000
	s_nop 0
	global_load_lds_dwordx4 v[154:155], off
	s_add_i32 s82, 0, 0x18000
	v_add_u32_e32 v153, s82, v148
	ds_read_b128 v[154:157], v153
	ds_read_b128 v[158:161], v153 offset:1024
	ds_read_b128 v[162:165], v153 offset:2048
	ds_read_b128 v[166:169], v153 offset:3072
	ds_read_b128 v[170:173], v151 offset:32768
	ds_read_b128 v[174:177], v151 offset:33792
	ds_read_b128 v[178:181], v151 offset:34816
	ds_read_b128 v[186:189], v151 offset:35840
	ds_read_b128 v[190:193], v151 offset:36864
	ds_read_b128 v[194:197], v151 offset:37888
	ds_read_b128 v[198:201], v151 offset:38912
	ds_read_b128 v[202:205], v151 offset:39936
	s_add_u32 s28, s34, 0xf0000
	s_addc_u32 s29, s35, 0
	s_mov_b32 m0, s50
	v_lshl_add_u64 v[206:207], s[28:29], 0, v[130:131]
	global_load_lds_dwordx4 v[206:207], off
	v_lshl_add_u64 v[206:207], s[28:29], 0, v[134:135]
	s_mov_b32 m0, s51
	s_nop 0
	global_load_lds_dwordx4 v[206:207], off
	v_add_u32_e32 v218, 0x1c000, v148
	ds_read_b128 v[206:209], v218
	ds_read_b128 v[210:213], v218 offset:1024
	ds_read_b128 v[214:217], v218 offset:2048
	ds_read_b128 v[218:221], v218 offset:3072
	s_waitcnt vmcnt(8)
	s_waitcnt lgkmcnt(0)
	s_barrier
	s_setprio 1
	v_mfma_f32_16x16x32_bf16 v[126:129], v[154:157], v[170:173], v[126:129]
	v_mfma_f32_16x16x32_bf16 v[122:125], v[162:165], v[170:173], v[122:125]
	v_mfma_f32_16x16x32_bf16 v[114:117], v[154:157], v[178:181], v[114:117]
	v_mfma_f32_16x16x32_bf16 v[106:109], v[162:165], v[178:181], v[106:109]
	v_mfma_f32_16x16x32_bf16 v[98:101], v[154:157], v[190:193], v[98:101]
	v_mfma_f32_16x16x32_bf16 v[90:93], v[162:165], v[190:193], v[90:93]
	v_mfma_f32_16x16x32_bf16 v[82:85], v[154:157], v[198:201], v[82:85]
	v_mfma_f32_16x16x32_bf16 v[74:77], v[162:165], v[198:201], v[74:77]
	v_mfma_f32_16x16x32_bf16 v[126:129], v[158:161], v[174:177], v[126:129]
	v_mfma_f32_16x16x32_bf16 v[122:125], v[166:169], v[174:177], v[122:125]
	v_mfma_f32_16x16x32_bf16 v[114:117], v[158:161], v[186:189], v[114:117]
	v_mfma_f32_16x16x32_bf16 v[106:109], v[166:169], v[186:189], v[106:109]
	v_mfma_f32_16x16x32_bf16 v[98:101], v[158:161], v[194:197], v[98:101]
	v_mfma_f32_16x16x32_bf16 v[90:93], v[166:169], v[194:197], v[90:93]
	v_mfma_f32_16x16x32_bf16 v[82:85], v[158:161], v[202:205], v[82:85]
	v_mfma_f32_16x16x32_bf16 v[74:77], v[166:169], v[202:205], v[74:77]
	v_mfma_f32_16x16x32_bf16 v[118:121], v[206:209], v[170:173], v[118:121]
	v_mfma_f32_16x16x32_bf16 v[110:113], v[214:217], v[170:173], v[110:113]
	v_mfma_f32_16x16x32_bf16 v[102:105], v[206:209], v[178:181], v[102:105]
	v_mfma_f32_16x16x32_bf16 v[94:97], v[214:217], v[178:181], v[94:97]
	v_mfma_f32_16x16x32_bf16 v[86:89], v[206:209], v[190:193], v[86:89]
	v_mfma_f32_16x16x32_bf16 v[78:81], v[214:217], v[190:193], v[78:81]
	v_mfma_f32_16x16x32_bf16 v[70:73], v[206:209], v[198:201], v[70:73]
	v_mfma_f32_16x16x32_bf16 v[66:69], v[214:217], v[198:201], v[66:69]
	v_mfma_f32_16x16x32_bf16 v[118:121], v[210:213], v[174:177], v[118:121]
	v_mfma_f32_16x16x32_bf16 v[110:113], v[218:221], v[174:177], v[110:113]
	v_mfma_f32_16x16x32_bf16 v[102:105], v[210:213], v[186:189], v[102:105]
	v_mfma_f32_16x16x32_bf16 v[94:97], v[218:221], v[186:189], v[94:97]
	v_mfma_f32_16x16x32_bf16 v[86:89], v[210:213], v[194:197], v[86:89]
	v_mfma_f32_16x16x32_bf16 v[78:81], v[218:221], v[194:197], v[78:81]
	v_mfma_f32_16x16x32_bf16 v[70:73], v[210:213], v[202:205], v[70:73]
	v_mfma_f32_16x16x32_bf16 v[66:69], v[218:221], v[202:205], v[66:69]
	s_setprio 0
	s_barrier
	ds_read_b128 v[170:173], v151 offset:49152
	ds_read_b128 v[174:177], v151 offset:50176
	ds_read_b128 v[178:181], v151 offset:51200
	ds_read_b128 v[186:189], v151 offset:52224
	ds_read_b128 v[190:193], v151 offset:53248
	ds_read_b128 v[194:197], v151 offset:54272
	ds_read_b128 v[198:201], v151 offset:55296
	ds_read_b128 v[202:205], v151 offset:56320
	s_add_i32 s34, 0, 0x1c000
	s_add_i32 s28, s82, s45
	v_lshl_add_u64 v[146:147], v[146:147], 0, s[6:7]
	s_mov_b32 m0, s28
	global_load_lds_dwordx4 v[146:147], off
	v_lshl_add_u64 v[146:147], v[182:183], 0, s[6:7]
	s_add_i32 m0, s28, 0x2000
	s_nop 0
	global_load_lds_dwordx4 v[146:147], off
	s_mov_b32 m0, s53
	v_lshl_add_u64 v[146:147], v[222:223], 0, s[6:7]
	global_load_lds_dwordx4 v[146:147], off
	v_lshl_add_u64 v[146:147], v[224:225], 0, s[6:7]
	s_mov_b32 m0, s58
	s_nop 0
	global_load_lds_dwordx4 v[146:147], off
	s_add_u32 s28, s30, 0x20080
	s_addc_u32 s29, s31, 0
	s_add_i32 s30, s34, s45
	v_lshl_add_u64 v[146:147], s[28:29], 0, v[132:133]
	s_mov_b32 m0, s30
	s_nop 0
	global_load_lds_dwordx4 v[146:147], off
	v_lshl_add_u64 v[146:147], s[28:29], 0, v[136:137]
	s_add_i32 m0, s30, 0x2000
	s_nop 0
	global_load_lds_dwordx4 v[146:147], off
	s_waitcnt vmcnt(8)
	s_waitcnt lgkmcnt(0)
	s_barrier
	s_setprio 1
	v_mfma_f32_16x16x32_bf16 v[62:65], v[154:157], v[170:173], v[62:65]
	v_mfma_f32_16x16x32_bf16 v[58:61], v[162:165], v[170:173], v[58:61]
	v_mfma_f32_16x16x32_bf16 v[54:57], v[154:157], v[178:181], v[54:57]
	v_mfma_f32_16x16x32_bf16 v[46:49], v[162:165], v[178:181], v[46:49]
	v_mfma_f32_16x16x32_bf16 v[38:41], v[154:157], v[190:193], v[38:41]
	v_mfma_f32_16x16x32_bf16 v[30:33], v[162:165], v[190:193], v[30:33]
	v_mfma_f32_16x16x32_bf16 v[22:25], v[154:157], v[198:201], v[22:25]
	v_mfma_f32_16x16x32_bf16 v[14:17], v[162:165], v[198:201], v[14:17]
	v_mfma_f32_16x16x32_bf16 v[62:65], v[158:161], v[174:177], v[62:65]
	v_mfma_f32_16x16x32_bf16 v[58:61], v[166:169], v[174:177], v[58:61]
	v_mfma_f32_16x16x32_bf16 v[54:57], v[158:161], v[186:189], v[54:57]
	v_mfma_f32_16x16x32_bf16 v[46:49], v[166:169], v[186:189], v[46:49]
	v_mfma_f32_16x16x32_bf16 v[38:41], v[158:161], v[194:197], v[38:41]
	v_mfma_f32_16x16x32_bf16 v[30:33], v[166:169], v[194:197], v[30:33]
	v_mfma_f32_16x16x32_bf16 v[22:25], v[158:161], v[202:205], v[22:25]
	v_mfma_f32_16x16x32_bf16 v[14:17], v[166:169], v[202:205], v[14:17]
	v_mfma_f32_16x16x32_bf16 v[50:53], v[206:209], v[170:173], v[50:53]
	v_mfma_f32_16x16x32_bf16 v[42:45], v[214:217], v[170:173], v[42:45]
	v_mfma_f32_16x16x32_bf16 v[34:37], v[206:209], v[178:181], v[34:37]
	v_mfma_f32_16x16x32_bf16 v[26:29], v[214:217], v[178:181], v[26:29]
	v_mfma_f32_16x16x32_bf16 v[18:21], v[206:209], v[190:193], v[18:21]
	v_mfma_f32_16x16x32_bf16 v[10:13], v[214:217], v[190:193], v[10:13]
	v_mfma_f32_16x16x32_bf16 v[6:9], v[206:209], v[198:201], v[6:9]
	v_mfma_f32_16x16x32_bf16 v[2:5], v[214:217], v[198:201], v[2:5]
	v_mfma_f32_16x16x32_bf16 v[50:53], v[210:213], v[174:177], v[50:53]
	v_mfma_f32_16x16x32_bf16 v[42:45], v[218:221], v[174:177], v[42:45]
	v_mfma_f32_16x16x32_bf16 v[34:37], v[210:213], v[186:189], v[34:37]
	v_mfma_f32_16x16x32_bf16 v[26:29], v[218:221], v[186:189], v[26:29]
	v_mfma_f32_16x16x32_bf16 v[18:21], v[210:213], v[194:197], v[18:21]
	v_mfma_f32_16x16x32_bf16 v[10:13], v[218:221], v[194:197], v[10:13]
	v_mfma_f32_16x16x32_bf16 v[6:9], v[210:213], v[202:205], v[6:9]
	v_mfma_f32_16x16x32_bf16 v[2:5], v[218:221], v[202:205], v[2:5]
	s_setprio 0
	s_add_i32 s81, s81, 2
	s_add_u32 s79, s79, 0x100
	s_addc_u32 s80, s80, 0
	s_cmp_gt_u32 s81, 5
	s_mov_b64 s[28:29], s[4:5]
	s_barrier
	s_cbranch_scc0 .LBB0_457
	v_lshl_add_u32 v154, s69, 8, v1
	v_lshl_or_b32 v146, s70, 8, v149
	v_ashrrev_i32_e32 v155, 31, v154
	v_ashrrev_i32_e32 v147, 31, v146
	v_lshlrev_b64 v[156:157], 12, v[154:155]
	v_lshl_add_u64 v[156:157], s[88:89], 0, v[156:157]
	v_lshlrev_b64 v[158:159], 1, v[146:147]
	v_lshl_add_u64 v[146:147], v[156:157], 0, v[158:159]
	v_cvt_pk_bf16_f32 v126, v126, v127
	v_cvt_pk_bf16_f32 v127, v128, v129
	v_cvt_pk_bf16_f32 v128, v122, v123
	v_cvt_pk_bf16_f32 v129, v124, v125
	global_store_dwordx4 v[146:147], v[126:129], off
	v_cvt_pk_bf16_f32 v118, v118, v119
	v_cvt_pk_bf16_f32 v119, v120, v121
	v_cvt_pk_bf16_f32 v120, v110, v111
	v_or_b32_e32 v110, 16, v154
	v_ashrrev_i32_e32 v111, 31, v110
	v_lshlrev_b64 v[110:111], 12, v[110:111]
	v_lshl_add_u64 v[110:111], s[88:89], 0, v[110:111]
	v_cvt_pk_bf16_f32 v121, v112, v113
	global_store_dwordx4 v[146:147], v[118:121], off offset:256
	s_mov_b32 s70, s22
	s_mov_b32 s69, s68
	v_lshl_add_u64 v[118:119], v[110:111], 0, v[158:159]
	v_cvt_pk_bf16_f32 v110, v114, v115
	v_cvt_pk_bf16_f32 v111, v116, v117
	v_cvt_pk_bf16_f32 v112, v106, v107
	v_cvt_pk_bf16_f32 v113, v108, v109
	global_store_dwordx4 v[118:119], v[110:113], off
	v_cvt_pk_bf16_f32 v102, v102, v103
	v_cvt_pk_bf16_f32 v103, v104, v105
	v_cvt_pk_bf16_f32 v104, v94, v95
	v_or_b32_e32 v94, 32, v154
	v_ashrrev_i32_e32 v95, 31, v94
	v_lshlrev_b64 v[94:95], 12, v[94:95]
	v_lshl_add_u64 v[94:95], s[88:89], 0, v[94:95]
	v_cvt_pk_bf16_f32 v105, v96, v97
	global_store_dwordx4 v[118:119], v[102:105], off offset:256
	s_mov_b64 s[30:31], s[26:27]
	s_mov_b64 s[28:29], s[24:25]
	v_lshl_add_u64 v[102:103], v[94:95], 0, v[158:159]
	v_cvt_pk_bf16_f32 v94, v98, v99
	v_cvt_pk_bf16_f32 v95, v100, v101
	v_cvt_pk_bf16_f32 v96, v90, v91
	v_cvt_pk_bf16_f32 v97, v92, v93
	global_store_dwordx4 v[102:103], v[94:97], off
	v_cvt_pk_bf16_f32 v86, v86, v87
	v_cvt_pk_bf16_f32 v87, v88, v89
	v_cvt_pk_bf16_f32 v88, v78, v79
	v_or_b32_e32 v78, 48, v154
	v_ashrrev_i32_e32 v79, 31, v78
	v_lshlrev_b64 v[78:79], 12, v[78:79]
	v_lshl_add_u64 v[78:79], s[88:89], 0, v[78:79]
	v_cvt_pk_bf16_f32 v89, v80, v81
	global_store_dwordx4 v[102:103], v[86:89], off offset:256
	s_nop 1
	v_lshl_add_u64 v[86:87], v[78:79], 0, v[158:159]
	v_cvt_pk_bf16_f32 v78, v82, v83
	v_cvt_pk_bf16_f32 v79, v84, v85
	v_cvt_pk_bf16_f32 v80, v74, v75
	v_cvt_pk_bf16_f32 v81, v76, v77
	global_store_dwordx4 v[86:87], v[78:81], off
	v_cvt_pk_bf16_f32 v70, v70, v71
	v_cvt_pk_bf16_f32 v71, v72, v73
	v_cvt_pk_bf16_f32 v72, v66, v67
	v_cvt_pk_bf16_f32 v73, v68, v69
	global_store_dwordx4 v[86:87], v[70:73], off offset:256
	v_cvt_pk_bf16_f32 v62, v62, v63
	v_cvt_pk_bf16_f32 v63, v64, v65
	v_cvt_pk_bf16_f32 v64, v58, v59
	v_add_co_u32_e32 v58, vcc, s74, v146
	v_lshl_add_u64 v[66:67], v[146:147], 0, s[8:9]
	s_nop 0
	v_addc_co_u32_e32 v59, vcc, 0, v147, vcc
	v_cvt_pk_bf16_f32 v65, v60, v61
	global_store_dwordx4 v[58:59], v[62:65], off
	v_cvt_pk_bf16_f32 v50, v50, v51
	v_cvt_pk_bf16_f32 v51, v52, v53
	v_cvt_pk_bf16_f32 v52, v42, v43
	v_cvt_pk_bf16_f32 v53, v44, v45
	global_store_dwordx4 v[66:67], v[50:53], off offset:256
	v_cvt_pk_bf16_f32 v42, v54, v55
	v_cvt_pk_bf16_f32 v43, v56, v57
	v_cvt_pk_bf16_f32 v44, v46, v47
	v_add_co_u32_e32 v46, vcc, s75, v146
	s_nop 0
	v_lshl_add_u64 v[50:51], v[146:147], 0, s[16:17]
	v_addc_co_u32_e32 v47, vcc, 0, v147, vcc
	v_cvt_pk_bf16_f32 v45, v48, v49
	global_store_dwordx4 v[46:47], v[42:45], off
	v_cvt_pk_bf16_f32 v34, v34, v35
	v_cvt_pk_bf16_f32 v35, v36, v37
	v_cvt_pk_bf16_f32 v36, v26, v27
	v_cvt_pk_bf16_f32 v37, v28, v29
	global_store_dwordx4 v[50:51], v[34:37], off offset:256
	v_cvt_pk_bf16_f32 v26, v38, v39
	v_cvt_pk_bf16_f32 v27, v40, v41
	v_cvt_pk_bf16_f32 v28, v30, v31
	v_add_co_u32_e32 v30, vcc, s76, v146
	s_nop 0
	v_lshl_add_u64 v[34:35], v[146:147], 0, s[18:19]
	v_addc_co_u32_e32 v31, vcc, 0, v147, vcc
	v_cvt_pk_bf16_f32 v29, v32, v33
	global_store_dwordx4 v[30:31], v[26:29], off
	v_cvt_pk_bf16_f32 v18, v18, v19
	v_cvt_pk_bf16_f32 v19, v20, v21
	v_cvt_pk_bf16_f32 v20, v10, v11
	v_cvt_pk_bf16_f32 v21, v12, v13
	global_store_dwordx4 v[34:35], v[18:21], off offset:256
	v_cvt_pk_bf16_f32 v10, v22, v23
	v_cvt_pk_bf16_f32 v11, v24, v25
	v_cvt_pk_bf16_f32 v12, v14, v15
	v_add_co_u32_e32 v14, vcc, s77, v146
	s_nop 0
	v_lshl_add_u64 v[18:19], v[146:147], 0, s[20:21]
	v_addc_co_u32_e32 v15, vcc, 0, v147, vcc
	s_and_b64 vcc, exec, s[2:3]
	v_cvt_pk_bf16_f32 v13, v16, v17
	global_store_dwordx4 v[14:15], v[10:13], off
	v_cvt_pk_bf16_f32 v6, v6, v7
	v_cvt_pk_bf16_f32 v7, v8, v9
	v_cvt_pk_bf16_f32 v8, v2, v3
	v_cvt_pk_bf16_f32 v9, v4, v5
	global_store_dwordx4 v[18:19], v[6:9], off offset:256
	s_cbranch_vccz .LBB0_448
	s_waitcnt vmcnt(0)
	s_cmpk_gt_u32 s36, 0xff
	s_cbranch_scc1 .LBB0_461
	s_barrier

.LBB0_696:
	ds_read_b128 v[82:85], v208
	ds_read_b128 v[86:89], v208 offset:1024
	ds_read_b128 v[94:97], v208 offset:2048
	ds_read_b128 v[102:105], v208 offset:3072
	ds_read_b128 v[146:149], v209
	ds_read_b128 v[150:153], v209 offset:1024
	ds_read_b128 v[154:157], v209 offset:2048
	ds_read_b128 v[158:161], v209 offset:3072
	ds_read_b128 v[178:181], v209 offset:4096
	ds_read_b128 v[186:189], v209 offset:5120
	ds_read_b128 v[190:193], v209 offset:6144
	ds_read_b128 v[194:197], v209 offset:7168
	s_add_u32 s8, s2, 0x100
	s_addc_u32 s9, s3, 0
	s_cmp_eq_u32 s68, 28
	s_cselect_b32 s31, s25, s9
	s_cselect_b32 s30, s24, s8
	s_cselect_b32 s29, s1, s63
	s_cselect_b32 s28, s23, s53
	v_lshl_add_u64 v[182:183], s[2:3], 0, v[170:171]
	s_add_i32 m0, s41, 0xc000
	global_load_lds_dwordx4 v[182:183], off
	v_lshl_add_u64 v[182:183], s[2:3], 0, v[172:173]
	s_add_i32 m0, s41, 0xe000
	s_nop 0
	global_load_lds_dwordx4 v[182:183], off
	ds_read_b128 v[198:201], v210
	ds_read_b128 v[202:205], v210 offset:1024
	ds_read_b128 v[212:215], v210 offset:2048
	ds_read_b128 v[216:219], v210 offset:3072
	s_waitcnt vmcnt(8)
	s_waitcnt lgkmcnt(0)
	s_barrier
	s_setprio 1
	v_mfma_f32_16x16x32_bf16 v[142:145], v[82:85], v[146:149], v[142:145]
	v_mfma_f32_16x16x32_bf16 v[138:141], v[94:97], v[146:149], v[138:141]
	v_mfma_f32_16x16x32_bf16 v[126:129], v[82:85], v[154:157], v[126:129]
	v_mfma_f32_16x16x32_bf16 v[122:125], v[94:97], v[154:157], v[122:125]
	v_mfma_f32_16x16x32_bf16 v[110:113], v[82:85], v[178:181], v[110:113]
	v_mfma_f32_16x16x32_bf16 v[106:109], v[94:97], v[178:181], v[106:109]
	v_mfma_f32_16x16x32_bf16 v[78:81], v[82:85], v[190:193], v[78:81]
	v_mfma_f32_16x16x32_bf16 v[74:77], v[94:97], v[190:193], v[74:77]
	v_mfma_f32_16x16x32_bf16 v[142:145], v[86:89], v[150:153], v[142:145]
	v_mfma_f32_16x16x32_bf16 v[138:141], v[102:105], v[150:153], v[138:141]
	v_mfma_f32_16x16x32_bf16 v[126:129], v[86:89], v[158:161], v[126:129]
	v_mfma_f32_16x16x32_bf16 v[122:125], v[102:105], v[158:161], v[122:125]
	v_mfma_f32_16x16x32_bf16 v[110:113], v[86:89], v[186:189], v[110:113]
	v_mfma_f32_16x16x32_bf16 v[106:109], v[102:105], v[186:189], v[106:109]
	v_mfma_f32_16x16x32_bf16 v[78:81], v[86:89], v[194:197], v[78:81]
	v_mfma_f32_16x16x32_bf16 v[74:77], v[102:105], v[194:197], v[74:77]
	v_mfma_f32_16x16x32_bf16 v[134:137], v[198:201], v[146:149], v[134:137]
	v_mfma_f32_16x16x32_bf16 v[130:133], v[212:215], v[146:149], v[130:133]
	v_mfma_f32_16x16x32_bf16 v[118:121], v[198:201], v[154:157], v[118:121]
	v_mfma_f32_16x16x32_bf16 v[114:117], v[212:215], v[154:157], v[114:117]
	v_mfma_f32_16x16x32_bf16 v[98:101], v[198:201], v[178:181], v[98:101]
	v_mfma_f32_16x16x32_bf16 v[90:93], v[212:215], v[178:181], v[90:93]
	v_mfma_f32_16x16x32_bf16 v[70:73], v[198:201], v[190:193], v[70:73]
	v_mfma_f32_16x16x32_bf16 v[66:69], v[212:215], v[190:193], v[66:69]
	v_mfma_f32_16x16x32_bf16 v[134:137], v[202:205], v[150:153], v[134:137]
	v_mfma_f32_16x16x32_bf16 v[130:133], v[216:219], v[150:153], v[130:133]
	v_mfma_f32_16x16x32_bf16 v[118:121], v[202:205], v[158:161], v[118:121]
	v_mfma_f32_16x16x32_bf16 v[114:117], v[216:219], v[158:161], v[114:117]
	v_mfma_f32_16x16x32_bf16 v[98:101], v[202:205], v[186:189], v[98:101]
	v_mfma_f32_16x16x32_bf16 v[90:93], v[216:219], v[186:189], v[90:93]
	v_mfma_f32_16x16x32_bf16 v[70:73], v[202:205], v[194:197], v[70:73]
	v_mfma_f32_16x16x32_bf16 v[66:69], v[216:219], v[194:197], v[66:69]
	s_setprio 0
	s_barrier
	ds_read_b128 v[146:149], v209 offset:16384
	ds_read_b128 v[150:153], v209 offset:17408
	ds_read_b128 v[154:157], v209 offset:18432
	ds_read_b128 v[158:161], v209 offset:19456
	ds_read_b128 v[178:181], v209 offset:20480
	ds_read_b128 v[186:189], v209 offset:21504
	ds_read_b128 v[190:193], v209 offset:22528
	ds_read_b128 v[194:197], v209 offset:23552
	s_add_i32 s2, s59, s37
	v_lshl_add_u64 v[182:183], s[28:29], 0, v[164:165]
	s_mov_b32 m0, s2
	global_load_lds_dwordx4 v[182:183], off
	v_lshl_add_u64 v[220:221], s[28:29], 0, v[168:169]
	s_add_i32 m0, s2, 0x2000
	s_nop 0
	global_load_lds_dwordx4 v[220:221], off
	s_mov_b32 m0, s41
	v_lshl_add_u64 v[222:223], s[30:31], 0, v[162:163]
	global_load_lds_dwordx4 v[222:223], off
	v_lshl_add_u64 v[224:225], s[30:31], 0, v[166:167]
	s_mov_b32 m0, s42
	s_nop 0
	global_load_lds_dwordx4 v[224:225], off
	s_waitcnt vmcnt(6)
	s_waitcnt lgkmcnt(0)
	s_barrier
	s_setprio 1
	v_mfma_f32_16x16x32_bf16 v[62:65], v[82:85], v[146:149], v[62:65]
	v_mfma_f32_16x16x32_bf16 v[58:61], v[94:97], v[146:149], v[58:61]
	v_mfma_f32_16x16x32_bf16 v[46:49], v[82:85], v[154:157], v[46:49]
	v_mfma_f32_16x16x32_bf16 v[42:45], v[94:97], v[154:157], v[42:45]
	v_mfma_f32_16x16x32_bf16 v[30:33], v[82:85], v[178:181], v[30:33]
	v_mfma_f32_16x16x32_bf16 v[26:29], v[94:97], v[178:181], v[26:29]
	v_mfma_f32_16x16x32_bf16 v[14:17], v[82:85], v[190:193], v[14:17]
	v_mfma_f32_16x16x32_bf16 v[10:13], v[94:97], v[190:193], v[10:13]
	v_mfma_f32_16x16x32_bf16 v[62:65], v[86:89], v[150:153], v[62:65]
	v_mfma_f32_16x16x32_bf16 v[58:61], v[102:105], v[150:153], v[58:61]
	v_mfma_f32_16x16x32_bf16 v[46:49], v[86:89], v[158:161], v[46:49]
	v_mfma_f32_16x16x32_bf16 v[42:45], v[102:105], v[158:161], v[42:45]
	v_mfma_f32_16x16x32_bf16 v[30:33], v[86:89], v[186:189], v[30:33]
	v_mfma_f32_16x16x32_bf16 v[26:29], v[102:105], v[186:189], v[26:29]
	v_mfma_f32_16x16x32_bf16 v[14:17], v[86:89], v[194:197], v[14:17]
	v_mfma_f32_16x16x32_bf16 v[10:13], v[102:105], v[194:197], v[10:13]
	v_mfma_f32_16x16x32_bf16 v[54:57], v[198:201], v[146:149], v[54:57]
	v_mfma_f32_16x16x32_bf16 v[50:53], v[212:215], v[146:149], v[50:53]
	v_mfma_f32_16x16x32_bf16 v[38:41], v[198:201], v[154:157], v[38:41]
	v_mfma_f32_16x16x32_bf16 v[34:37], v[212:215], v[154:157], v[34:37]
	v_mfma_f32_16x16x32_bf16 v[22:25], v[198:201], v[178:181], v[22:25]
	v_mfma_f32_16x16x32_bf16 v[18:21], v[212:215], v[178:181], v[18:21]
	v_mfma_f32_16x16x32_bf16 v[6:9], v[198:201], v[190:193], v[6:9]
	v_mfma_f32_16x16x32_bf16 v[2:5], v[212:215], v[190:193], v[2:5]
	v_mfma_f32_16x16x32_bf16 v[54:57], v[202:205], v[150:153], v[54:57]
	v_mfma_f32_16x16x32_bf16 v[50:53], v[216:219], v[150:153], v[50:53]
	v_mfma_f32_16x16x32_bf16 v[38:41], v[202:205], v[158:161], v[38:41]
	v_mfma_f32_16x16x32_bf16 v[34:37], v[216:219], v[158:161], v[34:37]
	v_mfma_f32_16x16x32_bf16 v[22:25], v[202:205], v[186:189], v[22:25]
	v_mfma_f32_16x16x32_bf16 v[18:21], v[216:219], v[186:189], v[18:21]
	v_mfma_f32_16x16x32_bf16 v[6:9], v[202:205], v[194:197], v[6:9]
	v_mfma_f32_16x16x32_bf16 v[2:5], v[216:219], v[194:197], v[2:5]
	s_setprio 0
	s_barrier
	s_add_u32 s2, s28, 0x80000
	s_addc_u32 s3, s29, 0
	s_add_i32 s69, s60, s37
	v_lshl_add_u64 v[82:83], s[2:3], 0, v[164:165]
	s_mov_b32 m0, s69
	s_nop 0
	global_load_lds_dwordx4 v[82:83], off
	v_lshl_add_u64 v[82:83], s[2:3], 0, v[168:169]
	s_add_i32 m0, s69, 0x2000
	s_nop 0
	global_load_lds_dwordx4 v[82:83], off
	s_add_i32 s69, 0, 0x18000
	v_add_u32_e32 v102, s69, v206
	ds_read_b128 v[82:85], v102
	ds_read_b128 v[86:89], v102 offset:1024
	ds_read_b128 v[94:97], v102 offset:2048
	ds_read_b128 v[102:105], v102 offset:3072
	ds_read_b128 v[146:149], v209 offset:32768
	ds_read_b128 v[150:153], v209 offset:33792
	ds_read_b128 v[154:157], v209 offset:34816
	ds_read_b128 v[158:161], v209 offset:35840
	ds_read_b128 v[178:181], v209 offset:36864
	ds_read_b128 v[186:189], v209 offset:37888
	ds_read_b128 v[190:193], v209 offset:38912
	ds_read_b128 v[194:197], v209 offset:39936
	s_add_u32 s2, s30, 0xf0000
	s_addc_u32 s3, s31, 0
	s_mov_b32 m0, s43
	v_lshl_add_u64 v[198:199], s[2:3], 0, v[162:163]
	global_load_lds_dwordx4 v[198:199], off
	v_lshl_add_u64 v[198:199], s[2:3], 0, v[166:167]
	s_mov_b32 m0, s44
	s_nop 0
	global_load_lds_dwordx4 v[198:199], off
	v_add_u32_e32 v216, 0x1c000, v206
	ds_read_b128 v[198:201], v216
	ds_read_b128 v[202:205], v216 offset:1024
	ds_read_b128 v[212:215], v216 offset:2048
	ds_read_b128 v[216:219], v216 offset:3072
	s_waitcnt vmcnt(8)
	s_waitcnt lgkmcnt(0)
	s_barrier
	s_setprio 1
	v_mfma_f32_16x16x32_bf16 v[142:145], v[82:85], v[146:149], v[142:145]
	v_mfma_f32_16x16x32_bf16 v[138:141], v[94:97], v[146:149], v[138:141]
	v_mfma_f32_16x16x32_bf16 v[126:129], v[82:85], v[154:157], v[126:129]
	v_mfma_f32_16x16x32_bf16 v[122:125], v[94:97], v[154:157], v[122:125]
	v_mfma_f32_16x16x32_bf16 v[110:113], v[82:85], v[178:181], v[110:113]
	v_mfma_f32_16x16x32_bf16 v[106:109], v[94:97], v[178:181], v[106:109]
	v_mfma_f32_16x16x32_bf16 v[78:81], v[82:85], v[190:193], v[78:81]
	v_mfma_f32_16x16x32_bf16 v[74:77], v[94:97], v[190:193], v[74:77]
	v_mfma_f32_16x16x32_bf16 v[142:145], v[86:89], v[150:153], v[142:145]
	v_mfma_f32_16x16x32_bf16 v[138:141], v[102:105], v[150:153], v[138:141]
	v_mfma_f32_16x16x32_bf16 v[126:129], v[86:89], v[158:161], v[126:129]
	v_mfma_f32_16x16x32_bf16 v[122:125], v[102:105], v[158:161], v[122:125]
	v_mfma_f32_16x16x32_bf16 v[110:113], v[86:89], v[186:189], v[110:113]
	v_mfma_f32_16x16x32_bf16 v[106:109], v[102:105], v[186:189], v[106:109]
	v_mfma_f32_16x16x32_bf16 v[78:81], v[86:89], v[194:197], v[78:81]
	v_mfma_f32_16x16x32_bf16 v[74:77], v[102:105], v[194:197], v[74:77]
	v_mfma_f32_16x16x32_bf16 v[134:137], v[198:201], v[146:149], v[134:137]
	v_mfma_f32_16x16x32_bf16 v[130:133], v[212:215], v[146:149], v[130:133]
	v_mfma_f32_16x16x32_bf16 v[118:121], v[198:201], v[154:157], v[118:121]
	v_mfma_f32_16x16x32_bf16 v[114:117], v[212:215], v[154:157], v[114:117]
	v_mfma_f32_16x16x32_bf16 v[98:101], v[198:201], v[178:181], v[98:101]
	v_mfma_f32_16x16x32_bf16 v[90:93], v[212:215], v[178:181], v[90:93]
	v_mfma_f32_16x16x32_bf16 v[70:73], v[198:201], v[190:193], v[70:73]
	v_mfma_f32_16x16x32_bf16 v[66:69], v[212:215], v[190:193], v[66:69]
	v_mfma_f32_16x16x32_bf16 v[134:137], v[202:205], v[150:153], v[134:137]
	v_mfma_f32_16x16x32_bf16 v[130:133], v[216:219], v[150:153], v[130:133]
	v_mfma_f32_16x16x32_bf16 v[118:121], v[202:205], v[158:161], v[118:121]
	v_mfma_f32_16x16x32_bf16 v[114:117], v[216:219], v[158:161], v[114:117]
	v_mfma_f32_16x16x32_bf16 v[98:101], v[202:205], v[186:189], v[98:101]
	v_mfma_f32_16x16x32_bf16 v[90:93], v[216:219], v[186:189], v[90:93]
	v_mfma_f32_16x16x32_bf16 v[70:73], v[202:205], v[194:197], v[70:73]
	v_mfma_f32_16x16x32_bf16 v[66:69], v[216:219], v[194:197], v[66:69]
	s_setprio 0
	s_barrier
	ds_read_b128 v[146:149], v209 offset:49152
	ds_read_b128 v[150:153], v209 offset:50176
	ds_read_b128 v[154:157], v209 offset:51200
	ds_read_b128 v[158:161], v209 offset:52224
	ds_read_b128 v[178:181], v209 offset:53248
	ds_read_b128 v[186:189], v209 offset:54272
	ds_read_b128 v[190:193], v209 offset:55296
	ds_read_b128 v[194:197], v209 offset:56320
	s_add_i32 s30, 0, 0x1c000
	s_add_i32 s2, s69, s37
	v_lshl_add_u64 v[182:183], v[182:183], 0, s[20:21]
	s_mov_b32 m0, s2
	global_load_lds_dwordx4 v[182:183], off
	v_lshl_add_u64 v[182:183], v[220:221], 0, s[20:21]
	s_add_i32 m0, s2, 0x2000
	s_nop 0
	global_load_lds_dwordx4 v[182:183], off
	s_mov_b32 m0, s47
	v_lshl_add_u64 v[182:183], v[222:223], 0, s[20:21]
	global_load_lds_dwordx4 v[182:183], off
	v_lshl_add_u64 v[182:183], v[224:225], 0, s[20:21]
	s_mov_b32 m0, s48
	s_nop 0
	global_load_lds_dwordx4 v[182:183], off
	s_add_u32 s2, s28, 0x80080
	s_addc_u32 s3, s29, 0
	s_add_i32 s28, s30, s37
	v_lshl_add_u64 v[182:183], s[2:3], 0, v[164:165]
	s_mov_b32 m0, s28
	s_nop 0
	global_load_lds_dwordx4 v[182:183], off
	v_lshl_add_u64 v[182:183], s[2:3], 0, v[168:169]
	s_add_i32 m0, s28, 0x2000
	s_nop 0
	global_load_lds_dwordx4 v[182:183], off
	s_waitcnt vmcnt(8)
	s_waitcnt lgkmcnt(0)
	s_barrier
	s_setprio 1
	v_mfma_f32_16x16x32_bf16 v[62:65], v[82:85], v[146:149], v[62:65]
	v_mfma_f32_16x16x32_bf16 v[58:61], v[94:97], v[146:149], v[58:61]
	v_mfma_f32_16x16x32_bf16 v[46:49], v[82:85], v[154:157], v[46:49]
	v_mfma_f32_16x16x32_bf16 v[42:45], v[94:97], v[154:157], v[42:45]
	v_mfma_f32_16x16x32_bf16 v[30:33], v[82:85], v[178:181], v[30:33]
	v_mfma_f32_16x16x32_bf16 v[26:29], v[94:97], v[178:181], v[26:29]
	v_mfma_f32_16x16x32_bf16 v[14:17], v[82:85], v[190:193], v[14:17]
	v_mfma_f32_16x16x32_bf16 v[10:13], v[94:97], v[190:193], v[10:13]
	v_mfma_f32_16x16x32_bf16 v[62:65], v[86:89], v[150:153], v[62:65]
	v_mfma_f32_16x16x32_bf16 v[58:61], v[102:105], v[150:153], v[58:61]
	v_mfma_f32_16x16x32_bf16 v[46:49], v[86:89], v[158:161], v[46:49]
	v_mfma_f32_16x16x32_bf16 v[42:45], v[102:105], v[158:161], v[42:45]
	v_mfma_f32_16x16x32_bf16 v[30:33], v[86:89], v[186:189], v[30:33]
	v_mfma_f32_16x16x32_bf16 v[26:29], v[102:105], v[186:189], v[26:29]
	v_mfma_f32_16x16x32_bf16 v[14:17], v[86:89], v[194:197], v[14:17]
	v_mfma_f32_16x16x32_bf16 v[10:13], v[102:105], v[194:197], v[10:13]
	v_mfma_f32_16x16x32_bf16 v[54:57], v[198:201], v[146:149], v[54:57]
	v_mfma_f32_16x16x32_bf16 v[50:53], v[212:215], v[146:149], v[50:53]
	v_mfma_f32_16x16x32_bf16 v[38:41], v[198:201], v[154:157], v[38:41]
	v_mfma_f32_16x16x32_bf16 v[34:37], v[212:215], v[154:157], v[34:37]
	v_mfma_f32_16x16x32_bf16 v[22:25], v[198:201], v[178:181], v[22:25]
	v_mfma_f32_16x16x32_bf16 v[18:21], v[212:215], v[178:181], v[18:21]
	v_mfma_f32_16x16x32_bf16 v[6:9], v[198:201], v[190:193], v[6:9]
	v_mfma_f32_16x16x32_bf16 v[2:5], v[212:215], v[190:193], v[2:5]
	v_mfma_f32_16x16x32_bf16 v[54:57], v[202:205], v[150:153], v[54:57]
	v_mfma_f32_16x16x32_bf16 v[50:53], v[216:219], v[150:153], v[50:53]
	v_mfma_f32_16x16x32_bf16 v[38:41], v[202:205], v[158:161], v[38:41]
	v_mfma_f32_16x16x32_bf16 v[34:37], v[216:219], v[158:161], v[34:37]
	v_mfma_f32_16x16x32_bf16 v[22:25], v[202:205], v[186:189], v[22:25]
	v_mfma_f32_16x16x32_bf16 v[18:21], v[216:219], v[186:189], v[18:21]
	v_mfma_f32_16x16x32_bf16 v[6:9], v[202:205], v[194:197], v[6:9]
	v_mfma_f32_16x16x32_bf16 v[2:5], v[216:219], v[194:197], v[2:5]
	s_setprio 0
	s_add_i32 s68, s68, 2
	s_add_u32 s53, s53, 0x100
	s_addc_u32 s63, s63, 0
	s_cmp_gt_u32 s68, 29
	s_mov_b64 s[2:3], s[8:9]
	s_barrier
	s_cbranch_scc0 .LBB0_696
	s_min_i32 s1, s52, 64
	s_ashr_i32 s1, s1, 3
	v_lshl_or_b32 v178, s0, 8, v207
	s_mul_hi_i32 s2, s1, 0xc000
	s_mul_i32 s1, s1, 0xc000
	s_add_u32 s0, s10, s1
	v_ashrrev_i32_e32 v179, 31, v178
	s_addc_u32 s1, s11, s2
	v_lshlrev_b64 v[198:199], 2, v[178:179]
	v_lshl_add_u32 v200, s52, 8, v1
	v_lshl_add_u64 v[82:83], s[0:1], 0, v[198:199]
	v_add_u32_e32 v94, 0xffffc000, v200
	v_ashrrev_i32_e32 v201, 31, v200
	v_cmp_gt_i32_e64 s[0:1], s46, v200
	v_add_co_u32_e32 v84, vcc, s46, v82
	s_nop 0
	v_cndmask_b32_e64 v95, 0, v201, s[0:1]
	v_cndmask_b32_e64 v94, v94, v200, s[0:1]
	v_mov_b32_e32 v152, s15
	v_mov_b32_e32 v153, s13
	v_mov_b32_e32 v154, s14
	v_mov_b32_e32 v155, s12
	v_addc_co_u32_e32 v85, vcc, 0, v83, vcc
	v_cndmask_b32_e64 v97, v152, v153, s[0:1]
	v_cndmask_b32_e64 v96, v154, v155, s[0:1]
	v_lshlrev_b64 v[94:95], 13, v[94:95]
	v_add_co_u32_e32 v82, vcc, s49, v82
	v_lshl_add_u64 v[94:95], v[96:97], 0, v[94:95]
	v_lshl_add_u64 v[146:147], v[94:95], 0, v[198:199]
	v_addc_co_u32_e32 v83, vcc, 0, v83, vcc
	global_load_dwordx4 v[86:89], v[84:85], off
	global_load_dwordx4 v[180:183], v[146:147], off
	global_load_dwordx4 v[186:189], v[82:83], off
	global_load_dwordx4 v[190:193], v[82:83], off offset:64
	global_load_dwordx4 v[194:197], v[82:83], off offset:512
	global_load_dwordx4 v[212:215], v[82:83], off offset:576
	v_lshl_add_u64 v[82:83], s[56:57], 0, v[198:199]
	global_load_dwordx4 v[216:219], v[82:83], off
	global_load_dwordx4 v[220:223], v[82:83], off offset:64
	global_load_dwordx4 v[224:227], v[82:83], off offset:512
	global_load_dwordx4 v[228:231], v[82:83], off offset:576
	global_load_dwordx4 v[232:235], v[146:147], off offset:64
	global_load_dwordx4 v[102:105], v[84:85], off offset:64
	global_load_dwordx4 v[94:97], v[84:85], off offset:512
	global_load_dwordx4 v[236:239], v[146:147], off offset:512
	global_load_dwordx4 v[240:243], v[146:147], off offset:576
	s_nop 0
	global_load_dwordx4 v[82:85], v[84:85], off offset:576
	v_or_b32_e32 v202, 16, v200
	v_add_u32_e32 v150, 0xffffc010, v200
	v_ashrrev_i32_e32 v203, 31, v202
	v_cmp_gt_i32_e32 vcc, s46, v202
	v_lshlrev_b64 v[146:147], 13, v[200:201]
	v_lshl_add_u64 v[146:147], s[66:67], 0, v[146:147]
	v_cndmask_b32_e32 v151, 0, v203, vcc
	v_cndmask_b32_e32 v150, v150, v202, vcc
	v_cndmask_b32_e32 v153, v152, v153, vcc
	v_cndmask_b32_e32 v152, v154, v155, vcc
	v_lshlrev_b64 v[150:151], 13, v[150:151]
	v_lshlrev_b64 v[148:149], 12, v[200:201]
	v_lshl_add_u64 v[204:205], v[146:147], 0, v[198:199]
	v_lshl_add_u64 v[146:147], v[152:153], 0, v[150:151]
	v_lshl_add_u64 v[148:149], s[88:89], 0, v[148:149]
	v_lshl_add_u64 v[146:147], v[146:147], 0, v[198:199]
	v_lshl_add_u64 v[244:245], v[178:179], 1, v[148:149]
	global_load_dwordx4 v[158:161], v[146:147], off
	global_load_dwordx4 v[154:157], v[146:147], off offset:64
	global_load_dwordx4 v[150:153], v[146:147], off offset:512
	s_nop 0
	global_load_dwordx4 v[146:149], v[146:147], off offset:576
	s_waitcnt vmcnt(0)
	v_pk_fma_f32 v[138:139], v[138:139], v[102:103], v[232:233]
	v_pk_fma_f32 v[144:145], v[144:145], v[88:89], v[182:183]
	v_pk_fma_f32 v[142:143], v[142:143], v[86:87], v[180:181]
	v_pk_add_f32 v[180:181], v[188:189], 1.0 op_sel_hi:[1,0]
	v_pk_add_f32 v[182:183], v[186:187], 1.0 op_sel_hi:[1,0]
	v_pk_add_f32 v[212:213], v[212:213], 1.0 op_sel_hi:[1,0]
	v_pk_add_f32 v[246:247], v[196:197], 1.0 op_sel_hi:[1,0]
	v_pk_add_f32 v[248:249], v[194:195], 1.0 op_sel_hi:[1,0]
	v_pk_mul_f32 v[194:195], v[218:219], v[180:181]
	v_pk_mul_f32 v[196:197], v[216:217], v[182:183]
	v_pk_mul_f32 v[180:181], v[228:229], v[212:213]
	v_mul_f32_e32 v212, v143, v143
	global_store_dwordx4 v[204:205], v[142:145], off
	v_fmac_f32_e32 v212, v142, v142
	v_pk_add_f32 v[188:189], v[190:191], 1.0 op_sel_hi:[1,0]
	v_pk_mul_f32 v[142:143], v[196:197], v[142:143]
	v_fmac_f32_e32 v212, v144, v144
	v_cvt_pk_bf16_f32 v142, v142, v143
	v_pk_add_f32 v[186:187], v[192:193], 1.0 op_sel_hi:[1,0]
	v_pk_mul_f32 v[192:193], v[220:221], v[188:189]
	v_fmac_f32_e32 v212, v145, v145
	v_pk_mul_f32 v[144:145], v[194:195], v[144:145]
	v_pk_fma_f32 v[140:141], v[140:141], v[104:105], v[234:235]
	v_cvt_pk_bf16_f32 v143, v144, v145
	global_store_dwordx2 v[244:245], v[142:143], off
	v_mul_f32_e32 v142, v139, v139
	global_store_dwordx4 v[204:205], v[138:141], off offset:64
	v_fmac_f32_e32 v142, v138, v138
	v_pk_mul_f32 v[190:191], v[222:223], v[186:187]
	v_pk_mul_f32 v[138:139], v[192:193], v[138:139]
	v_fmac_f32_e32 v142, v140, v140
	v_cvt_pk_bf16_f32 v138, v138, v139
	v_pk_fma_f32 v[134:135], v[134:135], v[94:95], v[236:237]
	v_fmac_f32_e32 v142, v141, v141
	v_pk_mul_f32 v[140:141], v[190:191], v[140:141]
	v_pk_fma_f32 v[136:137], v[136:137], v[96:97], v[238:239]
	v_cvt_pk_bf16_f32 v139, v140, v141
	global_store_dwordx2 v[244:245], v[138:139], off offset:32
	v_mul_f32_e32 v138, v135, v135
	v_fmac_f32_e32 v138, v134, v134
	v_pk_mul_f32 v[188:189], v[224:225], v[248:249]
	v_fmac_f32_e32 v138, v136, v136
	v_add_f32_e32 v142, v212, v142
	global_store_dwordx4 v[204:205], v[134:137], off offset:512
	v_fmac_f32_e32 v138, v137, v137
	v_add_f32_e32 v139, v142, v138
	v_pk_mul_f32 v[134:135], v[188:189], v[134:135]
	v_pk_mul_f32 v[186:187], v[226:227], v[246:247]
	v_cvt_pk_bf16_f32 v138, v134, v135
	v_pk_fma_f32 v[134:135], v[132:133], v[84:85], v[242:243]
	v_pk_fma_f32 v[132:133], v[130:131], v[82:83], v[240:241]
	v_xor_b32_e32 v131, 16, v211
	v_mul_f32_e32 v130, v133, v133
	v_fmac_f32_e32 v130, v132, v132
	v_fmac_f32_e32 v130, v134, v134
	v_fmac_f32_e32 v130, v135, v135
	v_add_f32_e32 v130, v139, v130
	v_and_b32_e32 v139, 64, v211
	v_add_u32_e32 v140, 64, v139
	v_cmp_lt_i32_e32 vcc, v131, v140
	v_pk_add_f32 v[214:215], v[214:215], 1.0 op_sel_hi:[1,0]
	v_pk_mul_f32 v[136:137], v[186:187], v[136:137]
	v_cndmask_b32_e32 v131, v211, v131, vcc
	v_lshlrev_b32_e32 v212, 2, v131
	ds_bpermute_b32 v131, v212, v130
	v_cvt_pk_bf16_f32 v139, v136, v137
	v_pk_mul_f32 v[182:183], v[230:231], v[214:215]
	global_store_dwordx2 v[244:245], v[138:139], off offset:256
	global_store_dwordx4 v[204:205], v[132:135], off offset:576
	s_waitcnt lgkmcnt(0)
	v_add_f32_e32 v130, v130, v131
	v_xor_b32_e32 v131, 32, v211
	v_cmp_lt_i32_e32 vcc, v131, v140
	v_pk_mul_f32 v[132:133], v[180:181], v[132:133]
	v_pk_mul_f32 v[134:135], v[182:183], v[134:135]
	v_cndmask_b32_e32 v131, v211, v131, vcc
	v_lshlrev_b32_e32 v213, 2, v131
	ds_bpermute_b32 v131, v213, v130
	v_cvt_pk_bf16_f32 v132, v132, v133
	v_cvt_pk_bf16_f32 v133, v134, v135
	global_store_dwordx2 v[244:245], v[132:133], off offset:288
	s_and_saveexec_b64 s[0:1], s[4:5]
	s_cbranch_execz .LBB0_699
	v_lshl_add_u64 v[132:133], v[200:201], 2, s[18:19]
	s_waitcnt lgkmcnt(0)
	v_add_f32_e32 v130, v130, v131
	global_atomic_add_f32 v[132:133], v130, off

.LBB0_803:
	s_add_i32 s58, 0, 0x10000
	v_add_u32_e32 v140, s58, v161
	ds_read_b128 v[128:131], v140
	ds_read_b128 v[132:135], v140 offset:1024
	ds_read_b128 v[136:139], v140 offset:2048
	ds_read_b128 v[140:143], v140 offset:3072
	ds_read_b128 v[154:157], v163
	ds_read_b128 v[164:167], v163 offset:1024
	ds_read_b128 v[168:171], v163 offset:2048
	ds_read_b128 v[172:175], v163 offset:3072
	ds_read_b128 v[176:179], v163 offset:4096
	ds_read_b128 v[180:183], v163 offset:5120
	ds_read_b128 v[196:199], v163 offset:6144
	ds_read_b128 v[200:203], v163 offset:7168
	s_add_u32 s4, s12, 0xfff80080
	s_addc_u32 s20, s13, -1
	s_cmp_eq_u32 s57, 28
	s_cselect_b32 s25, s15, s20
	s_cselect_b32 s24, s45, s4
	s_cselect_b32 s21, s3, s56
	s_cselect_b32 s20, s52, s53
	v_lshl_add_u64 v[158:159], s[12:13], 0, v[150:151]
	s_add_i32 m0, s16, 0xc000
	global_load_lds_dwordx4 v[158:159], off
	v_lshl_add_u64 v[158:159], s[12:13], 0, v[152:153]
	s_add_i32 m0, s16, 0xe000
	s_nop 0
	global_load_lds_dwordx4 v[158:159], off
	v_add_u32_e32 v216, 0x14000, v161
	ds_read_b128 v[204:207], v216
	ds_read_b128 v[208:211], v216 offset:1024
	ds_read_b128 v[212:215], v216 offset:2048
	ds_read_b128 v[216:219], v216 offset:3072
	s_waitcnt vmcnt(8)
	s_waitcnt lgkmcnt(0)
	s_barrier
	s_setprio 1
	v_mfma_f32_16x16x32_bf16 v[124:127], v[128:131], v[154:157], v[124:127]
	v_mfma_f32_16x16x32_bf16 v[120:123], v[136:139], v[154:157], v[120:123]
	v_mfma_f32_16x16x32_bf16 v[108:111], v[128:131], v[168:171], v[108:111]
	v_mfma_f32_16x16x32_bf16 v[104:107], v[136:139], v[168:171], v[104:107]
	v_mfma_f32_16x16x32_bf16 v[92:95], v[128:131], v[176:179], v[92:95]
	v_mfma_f32_16x16x32_bf16 v[88:91], v[136:139], v[176:179], v[88:91]
	v_mfma_f32_16x16x32_bf16 v[76:79], v[128:131], v[196:199], v[76:79]
	v_mfma_f32_16x16x32_bf16 v[72:75], v[136:139], v[196:199], v[72:75]
	v_mfma_f32_16x16x32_bf16 v[124:127], v[132:135], v[164:167], v[124:127]
	v_mfma_f32_16x16x32_bf16 v[120:123], v[140:143], v[164:167], v[120:123]
	v_mfma_f32_16x16x32_bf16 v[108:111], v[132:135], v[172:175], v[108:111]
	v_mfma_f32_16x16x32_bf16 v[104:107], v[140:143], v[172:175], v[104:107]
	v_mfma_f32_16x16x32_bf16 v[92:95], v[132:135], v[180:183], v[92:95]
	v_mfma_f32_16x16x32_bf16 v[88:91], v[140:143], v[180:183], v[88:91]
	v_mfma_f32_16x16x32_bf16 v[76:79], v[132:135], v[200:203], v[76:79]
	v_mfma_f32_16x16x32_bf16 v[72:75], v[140:143], v[200:203], v[72:75]
	v_mfma_f32_16x16x32_bf16 v[116:119], v[204:207], v[154:157], v[116:119]
	v_mfma_f32_16x16x32_bf16 v[112:115], v[212:215], v[154:157], v[112:115]
	v_mfma_f32_16x16x32_bf16 v[100:103], v[204:207], v[168:171], v[100:103]
	v_mfma_f32_16x16x32_bf16 v[96:99], v[212:215], v[168:171], v[96:99]
	v_mfma_f32_16x16x32_bf16 v[84:87], v[204:207], v[176:179], v[84:87]
	v_mfma_f32_16x16x32_bf16 v[80:83], v[212:215], v[176:179], v[80:83]
	v_mfma_f32_16x16x32_bf16 v[68:71], v[204:207], v[196:199], v[68:71]
	v_mfma_f32_16x16x32_bf16 v[64:67], v[212:215], v[196:199], v[64:67]
	v_mfma_f32_16x16x32_bf16 v[116:119], v[208:211], v[164:167], v[116:119]
	v_mfma_f32_16x16x32_bf16 v[112:115], v[216:219], v[164:167], v[112:115]
	v_mfma_f32_16x16x32_bf16 v[100:103], v[208:211], v[172:175], v[100:103]
	v_mfma_f32_16x16x32_bf16 v[96:99], v[216:219], v[172:175], v[96:99]
	v_mfma_f32_16x16x32_bf16 v[84:87], v[208:211], v[180:183], v[84:87]
	v_mfma_f32_16x16x32_bf16 v[80:83], v[216:219], v[180:183], v[80:83]
	v_mfma_f32_16x16x32_bf16 v[68:71], v[208:211], v[200:203], v[68:71]
	v_mfma_f32_16x16x32_bf16 v[64:67], v[216:219], v[200:203], v[64:67]
	s_setprio 0
	s_barrier
	ds_read_b128 v[154:157], v163 offset:16384
	ds_read_b128 v[164:167], v163 offset:17408
	ds_read_b128 v[168:171], v163 offset:18432
	ds_read_b128 v[172:175], v163 offset:19456
	ds_read_b128 v[176:179], v163 offset:20480
	ds_read_b128 v[180:183], v163 offset:21504
	ds_read_b128 v[196:199], v163 offset:22528
	ds_read_b128 v[200:203], v163 offset:23552
	s_add_i32 s4, 0, 0x14000
	s_add_i32 s58, s58, s27
	v_lshl_add_u64 v[158:159], s[20:21], 0, v[186:187]
	s_mov_b32 m0, s58
	v_lshl_add_u64 v[220:221], s[20:21], 0, v[144:145]
	global_load_lds_dwordx4 v[158:159], off
	s_add_i32 m0, s58, 0x2000
	s_nop 0
	global_load_lds_dwordx4 v[220:221], off
	s_mov_b32 m0, s16
	v_lshl_add_u64 v[222:223], s[24:25], 0, v[148:149]
	global_load_lds_dwordx4 v[222:223], off
	v_lshl_add_u64 v[224:225], s[24:25], 0, v[146:147]
	s_mov_b32 m0, s17
	s_nop 0
	global_load_lds_dwordx4 v[224:225], off
	s_waitcnt vmcnt(6)
	s_waitcnt lgkmcnt(0)
	s_barrier
	s_setprio 1
	v_mfma_f32_16x16x32_bf16 v[60:63], v[128:131], v[154:157], v[60:63]
	v_mfma_f32_16x16x32_bf16 v[56:59], v[136:139], v[154:157], v[56:59]
	v_mfma_f32_16x16x32_bf16 v[44:47], v[128:131], v[168:171], v[44:47]
	v_mfma_f32_16x16x32_bf16 v[40:43], v[136:139], v[168:171], v[40:43]
	v_mfma_f32_16x16x32_bf16 v[28:31], v[128:131], v[176:179], v[28:31]
	v_mfma_f32_16x16x32_bf16 v[24:27], v[136:139], v[176:179], v[24:27]
	v_mfma_f32_16x16x32_bf16 v[12:15], v[128:131], v[196:199], v[12:15]
	v_mfma_f32_16x16x32_bf16 v[8:11], v[136:139], v[196:199], v[8:11]
	v_mfma_f32_16x16x32_bf16 v[60:63], v[132:135], v[164:167], v[60:63]
	v_mfma_f32_16x16x32_bf16 v[56:59], v[140:143], v[164:167], v[56:59]
	v_mfma_f32_16x16x32_bf16 v[44:47], v[132:135], v[172:175], v[44:47]
	v_mfma_f32_16x16x32_bf16 v[40:43], v[140:143], v[172:175], v[40:43]
	v_mfma_f32_16x16x32_bf16 v[28:31], v[132:135], v[180:183], v[28:31]
	v_mfma_f32_16x16x32_bf16 v[24:27], v[140:143], v[180:183], v[24:27]
	v_mfma_f32_16x16x32_bf16 v[12:15], v[132:135], v[200:203], v[12:15]
	v_mfma_f32_16x16x32_bf16 v[8:11], v[140:143], v[200:203], v[8:11]
	v_mfma_f32_16x16x32_bf16 v[52:55], v[204:207], v[154:157], v[52:55]
	v_mfma_f32_16x16x32_bf16 v[48:51], v[212:215], v[154:157], v[48:51]
	v_mfma_f32_16x16x32_bf16 v[36:39], v[204:207], v[168:171], v[36:39]
	v_mfma_f32_16x16x32_bf16 v[32:35], v[212:215], v[168:171], v[32:35]
	v_mfma_f32_16x16x32_bf16 v[20:23], v[204:207], v[176:179], v[20:23]
	v_mfma_f32_16x16x32_bf16 v[16:19], v[212:215], v[176:179], v[16:19]
	v_mfma_f32_16x16x32_bf16 v[4:7], v[204:207], v[196:199], v[4:7]
	v_mfma_f32_16x16x32_bf16 v[0:3], v[212:215], v[196:199], v[0:3]
	v_mfma_f32_16x16x32_bf16 v[52:55], v[208:211], v[164:167], v[52:55]
	v_mfma_f32_16x16x32_bf16 v[48:51], v[216:219], v[164:167], v[48:51]
	v_mfma_f32_16x16x32_bf16 v[36:39], v[208:211], v[172:175], v[36:39]
	v_mfma_f32_16x16x32_bf16 v[32:35], v[216:219], v[172:175], v[32:35]
	v_mfma_f32_16x16x32_bf16 v[20:23], v[208:211], v[180:183], v[20:23]
	v_mfma_f32_16x16x32_bf16 v[16:19], v[216:219], v[180:183], v[16:19]
	v_mfma_f32_16x16x32_bf16 v[4:7], v[208:211], v[200:203], v[4:7]
	v_mfma_f32_16x16x32_bf16 v[0:3], v[216:219], v[200:203], v[0:3]
	s_setprio 0
	s_barrier
	s_add_u32 s58, s20, 0x80000
	s_addc_u32 s59, s21, 0
	s_add_i32 s4, s4, s27
	v_lshl_add_u64 v[128:129], s[58:59], 0, v[186:187]
	s_mov_b32 m0, s4
	s_nop 0
	global_load_lds_dwordx4 v[128:129], off
	v_lshl_add_u64 v[128:129], s[58:59], 0, v[144:145]
	s_add_i32 m0, s4, 0x2000
	s_nop 0
	global_load_lds_dwordx4 v[128:129], off
	s_add_i32 s4, 0, 0x18000
	v_add_u32_e32 v140, s4, v161
	ds_read_b128 v[128:131], v140
	ds_read_b128 v[132:135], v140 offset:1024
	ds_read_b128 v[136:139], v140 offset:2048
	ds_read_b128 v[140:143], v140 offset:3072
	ds_read_b128 v[154:157], v163 offset:32768
	ds_read_b128 v[164:167], v163 offset:33792
	ds_read_b128 v[168:171], v163 offset:34816
	ds_read_b128 v[172:175], v163 offset:35840
	ds_read_b128 v[176:179], v163 offset:36864
	ds_read_b128 v[180:183], v163 offset:37888
	ds_read_b128 v[196:199], v163 offset:38912
	ds_read_b128 v[200:203], v163 offset:39936
	s_add_u32 s24, s24, 0x80000
	s_addc_u32 s25, s25, 0
	s_mov_b32 m0, s30
	v_lshl_add_u64 v[204:205], s[24:25], 0, v[148:149]
	global_load_lds_dwordx4 v[204:205], off
	v_lshl_add_u64 v[204:205], s[24:25], 0, v[146:147]
	s_mov_b32 m0, s31
	s_nop 0
	global_load_lds_dwordx4 v[204:205], off
	v_add_u32_e32 v216, 0x1c000, v161
	ds_read_b128 v[204:207], v216
	ds_read_b128 v[208:211], v216 offset:1024
	ds_read_b128 v[212:215], v216 offset:2048
	ds_read_b128 v[216:219], v216 offset:3072
	s_waitcnt vmcnt(8)
	s_waitcnt lgkmcnt(0)
	s_barrier
	s_setprio 1
	v_mfma_f32_16x16x32_bf16 v[124:127], v[128:131], v[154:157], v[124:127]
	v_mfma_f32_16x16x32_bf16 v[120:123], v[136:139], v[154:157], v[120:123]
	v_mfma_f32_16x16x32_bf16 v[108:111], v[128:131], v[168:171], v[108:111]
	v_mfma_f32_16x16x32_bf16 v[104:107], v[136:139], v[168:171], v[104:107]
	v_mfma_f32_16x16x32_bf16 v[92:95], v[128:131], v[176:179], v[92:95]
	v_mfma_f32_16x16x32_bf16 v[88:91], v[136:139], v[176:179], v[88:91]
	v_mfma_f32_16x16x32_bf16 v[76:79], v[128:131], v[196:199], v[76:79]
	v_mfma_f32_16x16x32_bf16 v[72:75], v[136:139], v[196:199], v[72:75]
	v_mfma_f32_16x16x32_bf16 v[124:127], v[132:135], v[164:167], v[124:127]
	v_mfma_f32_16x16x32_bf16 v[120:123], v[140:143], v[164:167], v[120:123]
	v_mfma_f32_16x16x32_bf16 v[108:111], v[132:135], v[172:175], v[108:111]
	v_mfma_f32_16x16x32_bf16 v[104:107], v[140:143], v[172:175], v[104:107]
	v_mfma_f32_16x16x32_bf16 v[92:95], v[132:135], v[180:183], v[92:95]
	v_mfma_f32_16x16x32_bf16 v[88:91], v[140:143], v[180:183], v[88:91]
	v_mfma_f32_16x16x32_bf16 v[76:79], v[132:135], v[200:203], v[76:79]
	v_mfma_f32_16x16x32_bf16 v[72:75], v[140:143], v[200:203], v[72:75]
	v_mfma_f32_16x16x32_bf16 v[116:119], v[204:207], v[154:157], v[116:119]
	v_mfma_f32_16x16x32_bf16 v[112:115], v[212:215], v[154:157], v[112:115]
	v_mfma_f32_16x16x32_bf16 v[100:103], v[204:207], v[168:171], v[100:103]
	v_mfma_f32_16x16x32_bf16 v[96:99], v[212:215], v[168:171], v[96:99]
	v_mfma_f32_16x16x32_bf16 v[84:87], v[204:207], v[176:179], v[84:87]
	v_mfma_f32_16x16x32_bf16 v[80:83], v[212:215], v[176:179], v[80:83]
	v_mfma_f32_16x16x32_bf16 v[68:71], v[204:207], v[196:199], v[68:71]
	v_mfma_f32_16x16x32_bf16 v[64:67], v[212:215], v[196:199], v[64:67]
	v_mfma_f32_16x16x32_bf16 v[116:119], v[208:211], v[164:167], v[116:119]
	v_mfma_f32_16x16x32_bf16 v[112:115], v[216:219], v[164:167], v[112:115]
	v_mfma_f32_16x16x32_bf16 v[100:103], v[208:211], v[172:175], v[100:103]
	v_mfma_f32_16x16x32_bf16 v[96:99], v[216:219], v[172:175], v[96:99]
	v_mfma_f32_16x16x32_bf16 v[84:87], v[208:211], v[180:183], v[84:87]
	v_mfma_f32_16x16x32_bf16 v[80:83], v[216:219], v[180:183], v[80:83]
	v_mfma_f32_16x16x32_bf16 v[68:71], v[208:211], v[200:203], v[68:71]
	v_mfma_f32_16x16x32_bf16 v[64:67], v[216:219], v[200:203], v[64:67]
	s_setprio 0
	s_barrier
	ds_read_b128 v[154:157], v163 offset:49152
	ds_read_b128 v[164:167], v163 offset:50176
	ds_read_b128 v[168:171], v163 offset:51200
	ds_read_b128 v[172:175], v163 offset:52224
	ds_read_b128 v[176:179], v163 offset:53248
	ds_read_b128 v[180:183], v163 offset:54272
	ds_read_b128 v[196:199], v163 offset:55296
	ds_read_b128 v[200:203], v163 offset:56320
	s_add_i32 s24, 0, 0x1c000
	s_add_i32 s4, s4, s27
	v_lshl_add_u64 v[158:159], v[158:159], 0, s[0:1]
	s_mov_b32 m0, s4
	global_load_lds_dwordx4 v[158:159], off
	v_lshl_add_u64 v[158:159], v[220:221], 0, s[0:1]
	s_add_i32 m0, s4, 0x2000
	s_nop 0
	global_load_lds_dwordx4 v[158:159], off
	s_mov_b32 m0, s38
	v_lshl_add_u64 v[158:159], v[222:223], 0, s[0:1]
	global_load_lds_dwordx4 v[158:159], off
	v_lshl_add_u64 v[158:159], v[224:225], 0, s[0:1]
	s_mov_b32 m0, s39
	s_nop 0
	global_load_lds_dwordx4 v[158:159], off
	s_add_u32 s20, s20, 0x80080
	s_addc_u32 s21, s21, 0
	s_add_i32 s4, s24, s27
	v_lshl_add_u64 v[158:159], s[20:21], 0, v[186:187]
	s_mov_b32 m0, s4
	s_nop 0
	global_load_lds_dwordx4 v[158:159], off
	v_lshl_add_u64 v[158:159], s[20:21], 0, v[144:145]
	s_add_i32 m0, s4, 0x2000
	s_nop 0
	global_load_lds_dwordx4 v[158:159], off
	s_waitcnt vmcnt(8)
	s_waitcnt lgkmcnt(0)
	s_barrier
	s_setprio 1
	v_mfma_f32_16x16x32_bf16 v[60:63], v[128:131], v[154:157], v[60:63]
	v_mfma_f32_16x16x32_bf16 v[56:59], v[136:139], v[154:157], v[56:59]
	v_mfma_f32_16x16x32_bf16 v[44:47], v[128:131], v[168:171], v[44:47]
	v_mfma_f32_16x16x32_bf16 v[40:43], v[136:139], v[168:171], v[40:43]
	v_mfma_f32_16x16x32_bf16 v[28:31], v[128:131], v[176:179], v[28:31]
	v_mfma_f32_16x16x32_bf16 v[24:27], v[136:139], v[176:179], v[24:27]
	v_mfma_f32_16x16x32_bf16 v[12:15], v[128:131], v[196:199], v[12:15]
	v_mfma_f32_16x16x32_bf16 v[8:11], v[136:139], v[196:199], v[8:11]
	v_mfma_f32_16x16x32_bf16 v[60:63], v[132:135], v[164:167], v[60:63]
	v_mfma_f32_16x16x32_bf16 v[56:59], v[140:143], v[164:167], v[56:59]
	v_mfma_f32_16x16x32_bf16 v[44:47], v[132:135], v[172:175], v[44:47]
	v_mfma_f32_16x16x32_bf16 v[40:43], v[140:143], v[172:175], v[40:43]
	v_mfma_f32_16x16x32_bf16 v[28:31], v[132:135], v[180:183], v[28:31]
	v_mfma_f32_16x16x32_bf16 v[24:27], v[140:143], v[180:183], v[24:27]
	v_mfma_f32_16x16x32_bf16 v[12:15], v[132:135], v[200:203], v[12:15]
	v_mfma_f32_16x16x32_bf16 v[8:11], v[140:143], v[200:203], v[8:11]
	v_mfma_f32_16x16x32_bf16 v[52:55], v[204:207], v[154:157], v[52:55]
	v_mfma_f32_16x16x32_bf16 v[48:51], v[212:215], v[154:157], v[48:51]
	v_mfma_f32_16x16x32_bf16 v[36:39], v[204:207], v[168:171], v[36:39]
	v_mfma_f32_16x16x32_bf16 v[32:35], v[212:215], v[168:171], v[32:35]
	v_mfma_f32_16x16x32_bf16 v[20:23], v[204:207], v[176:179], v[20:23]
	v_mfma_f32_16x16x32_bf16 v[16:19], v[212:215], v[176:179], v[16:19]
	v_mfma_f32_16x16x32_bf16 v[4:7], v[204:207], v[196:199], v[4:7]
	v_mfma_f32_16x16x32_bf16 v[0:3], v[212:215], v[196:199], v[0:3]
	v_mfma_f32_16x16x32_bf16 v[52:55], v[208:211], v[164:167], v[52:55]
	v_mfma_f32_16x16x32_bf16 v[48:51], v[216:219], v[164:167], v[48:51]
	v_mfma_f32_16x16x32_bf16 v[36:39], v[208:211], v[172:175], v[36:39]
	v_mfma_f32_16x16x32_bf16 v[32:35], v[216:219], v[172:175], v[32:35]
	v_mfma_f32_16x16x32_bf16 v[20:23], v[208:211], v[180:183], v[20:23]
	v_mfma_f32_16x16x32_bf16 v[16:19], v[216:219], v[180:183], v[16:19]
	v_mfma_f32_16x16x32_bf16 v[4:7], v[208:211], v[200:203], v[4:7]
	v_mfma_f32_16x16x32_bf16 v[0:3], v[216:219], v[200:203], v[0:3]
	s_setprio 0
	s_add_i32 s57, s57, 2
	s_add_u32 s12, s12, 0x100
	s_addc_u32 s13, s13, 0
	s_add_u32 s53, s53, 0x100
	s_addc_u32 s56, s56, 0
	s_cmp_gt_u32 s57, 29
	s_barrier
	s_cbranch_scc0 .LBB0_803
	s_lshl_b32 s3, s44, 8
	s_add_i32 s4, s3, s35
	v_add_u32_e32 v156, s3, v160
	s_min_i32 s3, s4, 0x4000
	v_add_u32_e32 v128, s35, v156
	s_ashr_i32 s12, s3, 11
	v_ashrrev_i32_e32 v129, 31, v128
	s_ashr_i32 s13, s12, 31
	v_lshl_add_u64 v[128:129], v[128:129], 2, s[48:49]
	s_lshl_b64 s[12:13], s[12:13], 15
	global_load_dword v167, v[128:129], off
	global_load_dword v170, v[128:129], off offset:64
	global_load_dword v171, v[128:129], off offset:128
	global_load_dword v172, v[128:129], off offset:192
	global_load_dword v173, v[128:129], off offset:512
	global_load_dword v166, v[128:129], off offset:576
	global_load_dword v165, v[128:129], off offset:640
	v_lshl_or_b32 v154, s41, 8, v162
	s_add_u32 s12, s37, s12
	s_addc_u32 s13, s6, s13
	v_ashrrev_i32_e32 v155, 31, v154
	global_load_dword v164, v[128:129], off offset:704
	v_lshl_add_u64 v[128:129], v[154:155], 2, s[12:13]
	global_load_dwordx4 v[140:143], v[128:129], off
	global_load_dwordx4 v[136:139], v[128:129], off offset:16
	global_load_dwordx4 v[132:135], v[128:129], off offset:512
	s_nop 0
	global_load_dwordx4 v[128:131], v[128:129], off offset:528
	v_ashrrev_i32_e32 v157, 31, v156
	v_lshlrev_b64 v[158:159], 1, v[154:155]
	v_lshlrev_b64 v[154:155], 14, v[156:157]
	v_lshl_add_u64 v[154:155], s[54:55], 0, v[154:155]
	v_lshl_add_u64 v[154:155], v[154:155], 0, v[158:159]
	v_or_b32_e32 v168, 16, v156
	v_ashrrev_i32_e32 v169, 31, v168
	s_mov_b32 s3, 0x200000
	s_mov_b64 s[12:13], 0x200000
	s_mov_b32 s41, s2
	s_mov_b32 s44, s14
	s_mov_b64 s[20:21], s[28:29]
	s_waitcnt vmcnt(0)
	s_nop 0
	v_fmamk_f32 v157, v167, 0x3a000000, v229
	v_mul_f32_e32 v167, 0x4b800000, v157
	v_cmp_gt_f32_e32 vcc, s5, v157
	s_nop 1
	v_cndmask_b32_e32 v157, v157, v167, vcc
	v_rsq_f32_e32 v157, v157
	v_fmamk_f32 v167, v170, 0x3a000000, v229
	v_mul_f32_e32 v170, 0x45800000, v157
	v_cndmask_b32_e32 v170, v157, v170, vcc
	v_pk_fma_f32 v[124:125], v[124:125], v[170:171], v[140:141] op_sel_hi:[1,0,1]
	v_pk_fma_f32 v[112:113], v[112:113], v[170:171], v[128:129] op_sel_hi:[1,0,1]
	v_pk_fma_f32 v[126:127], v[126:127], v[170:171], v[142:143] op_sel_hi:[1,0,1]
	v_pk_fma_f32 v[122:123], v[122:123], v[170:171], v[138:139] op_sel_hi:[1,0,1]
	v_pk_fma_f32 v[120:121], v[120:121], v[170:171], v[136:137] op_sel_hi:[1,0,1]
	v_pk_fma_f32 v[116:117], v[116:117], v[170:171], v[132:133] op_sel_hi:[1,0,1]
	v_pk_fma_f32 v[114:115], v[114:115], v[170:171], v[130:131] op_sel_hi:[1,0,1]
	v_max_f32_e32 v124, 0, v124
	v_max_f32_e32 v125, 0, v125
	v_max_f32_e32 v112, 0, v112
	v_pk_fma_f32 v[118:119], v[118:119], v[170:171], v[134:135] op_sel_hi:[1,0,1]
	v_max_f32_e32 v120, 0, v120
	v_max_f32_e32 v121, 0, v121
	v_max_f32_e32 v126, 0, v126
	v_max_f32_e32 v122, 0, v122
	v_max_f32_e32 v127, 0, v127
	v_max_f32_e32 v123, 0, v123
	v_max_f32_e32 v116, 0, v116
	v_max_f32_e32 v117, 0, v117
	v_max_f32_e32 v113, 0, v113
	v_max_f32_e32 v114, 0, v114
	v_max_f32_e32 v115, 0, v115
	v_mul_f32_e32 v124, v124, v124
	v_mul_f32_e32 v125, v125, v125
	v_mul_f32_e32 v157, v112, v112
	v_cvt_pk_bf16_f32 v112, v124, v125
	v_mul_f32_e32 v174, 0x4b800000, v167
	v_max_f32_e32 v118, 0, v118
	v_max_f32_e32 v119, 0, v119
	v_mul_f32_e32 v120, v120, v120
	v_mul_f32_e32 v121, v121, v121
	v_mul_f32_e32 v126, v126, v126
	v_mul_f32_e32 v122, v122, v122
	v_mul_f32_e32 v127, v127, v127
	v_mul_f32_e32 v123, v123, v123
	v_mul_f32_e32 v116, v116, v116
	v_mul_f32_e32 v117, v117, v117
	v_mul_f32_e32 v170, v113, v113
	v_mul_f32_e32 v175, v114, v114
	v_mul_f32_e32 v176, v115, v115
	v_cvt_pk_bf16_f32 v113, v126, v127
	v_cvt_pk_bf16_f32 v114, v120, v121
	v_cvt_pk_bf16_f32 v115, v122, v123
	global_store_dwordx4 v[154:155], v[112:115], off
	v_cmp_gt_f32_e32 vcc, s5, v167
	v_mul_f32_e32 v118, v118, v118
	v_cvt_pk_bf16_f32 v112, v116, v117
	v_mul_f32_e32 v119, v119, v119
	v_cvt_pk_bf16_f32 v113, v118, v119
	v_cvt_pk_bf16_f32 v114, v157, v170
	v_cvt_pk_bf16_f32 v115, v175, v176
	global_store_dwordx4 v[154:155], v[112:115], off offset:256
	s_nop 1
	v_cndmask_b32_e32 v112, v167, v174, vcc
	v_rsq_f32_e32 v114, v112
	v_lshlrev_b64 v[112:113], 14, v[168:169]
	v_lshl_add_u64 v[112:113], s[54:55], 0, v[112:113]
	v_lshl_add_u64 v[112:113], v[112:113], 0, v[158:159]
	v_mul_f32_e32 v115, 0x45800000, v114
	v_cndmask_b32_e32 v114, v114, v115, vcc
	v_pk_fma_f32 v[104:105], v[104:105], v[114:115], v[136:137] op_sel_hi:[1,0,1]
	v_pk_fma_f32 v[108:109], v[108:109], v[114:115], v[140:141] op_sel_hi:[1,0,1]
	v_pk_fma_f32 v[106:107], v[106:107], v[114:115], v[138:139] op_sel_hi:[1,0,1]
	v_max_f32_e32 v104, 0, v104
	v_pk_fma_f32 v[110:111], v[110:111], v[114:115], v[142:143] op_sel_hi:[1,0,1]
	v_mul_f32_e32 v115, v104, v104
	v_max_f32_e32 v104, 0, v109
	v_max_f32_e32 v105, 0, v105
	v_max_f32_e32 v106, 0, v106
	v_max_f32_e32 v108, 0, v108
	v_mul_f32_e32 v104, v104, v104
	v_mul_f32_e32 v109, v105, v105
	v_max_f32_e32 v105, 0, v110
	v_mul_f32_e32 v110, v106, v106
	v_max_f32_e32 v106, 0, v111
	v_max_f32_e32 v107, 0, v107
	v_pk_fma_f32 v[98:99], v[98:99], v[114:115], v[130:131] op_sel_hi:[1,0,1]
	v_pk_fma_f32 v[96:97], v[96:97], v[114:115], v[128:129] op_sel_hi:[1,0,1]
	v_mul_f32_e32 v108, v108, v108
	v_mul_f32_e32 v105, v105, v105
	v_mul_f32_e32 v106, v106, v106
	v_mul_f32_e32 v107, v107, v107
	v_cvt_pk_bf16_f32 v104, v108, v104
	v_pk_fma_f32 v[102:103], v[102:103], v[114:115], v[134:135] op_sel_hi:[1,0,1]
	v_pk_fma_f32 v[100:101], v[100:101], v[114:115], v[132:133] op_sel_hi:[1,0,1]
	v_max_f32_e32 v96, 0, v96
	v_max_f32_e32 v97, 0, v97
	v_max_f32_e32 v98, 0, v98
	v_cvt_pk_bf16_f32 v105, v105, v106
	v_cvt_pk_bf16_f32 v106, v115, v109
	v_cvt_pk_bf16_f32 v107, v110, v107
	global_store_dwordx4 v[112:113], v[104:107], off
	v_max_f32_e32 v100, 0, v100
	v_max_f32_e32 v99, 0, v99
	v_mul_f32_e32 v104, v96, v96
	v_max_f32_e32 v96, 0, v101
	v_mul_f32_e32 v101, v97, v97
	v_max_f32_e32 v97, 0, v102
	v_mul_f32_e32 v102, v98, v98
	v_max_f32_e32 v98, 0, v103
	v_mul_f32_e32 v96, v96, v96
	v_mul_f32_e32 v97, v97, v97
	v_mul_f32_e32 v98, v98, v98
	v_mul_f32_e32 v100, v100, v100
	v_mul_f32_e32 v99, v99, v99
	v_cvt_pk_bf16_f32 v96, v100, v96
	v_cvt_pk_bf16_f32 v97, v97, v98
	v_cvt_pk_bf16_f32 v98, v104, v101
	v_cvt_pk_bf16_f32 v99, v102, v99
	global_store_dwordx4 v[112:113], v[96:99], off offset:256
	s_nop 1
	v_fmamk_f32 v98, v171, 0x3a000000, v229
	v_mul_f32_e32 v99, 0x4b800000, v98
	v_cmp_gt_f32_e32 vcc, s5, v98
	v_or_b32_e32 v96, 32, v156
	v_ashrrev_i32_e32 v97, 31, v96
	v_cndmask_b32_e32 v98, v98, v99, vcc
	v_rsq_f32_e32 v98, v98
	v_lshlrev_b64 v[96:97], 14, v[96:97]
	v_lshl_add_u64 v[96:97], s[54:55], 0, v[96:97]
	v_lshl_add_u64 v[96:97], v[96:97], 0, v[158:159]
	v_mul_f32_e32 v99, 0x45800000, v98
	v_cndmask_b32_e32 v98, v98, v99, vcc
	v_pk_fma_f32 v[88:89], v[88:89], v[98:99], v[136:137] op_sel_hi:[1,0,1]
	v_pk_fma_f32 v[92:93], v[92:93], v[98:99], v[140:141] op_sel_hi:[1,0,1]
	v_pk_fma_f32 v[90:91], v[90:91], v[98:99], v[138:139] op_sel_hi:[1,0,1]
	v_max_f32_e32 v88, 0, v88
	v_pk_fma_f32 v[94:95], v[94:95], v[98:99], v[142:143] op_sel_hi:[1,0,1]
	v_mul_f32_e32 v99, v88, v88
	v_max_f32_e32 v88, 0, v93
	v_max_f32_e32 v89, 0, v89
	v_max_f32_e32 v90, 0, v90
	v_max_f32_e32 v92, 0, v92
	v_mul_f32_e32 v88, v88, v88
	v_mul_f32_e32 v93, v89, v89
	v_max_f32_e32 v89, 0, v94
	v_mul_f32_e32 v94, v90, v90
	v_max_f32_e32 v90, 0, v95
	v_max_f32_e32 v91, 0, v91
	v_pk_fma_f32 v[82:83], v[82:83], v[98:99], v[130:131] op_sel_hi:[1,0,1]
	v_pk_fma_f32 v[80:81], v[80:81], v[98:99], v[128:129] op_sel_hi:[1,0,1]
	v_mul_f32_e32 v92, v92, v92
	v_mul_f32_e32 v89, v89, v89
	v_mul_f32_e32 v90, v90, v90
	v_mul_f32_e32 v91, v91, v91
	v_cvt_pk_bf16_f32 v88, v92, v88
	v_pk_fma_f32 v[86:87], v[86:87], v[98:99], v[134:135] op_sel_hi:[1,0,1]
	v_pk_fma_f32 v[84:85], v[84:85], v[98:99], v[132:133] op_sel_hi:[1,0,1]
	v_max_f32_e32 v80, 0, v80
	v_max_f32_e32 v81, 0, v81
	v_max_f32_e32 v82, 0, v82
	v_cvt_pk_bf16_f32 v89, v89, v90
	v_cvt_pk_bf16_f32 v90, v99, v93
	v_cvt_pk_bf16_f32 v91, v94, v91
	global_store_dwordx4 v[96:97], v[88:91], off
	v_max_f32_e32 v84, 0, v84
	v_max_f32_e32 v83, 0, v83
	v_mul_f32_e32 v88, v80, v80
	v_max_f32_e32 v80, 0, v85
	v_mul_f32_e32 v85, v81, v81
	v_max_f32_e32 v81, 0, v86
	v_mul_f32_e32 v86, v82, v82
	v_max_f32_e32 v82, 0, v87
	v_mul_f32_e32 v80, v80, v80
	v_mul_f32_e32 v81, v81, v81
	v_mul_f32_e32 v82, v82, v82
	v_mul_f32_e32 v84, v84, v84
	v_mul_f32_e32 v83, v83, v83
	v_cvt_pk_bf16_f32 v80, v84, v80
	v_cvt_pk_bf16_f32 v81, v81, v82
	v_cvt_pk_bf16_f32 v82, v88, v85
	v_cvt_pk_bf16_f32 v83, v86, v83
	global_store_dwordx4 v[96:97], v[80:83], off offset:256
	s_nop 1
	v_fmamk_f32 v82, v172, 0x3a000000, v229
	v_mul_f32_e32 v83, 0x4b800000, v82
	v_cmp_gt_f32_e32 vcc, s5, v82
	v_or_b32_e32 v80, 48, v156
	v_ashrrev_i32_e32 v81, 31, v80
	v_cndmask_b32_e32 v82, v82, v83, vcc
	v_rsq_f32_e32 v82, v82
	v_lshlrev_b64 v[80:81], 14, v[80:81]
	v_lshl_add_u64 v[80:81], s[54:55], 0, v[80:81]
	v_lshl_add_u64 v[80:81], v[80:81], 0, v[158:159]
	v_mul_f32_e32 v83, 0x45800000, v82
	v_cndmask_b32_e32 v82, v82, v83, vcc
	v_pk_fma_f32 v[72:73], v[72:73], v[82:83], v[136:137] op_sel_hi:[1,0,1]
	v_pk_fma_f32 v[76:77], v[76:77], v[82:83], v[140:141] op_sel_hi:[1,0,1]
	v_pk_fma_f32 v[74:75], v[74:75], v[82:83], v[138:139] op_sel_hi:[1,0,1]
	v_max_f32_e32 v72, 0, v72
	v_pk_fma_f32 v[78:79], v[78:79], v[82:83], v[142:143] op_sel_hi:[1,0,1]
	v_mul_f32_e32 v83, v72, v72
	v_max_f32_e32 v72, 0, v77
	v_max_f32_e32 v73, 0, v73
	v_max_f32_e32 v74, 0, v74
	v_max_f32_e32 v76, 0, v76
	v_mul_f32_e32 v72, v72, v72
	v_mul_f32_e32 v77, v73, v73
	v_max_f32_e32 v73, 0, v78
	v_mul_f32_e32 v78, v74, v74
	v_max_f32_e32 v74, 0, v79
	v_max_f32_e32 v75, 0, v75
	v_pk_fma_f32 v[64:65], v[64:65], v[82:83], v[128:129] op_sel_hi:[1,0,1]
	v_mul_f32_e32 v76, v76, v76
	v_mul_f32_e32 v73, v73, v73
	v_mul_f32_e32 v74, v74, v74
	v_mul_f32_e32 v75, v75, v75
	v_cvt_pk_bf16_f32 v72, v76, v72
	v_pk_fma_f32 v[68:69], v[68:69], v[82:83], v[132:133] op_sel_hi:[1,0,1]
	v_pk_fma_f32 v[66:67], v[66:67], v[82:83], v[130:131] op_sel_hi:[1,0,1]
	v_max_f32_e32 v64, 0, v64
	v_cvt_pk_bf16_f32 v73, v73, v74
	v_cvt_pk_bf16_f32 v74, v83, v77
	v_cvt_pk_bf16_f32 v75, v78, v75
	global_store_dwordx4 v[80:81], v[72:75], off
	v_pk_fma_f32 v[70:71], v[70:71], v[82:83], v[134:135] op_sel_hi:[1,0,1]
	v_max_f32_e32 v68, 0, v68
	v_mul_f32_e32 v72, v64, v64
	v_max_f32_e32 v64, 0, v69
	v_max_f32_e32 v65, 0, v65
	v_max_f32_e32 v66, 0, v66
	v_mul_f32_e32 v68, v68, v68
	v_mul_f32_e32 v64, v64, v64
	v_mul_f32_e32 v69, v65, v65
	v_max_f32_e32 v65, 0, v70
	v_mul_f32_e32 v70, v66, v66
	v_max_f32_e32 v66, 0, v71
	v_mul_f32_e32 v65, v65, v65
	v_mul_f32_e32 v66, v66, v66
	v_cvt_pk_bf16_f32 v64, v68, v64
	v_fmamk_f32 v68, v173, 0x3a000000, v229
	v_cvt_pk_bf16_f32 v65, v65, v66
	v_cvt_pk_bf16_f32 v66, v72, v69
	v_mul_f32_e32 v69, 0x4b800000, v68
	v_cmp_gt_f32_e32 vcc, s5, v68
	v_max_f32_e32 v67, 0, v67
	v_mul_f32_e32 v67, v67, v67
	v_cndmask_b32_e32 v68, v68, v69, vcc
	v_rsq_f32_e32 v68, v68
	v_cvt_pk_bf16_f32 v67, v70, v67
	global_store_dwordx4 v[80:81], v[64:67], off offset:256
	s_nop 1
	v_mul_f32_e32 v66, 0x45800000, v68
	v_cndmask_b32_e32 v66, v68, v66, vcc
	v_pk_fma_f32 v[56:57], v[56:57], v[66:67], v[136:137] op_sel_hi:[1,0,1]
	v_pk_fma_f32 v[60:61], v[60:61], v[66:67], v[140:141] op_sel_hi:[1,0,1]
	v_pk_fma_f32 v[58:59], v[58:59], v[66:67], v[138:139] op_sel_hi:[1,0,1]
	v_max_f32_e32 v56, 0, v56
	v_pk_fma_f32 v[62:63], v[62:63], v[66:67], v[142:143] op_sel_hi:[1,0,1]
	v_max_f32_e32 v60, 0, v60
	v_mul_f32_e32 v67, v56, v56
	v_max_f32_e32 v56, 0, v61
	v_max_f32_e32 v57, 0, v57
	v_max_f32_e32 v58, 0, v58
	v_mul_f32_e32 v60, v60, v60
	v_mul_f32_e32 v56, v56, v56
	v_mul_f32_e32 v61, v57, v57
	v_max_f32_e32 v57, 0, v62
	v_mul_f32_e32 v62, v58, v58
	v_max_f32_e32 v58, 0, v63
	v_mul_f32_e32 v57, v57, v57
	v_max_f32_e32 v59, 0, v59
	v_mul_f32_e32 v58, v58, v58
	v_cvt_pk_bf16_f32 v56, v60, v56
	v_add_co_u32_e32 v60, vcc, s3, v154
	v_pk_fma_f32 v[48:49], v[48:49], v[66:67], v[128:129] op_sel_hi:[1,0,1]
	v_mul_f32_e32 v59, v59, v59
	v_cvt_pk_bf16_f32 v57, v57, v58
	v_cvt_pk_bf16_f32 v58, v67, v61
	v_addc_co_u32_e32 v61, vcc, 0, v155, vcc
	v_pk_fma_f32 v[52:53], v[52:53], v[66:67], v[132:133] op_sel_hi:[1,0,1]
	v_pk_fma_f32 v[50:51], v[50:51], v[66:67], v[130:131] op_sel_hi:[1,0,1]
	v_max_f32_e32 v48, 0, v48
	v_cvt_pk_bf16_f32 v59, v62, v59
	global_store_dwordx4 v[60:61], v[56:59], off
	v_pk_fma_f32 v[54:55], v[54:55], v[66:67], v[134:135] op_sel_hi:[1,0,1]
	v_max_f32_e32 v52, 0, v52
	v_mul_f32_e32 v56, v48, v48
	v_max_f32_e32 v48, 0, v53
	v_max_f32_e32 v49, 0, v49
	v_max_f32_e32 v50, 0, v50
	v_mul_f32_e32 v52, v52, v52
	v_mul_f32_e32 v48, v48, v48
	v_mul_f32_e32 v53, v49, v49
	v_max_f32_e32 v49, 0, v54
	v_mul_f32_e32 v54, v50, v50
	v_max_f32_e32 v50, 0, v55
	v_mul_f32_e32 v49, v49, v49
	v_mul_f32_e32 v50, v50, v50
	v_cvt_pk_bf16_f32 v48, v52, v48
	v_fmamk_f32 v52, v166, 0x3a000000, v229
	v_cvt_pk_bf16_f32 v49, v49, v50
	v_cvt_pk_bf16_f32 v50, v56, v53
	v_mul_f32_e32 v53, 0x4b800000, v52
	v_cmp_gt_f32_e32 vcc, s5, v52
	v_max_f32_e32 v51, 0, v51
	v_lshl_add_u64 v[64:65], v[154:155], 0, s[12:13]
	v_cndmask_b32_e32 v52, v52, v53, vcc
	v_rsq_f32_e32 v52, v52
	v_mul_f32_e32 v51, v51, v51
	v_cvt_pk_bf16_f32 v51, v54, v51
	global_store_dwordx4 v[64:65], v[48:51], off offset:256
	s_mov_b32 s3, 0x240000
	s_mov_b64 s[12:13], 0x240000
	v_mul_f32_e32 v50, 0x45800000, v52
	v_cndmask_b32_e32 v50, v52, v50, vcc
	v_pk_fma_f32 v[40:41], v[40:41], v[50:51], v[136:137] op_sel_hi:[1,0,1]
	v_pk_fma_f32 v[44:45], v[44:45], v[50:51], v[140:141] op_sel_hi:[1,0,1]
	v_pk_fma_f32 v[42:43], v[42:43], v[50:51], v[138:139] op_sel_hi:[1,0,1]
	v_max_f32_e32 v40, 0, v40
	v_pk_fma_f32 v[46:47], v[46:47], v[50:51], v[142:143] op_sel_hi:[1,0,1]
	v_max_f32_e32 v44, 0, v44
	v_mul_f32_e32 v51, v40, v40
	v_max_f32_e32 v40, 0, v45
	v_max_f32_e32 v41, 0, v41
	v_max_f32_e32 v42, 0, v42
	v_mul_f32_e32 v44, v44, v44
	v_mul_f32_e32 v40, v40, v40
	v_mul_f32_e32 v45, v41, v41
	v_max_f32_e32 v41, 0, v46
	v_mul_f32_e32 v46, v42, v42
	v_max_f32_e32 v42, 0, v47
	v_mul_f32_e32 v41, v41, v41
	v_max_f32_e32 v43, 0, v43
	v_mul_f32_e32 v42, v42, v42
	v_cvt_pk_bf16_f32 v40, v44, v40
	v_add_co_u32_e32 v44, vcc, s3, v154
	v_pk_fma_f32 v[32:33], v[32:33], v[50:51], v[128:129] op_sel_hi:[1,0,1]
	v_mul_f32_e32 v43, v43, v43
	v_cvt_pk_bf16_f32 v41, v41, v42
	v_cvt_pk_bf16_f32 v42, v51, v45
	v_addc_co_u32_e32 v45, vcc, 0, v155, vcc
	v_pk_fma_f32 v[36:37], v[36:37], v[50:51], v[132:133] op_sel_hi:[1,0,1]
	v_pk_fma_f32 v[34:35], v[34:35], v[50:51], v[130:131] op_sel_hi:[1,0,1]
	v_max_f32_e32 v32, 0, v32
	v_cvt_pk_bf16_f32 v43, v46, v43
	global_store_dwordx4 v[44:45], v[40:43], off
	v_pk_fma_f32 v[38:39], v[38:39], v[50:51], v[134:135] op_sel_hi:[1,0,1]
	v_max_f32_e32 v36, 0, v36
	v_mul_f32_e32 v40, v32, v32
	v_max_f32_e32 v32, 0, v37
	v_max_f32_e32 v33, 0, v33
	v_max_f32_e32 v34, 0, v34
	v_mul_f32_e32 v36, v36, v36
	v_mul_f32_e32 v32, v32, v32
	v_mul_f32_e32 v37, v33, v33
	v_max_f32_e32 v33, 0, v38
	v_mul_f32_e32 v38, v34, v34
	v_max_f32_e32 v34, 0, v39
	v_mul_f32_e32 v33, v33, v33
	v_mul_f32_e32 v34, v34, v34
	v_cvt_pk_bf16_f32 v32, v36, v32
	v_fmamk_f32 v36, v165, 0x3a000000, v229
	v_cvt_pk_bf16_f32 v33, v33, v34
	v_cvt_pk_bf16_f32 v34, v40, v37
	v_mul_f32_e32 v37, 0x4b800000, v36
	v_cmp_gt_f32_e32 vcc, s5, v36
	v_max_f32_e32 v35, 0, v35
	v_lshl_add_u64 v[48:49], v[154:155], 0, s[12:13]
	v_cndmask_b32_e32 v36, v36, v37, vcc
	v_rsq_f32_e32 v36, v36
	v_mul_f32_e32 v35, v35, v35
	v_cvt_pk_bf16_f32 v35, v38, v35
	global_store_dwordx4 v[48:49], v[32:35], off offset:256
	s_mov_b32 s3, 0x280000
	s_mov_b64 s[12:13], 0x280000
	v_mul_f32_e32 v34, 0x45800000, v36
	v_cndmask_b32_e32 v34, v36, v34, vcc
	v_pk_fma_f32 v[24:25], v[24:25], v[34:35], v[136:137] op_sel_hi:[1,0,1]
	v_pk_fma_f32 v[28:29], v[28:29], v[34:35], v[140:141] op_sel_hi:[1,0,1]
	v_pk_fma_f32 v[26:27], v[26:27], v[34:35], v[138:139] op_sel_hi:[1,0,1]
	v_max_f32_e32 v24, 0, v24
	v_pk_fma_f32 v[30:31], v[30:31], v[34:35], v[142:143] op_sel_hi:[1,0,1]
	v_max_f32_e32 v28, 0, v28
	v_mul_f32_e32 v35, v24, v24
	v_max_f32_e32 v24, 0, v29
	v_max_f32_e32 v25, 0, v25
	v_max_f32_e32 v26, 0, v26
	v_mul_f32_e32 v28, v28, v28
	v_mul_f32_e32 v24, v24, v24
	v_mul_f32_e32 v29, v25, v25
	v_max_f32_e32 v25, 0, v30
	v_mul_f32_e32 v30, v26, v26
	v_max_f32_e32 v26, 0, v31
	v_mul_f32_e32 v25, v25, v25
	v_max_f32_e32 v27, 0, v27
	v_mul_f32_e32 v26, v26, v26
	v_cvt_pk_bf16_f32 v24, v28, v24
	v_add_co_u32_e32 v28, vcc, s3, v154
	v_pk_fma_f32 v[16:17], v[16:17], v[34:35], v[128:129] op_sel_hi:[1,0,1]
	v_mul_f32_e32 v27, v27, v27
	v_cvt_pk_bf16_f32 v25, v25, v26
	v_cvt_pk_bf16_f32 v26, v35, v29
	v_addc_co_u32_e32 v29, vcc, 0, v155, vcc
	v_pk_fma_f32 v[20:21], v[20:21], v[34:35], v[132:133] op_sel_hi:[1,0,1]
	v_pk_fma_f32 v[18:19], v[18:19], v[34:35], v[130:131] op_sel_hi:[1,0,1]
	v_max_f32_e32 v16, 0, v16
	v_cvt_pk_bf16_f32 v27, v30, v27
	global_store_dwordx4 v[28:29], v[24:27], off
	v_pk_fma_f32 v[22:23], v[22:23], v[34:35], v[134:135] op_sel_hi:[1,0,1]
	v_max_f32_e32 v20, 0, v20
	v_mul_f32_e32 v24, v16, v16
	v_max_f32_e32 v16, 0, v21
	v_max_f32_e32 v17, 0, v17
	v_max_f32_e32 v18, 0, v18
	v_mul_f32_e32 v20, v20, v20
	v_mul_f32_e32 v16, v16, v16
	v_mul_f32_e32 v21, v17, v17
	v_max_f32_e32 v17, 0, v22
	v_mul_f32_e32 v22, v18, v18
	v_max_f32_e32 v18, 0, v23
	v_mul_f32_e32 v17, v17, v17
	v_mul_f32_e32 v18, v18, v18
	v_cvt_pk_bf16_f32 v16, v20, v16
	v_fmamk_f32 v20, v164, 0x3a000000, v229
	v_cvt_pk_bf16_f32 v17, v17, v18
	v_cvt_pk_bf16_f32 v18, v24, v21
	v_mul_f32_e32 v21, 0x4b800000, v20
	v_cmp_gt_f32_e32 vcc, s5, v20
	v_max_f32_e32 v19, 0, v19
	v_lshl_add_u64 v[32:33], v[154:155], 0, s[12:13]
	v_cndmask_b32_e32 v20, v20, v21, vcc
	v_rsq_f32_e32 v20, v20
	v_mul_f32_e32 v19, v19, v19
	v_cvt_pk_bf16_f32 v19, v22, v19
	global_store_dwordx4 v[32:33], v[16:19], off offset:256
	s_mov_b32 s3, 0x2c0000
	s_mov_b64 s[12:13], 0x2c0000
	v_mul_f32_e32 v18, 0x45800000, v20
	v_cndmask_b32_e32 v18, v20, v18, vcc
	v_pk_fma_f32 v[8:9], v[8:9], v[18:19], v[136:137] op_sel_hi:[1,0,1]
	v_pk_fma_f32 v[12:13], v[12:13], v[18:19], v[140:141] op_sel_hi:[1,0,1]
	v_pk_fma_f32 v[10:11], v[10:11], v[18:19], v[138:139] op_sel_hi:[1,0,1]
	v_max_f32_e32 v8, 0, v8
	v_pk_fma_f32 v[14:15], v[14:15], v[18:19], v[142:143] op_sel_hi:[1,0,1]
	v_max_f32_e32 v12, 0, v12
	v_mul_f32_e32 v19, v8, v8
	v_max_f32_e32 v8, 0, v13
	v_max_f32_e32 v9, 0, v9
	v_max_f32_e32 v10, 0, v10
	v_mul_f32_e32 v12, v12, v12
	v_mul_f32_e32 v8, v8, v8
	v_mul_f32_e32 v13, v9, v9
	v_max_f32_e32 v9, 0, v14
	v_mul_f32_e32 v14, v10, v10
	v_max_f32_e32 v10, 0, v15
	v_mul_f32_e32 v9, v9, v9
	v_max_f32_e32 v11, 0, v11
	v_mul_f32_e32 v10, v10, v10
	v_cvt_pk_bf16_f32 v8, v12, v8
	v_add_co_u32_e32 v12, vcc, s3, v154
	v_pk_fma_f32 v[2:3], v[2:3], v[18:19], v[130:131] op_sel_hi:[1,0,1]
	v_pk_fma_f32 v[0:1], v[0:1], v[18:19], v[128:129] op_sel_hi:[1,0,1]
	v_mul_f32_e32 v11, v11, v11
	v_cvt_pk_bf16_f32 v9, v9, v10
	v_cvt_pk_bf16_f32 v10, v19, v13
	v_addc_co_u32_e32 v13, vcc, 0, v155, vcc
	v_pk_fma_f32 v[6:7], v[6:7], v[18:19], v[134:135] op_sel_hi:[1,0,1]
	v_pk_fma_f32 v[4:5], v[4:5], v[18:19], v[132:133] op_sel_hi:[1,0,1]
	v_max_f32_e32 v0, 0, v0
	v_max_f32_e32 v1, 0, v1
	v_max_f32_e32 v2, 0, v2
	v_cvt_pk_bf16_f32 v11, v14, v11
	global_store_dwordx4 v[12:13], v[8:11], off
	v_max_f32_e32 v3, 0, v3
	v_lshl_add_u64 v[16:17], v[154:155], 0, s[12:13]
	v_mul_f32_e32 v8, v0, v0
	v_max_f32_e32 v0, 0, v5
	v_mul_f32_e32 v5, v1, v1
	v_max_f32_e32 v1, 0, v6
	v_mul_f32_e32 v6, v2, v2
	v_max_f32_e32 v2, 0, v7
	v_max_f32_e32 v4, 0, v4
	v_mul_f32_e32 v0, v0, v0
	v_mul_f32_e32 v1, v1, v1
	v_mul_f32_e32 v2, v2, v2
	v_mul_f32_e32 v3, v3, v3
	s_and_b64 vcc, exec, s[42:43]
	s_mov_b64 s[12:13], s[18:19]
	v_mul_f32_e32 v4, v4, v4
	v_cvt_pk_bf16_f32 v0, v4, v0
	v_cvt_pk_bf16_f32 v1, v1, v2
	v_cvt_pk_bf16_f32 v2, v8, v5
	v_cvt_pk_bf16_f32 v3, v6, v3
	global_store_dwordx4 v[16:17], v[0:3], off offset:256
	s_cbranch_vccz .LBB0_796
	s_waitcnt vmcnt(0)
	s_cmpk_gt_u32 s22, 0xff
	v_readlane_b32 s35, v252, 37
	s_cbranch_scc1 .LBB0_807
	s_barrier

.LBB0_889:
	s_add_i32 s58, 0, 0x10000
	v_add_u32_e32 v124, s58, v161
	ds_read_b128 v[104:107], v124
	ds_read_b128 v[108:111], v124 offset:1024
	ds_read_b128 v[116:119], v124 offset:2048
	ds_read_b128 v[124:127], v124 offset:3072
	ds_read_b128 v[152:155], v163
	ds_read_b128 v[156:159], v163 offset:1024
	ds_read_b128 v[164:167], v163 offset:2048
	ds_read_b128 v[168:171], v163 offset:3072
	ds_read_b128 v[172:175], v163 offset:4096
	ds_read_b128 v[176:179], v163 offset:5120
	ds_read_b128 v[180:183], v163 offset:6144
	ds_read_b128 v[196:199], v163 offset:7168
	s_add_u32 s4, s12, 0xffe00080
	s_addc_u32 s20, s13, -1
	s_cmpk_eq_i32 vcc_hi, 0x7c
	s_cselect_b32 s25, s29, s20
	s_cselect_b32 s24, s57, s4
	s_cselect_b32 s21, s19, vcc_lo
	s_cselect_b32 s20, s68, s69
	v_lshl_add_u64 v[200:201], s[12:13], 0, v[148:149]
	s_add_i32 m0, s22, 0xc000
	global_load_lds_dwordx4 v[200:201], off
	v_lshl_add_u64 v[200:201], s[12:13], 0, v[150:151]
	s_add_i32 m0, s22, 0xe000
	s_nop 0
	global_load_lds_dwordx4 v[200:201], off
	v_add_u32_e32 v212, 0x14000, v161
	ds_read_b128 v[200:203], v212
	ds_read_b128 v[204:207], v212 offset:1024
	ds_read_b128 v[208:211], v212 offset:2048
	ds_read_b128 v[212:215], v212 offset:3072
	s_waitcnt vmcnt(8)
	s_waitcnt lgkmcnt(0)
	s_barrier
	s_setprio 1
	v_mfma_f32_16x16x32_bf16 v[140:143], v[104:107], v[152:155], v[140:143]
	v_mfma_f32_16x16x32_bf16 v[136:139], v[116:119], v[152:155], v[136:139]
	v_mfma_f32_16x16x32_bf16 v[120:123], v[104:107], v[164:167], v[120:123]
	v_mfma_f32_16x16x32_bf16 v[112:115], v[116:119], v[164:167], v[112:115]
	v_mfma_f32_16x16x32_bf16 v[92:95], v[104:107], v[172:175], v[92:95]
	v_mfma_f32_16x16x32_bf16 v[88:91], v[116:119], v[172:175], v[88:91]
	v_mfma_f32_16x16x32_bf16 v[76:79], v[104:107], v[180:183], v[76:79]
	v_mfma_f32_16x16x32_bf16 v[72:75], v[116:119], v[180:183], v[72:75]
	v_mfma_f32_16x16x32_bf16 v[140:143], v[108:111], v[156:159], v[140:143]
	v_mfma_f32_16x16x32_bf16 v[136:139], v[124:127], v[156:159], v[136:139]
	v_mfma_f32_16x16x32_bf16 v[120:123], v[108:111], v[168:171], v[120:123]
	v_mfma_f32_16x16x32_bf16 v[112:115], v[124:127], v[168:171], v[112:115]
	v_mfma_f32_16x16x32_bf16 v[92:95], v[108:111], v[176:179], v[92:95]
	v_mfma_f32_16x16x32_bf16 v[88:91], v[124:127], v[176:179], v[88:91]
	v_mfma_f32_16x16x32_bf16 v[76:79], v[108:111], v[196:199], v[76:79]
	v_mfma_f32_16x16x32_bf16 v[72:75], v[124:127], v[196:199], v[72:75]
	v_mfma_f32_16x16x32_bf16 v[132:135], v[200:203], v[152:155], v[132:135]
	v_mfma_f32_16x16x32_bf16 v[128:131], v[208:211], v[152:155], v[128:131]
	v_mfma_f32_16x16x32_bf16 v[100:103], v[200:203], v[164:167], v[100:103]
	v_mfma_f32_16x16x32_bf16 v[96:99], v[208:211], v[164:167], v[96:99]
	v_mfma_f32_16x16x32_bf16 v[84:87], v[200:203], v[172:175], v[84:87]
	v_mfma_f32_16x16x32_bf16 v[80:83], v[208:211], v[172:175], v[80:83]
	v_mfma_f32_16x16x32_bf16 v[68:71], v[200:203], v[180:183], v[68:71]
	v_mfma_f32_16x16x32_bf16 v[64:67], v[208:211], v[180:183], v[64:67]
	v_mfma_f32_16x16x32_bf16 v[132:135], v[204:207], v[156:159], v[132:135]
	v_mfma_f32_16x16x32_bf16 v[128:131], v[212:215], v[156:159], v[128:131]
	v_mfma_f32_16x16x32_bf16 v[100:103], v[204:207], v[168:171], v[100:103]
	v_mfma_f32_16x16x32_bf16 v[96:99], v[212:215], v[168:171], v[96:99]
	v_mfma_f32_16x16x32_bf16 v[84:87], v[204:207], v[176:179], v[84:87]
	v_mfma_f32_16x16x32_bf16 v[80:83], v[212:215], v[176:179], v[80:83]
	v_mfma_f32_16x16x32_bf16 v[68:71], v[204:207], v[196:199], v[68:71]
	v_mfma_f32_16x16x32_bf16 v[64:67], v[212:215], v[196:199], v[64:67]
	s_setprio 0
	s_barrier
	ds_read_b128 v[152:155], v163 offset:16384
	ds_read_b128 v[156:159], v163 offset:17408
	ds_read_b128 v[164:167], v163 offset:18432
	ds_read_b128 v[168:171], v163 offset:19456
	ds_read_b128 v[172:175], v163 offset:20480
	ds_read_b128 v[176:179], v163 offset:21504
	ds_read_b128 v[180:183], v163 offset:22528
	ds_read_b128 v[196:199], v163 offset:23552
	s_add_i32 s4, 0, 0x14000
	s_add_i32 s58, s58, s27
	v_lshl_add_u64 v[216:217], s[20:21], 0, v[146:147]
	s_mov_b32 m0, s58
	global_load_lds_dwordx4 v[216:217], off
	v_lshl_add_u64 v[218:219], s[20:21], 0, v[144:145]
	s_add_i32 m0, s58, 0x2000
	s_nop 0
	global_load_lds_dwordx4 v[218:219], off
	s_mov_b32 m0, s22
	v_lshl_add_u64 v[220:221], s[24:25], 0, v[146:147]
	global_load_lds_dwordx4 v[220:221], off
	v_lshl_add_u64 v[222:223], s[24:25], 0, v[144:145]
	s_mov_b32 m0, s23
	s_nop 0
	global_load_lds_dwordx4 v[222:223], off
	s_waitcnt vmcnt(6)
	s_waitcnt lgkmcnt(0)
	s_barrier
	s_setprio 1
	v_mfma_f32_16x16x32_bf16 v[60:63], v[104:107], v[152:155], v[60:63]
	v_mfma_f32_16x16x32_bf16 v[56:59], v[116:119], v[152:155], v[56:59]
	v_mfma_f32_16x16x32_bf16 v[44:47], v[104:107], v[164:167], v[44:47]
	v_mfma_f32_16x16x32_bf16 v[40:43], v[116:119], v[164:167], v[40:43]
	v_mfma_f32_16x16x32_bf16 v[28:31], v[104:107], v[172:175], v[28:31]
	v_mfma_f32_16x16x32_bf16 v[24:27], v[116:119], v[172:175], v[24:27]
	v_mfma_f32_16x16x32_bf16 v[12:15], v[104:107], v[180:183], v[12:15]
	v_mfma_f32_16x16x32_bf16 v[8:11], v[116:119], v[180:183], v[8:11]
	v_mfma_f32_16x16x32_bf16 v[60:63], v[108:111], v[156:159], v[60:63]
	v_mfma_f32_16x16x32_bf16 v[56:59], v[124:127], v[156:159], v[56:59]
	v_mfma_f32_16x16x32_bf16 v[44:47], v[108:111], v[168:171], v[44:47]
	v_mfma_f32_16x16x32_bf16 v[40:43], v[124:127], v[168:171], v[40:43]
	v_mfma_f32_16x16x32_bf16 v[28:31], v[108:111], v[176:179], v[28:31]
	v_mfma_f32_16x16x32_bf16 v[24:27], v[124:127], v[176:179], v[24:27]
	v_mfma_f32_16x16x32_bf16 v[12:15], v[108:111], v[196:199], v[12:15]
	v_mfma_f32_16x16x32_bf16 v[8:11], v[124:127], v[196:199], v[8:11]
	v_mfma_f32_16x16x32_bf16 v[52:55], v[200:203], v[152:155], v[52:55]
	v_mfma_f32_16x16x32_bf16 v[48:51], v[208:211], v[152:155], v[48:51]
	v_mfma_f32_16x16x32_bf16 v[36:39], v[200:203], v[164:167], v[36:39]
	v_mfma_f32_16x16x32_bf16 v[32:35], v[208:211], v[164:167], v[32:35]
	v_mfma_f32_16x16x32_bf16 v[20:23], v[200:203], v[172:175], v[20:23]
	v_mfma_f32_16x16x32_bf16 v[16:19], v[208:211], v[172:175], v[16:19]
	v_mfma_f32_16x16x32_bf16 v[4:7], v[200:203], v[180:183], v[4:7]
	v_mfma_f32_16x16x32_bf16 v[0:3], v[208:211], v[180:183], v[0:3]
	v_mfma_f32_16x16x32_bf16 v[52:55], v[204:207], v[156:159], v[52:55]
	v_mfma_f32_16x16x32_bf16 v[48:51], v[212:215], v[156:159], v[48:51]
	v_mfma_f32_16x16x32_bf16 v[36:39], v[204:207], v[168:171], v[36:39]
	v_mfma_f32_16x16x32_bf16 v[32:35], v[212:215], v[168:171], v[32:35]
	v_mfma_f32_16x16x32_bf16 v[20:23], v[204:207], v[176:179], v[20:23]
	v_mfma_f32_16x16x32_bf16 v[16:19], v[212:215], v[176:179], v[16:19]
	v_mfma_f32_16x16x32_bf16 v[4:7], v[204:207], v[196:199], v[4:7]
	v_mfma_f32_16x16x32_bf16 v[0:3], v[212:215], v[196:199], v[0:3]
	s_setprio 0
	s_barrier
	s_add_u32 s58, s20, 0x200000
	s_addc_u32 s59, s21, 0
	s_add_i32 s4, s4, s27
	v_lshl_add_u64 v[104:105], s[58:59], 0, v[146:147]
	s_mov_b32 m0, s4
	s_nop 0
	global_load_lds_dwordx4 v[104:105], off
	v_lshl_add_u64 v[104:105], s[58:59], 0, v[144:145]
	s_add_i32 m0, s4, 0x2000
	s_nop 0
	global_load_lds_dwordx4 v[104:105], off
	s_add_i32 s4, 0, 0x18000
	v_add_u32_e32 v124, s4, v161
	ds_read_b128 v[104:107], v124
	ds_read_b128 v[108:111], v124 offset:1024
	ds_read_b128 v[116:119], v124 offset:2048
	ds_read_b128 v[124:127], v124 offset:3072
	ds_read_b128 v[152:155], v163 offset:32768
	ds_read_b128 v[156:159], v163 offset:33792
	ds_read_b128 v[164:167], v163 offset:34816
	ds_read_b128 v[168:171], v163 offset:35840
	ds_read_b128 v[172:175], v163 offset:36864
	ds_read_b128 v[176:179], v163 offset:37888
	ds_read_b128 v[180:183], v163 offset:38912
	ds_read_b128 v[196:199], v163 offset:39936
	s_add_u32 s24, s24, 0x200000
	s_addc_u32 s25, s25, 0
	s_mov_b32 m0, s30
	v_lshl_add_u64 v[200:201], s[24:25], 0, v[146:147]
	global_load_lds_dwordx4 v[200:201], off
	v_lshl_add_u64 v[200:201], s[24:25], 0, v[144:145]
	s_mov_b32 m0, s31
	s_nop 0
	global_load_lds_dwordx4 v[200:201], off
	v_add_u32_e32 v212, 0x1c000, v161
	ds_read_b128 v[200:203], v212
	ds_read_b128 v[204:207], v212 offset:1024
	ds_read_b128 v[208:211], v212 offset:2048
	ds_read_b128 v[212:215], v212 offset:3072
	s_waitcnt vmcnt(8)
	s_waitcnt lgkmcnt(0)
	s_barrier
	s_setprio 1
	v_mfma_f32_16x16x32_bf16 v[140:143], v[104:107], v[152:155], v[140:143]
	v_mfma_f32_16x16x32_bf16 v[136:139], v[116:119], v[152:155], v[136:139]
	v_mfma_f32_16x16x32_bf16 v[120:123], v[104:107], v[164:167], v[120:123]
	v_mfma_f32_16x16x32_bf16 v[112:115], v[116:119], v[164:167], v[112:115]
	v_mfma_f32_16x16x32_bf16 v[92:95], v[104:107], v[172:175], v[92:95]
	v_mfma_f32_16x16x32_bf16 v[88:91], v[116:119], v[172:175], v[88:91]
	v_mfma_f32_16x16x32_bf16 v[76:79], v[104:107], v[180:183], v[76:79]
	v_mfma_f32_16x16x32_bf16 v[72:75], v[116:119], v[180:183], v[72:75]
	v_mfma_f32_16x16x32_bf16 v[140:143], v[108:111], v[156:159], v[140:143]
	v_mfma_f32_16x16x32_bf16 v[136:139], v[124:127], v[156:159], v[136:139]
	v_mfma_f32_16x16x32_bf16 v[120:123], v[108:111], v[168:171], v[120:123]
	v_mfma_f32_16x16x32_bf16 v[112:115], v[124:127], v[168:171], v[112:115]
	v_mfma_f32_16x16x32_bf16 v[92:95], v[108:111], v[176:179], v[92:95]
	v_mfma_f32_16x16x32_bf16 v[88:91], v[124:127], v[176:179], v[88:91]
	v_mfma_f32_16x16x32_bf16 v[76:79], v[108:111], v[196:199], v[76:79]
	v_mfma_f32_16x16x32_bf16 v[72:75], v[124:127], v[196:199], v[72:75]
	v_mfma_f32_16x16x32_bf16 v[132:135], v[200:203], v[152:155], v[132:135]
	v_mfma_f32_16x16x32_bf16 v[128:131], v[208:211], v[152:155], v[128:131]
	v_mfma_f32_16x16x32_bf16 v[100:103], v[200:203], v[164:167], v[100:103]
	v_mfma_f32_16x16x32_bf16 v[96:99], v[208:211], v[164:167], v[96:99]
	v_mfma_f32_16x16x32_bf16 v[84:87], v[200:203], v[172:175], v[84:87]
	v_mfma_f32_16x16x32_bf16 v[80:83], v[208:211], v[172:175], v[80:83]
	v_mfma_f32_16x16x32_bf16 v[68:71], v[200:203], v[180:183], v[68:71]
	v_mfma_f32_16x16x32_bf16 v[64:67], v[208:211], v[180:183], v[64:67]
	v_mfma_f32_16x16x32_bf16 v[132:135], v[204:207], v[156:159], v[132:135]
	v_mfma_f32_16x16x32_bf16 v[128:131], v[212:215], v[156:159], v[128:131]
	v_mfma_f32_16x16x32_bf16 v[100:103], v[204:207], v[168:171], v[100:103]
	v_mfma_f32_16x16x32_bf16 v[96:99], v[212:215], v[168:171], v[96:99]
	v_mfma_f32_16x16x32_bf16 v[84:87], v[204:207], v[176:179], v[84:87]
	v_mfma_f32_16x16x32_bf16 v[80:83], v[212:215], v[176:179], v[80:83]
	v_mfma_f32_16x16x32_bf16 v[68:71], v[204:207], v[196:199], v[68:71]
	v_mfma_f32_16x16x32_bf16 v[64:67], v[212:215], v[196:199], v[64:67]
	s_setprio 0
	s_barrier
	ds_read_b128 v[152:155], v163 offset:49152
	ds_read_b128 v[156:159], v163 offset:50176
	ds_read_b128 v[164:167], v163 offset:51200
	ds_read_b128 v[168:171], v163 offset:52224
	ds_read_b128 v[172:175], v163 offset:53248
	ds_read_b128 v[176:179], v163 offset:54272
	ds_read_b128 v[180:183], v163 offset:55296
	ds_read_b128 v[196:199], v163 offset:56320
	s_add_i32 s24, 0, 0x1c000
	s_add_i32 s4, s4, s27
	v_lshl_add_u64 v[216:217], v[216:217], 0, s[0:1]
	s_mov_b32 m0, s4
	global_load_lds_dwordx4 v[216:217], off
	v_lshl_add_u64 v[216:217], v[218:219], 0, s[0:1]
	s_add_i32 m0, s4, 0x2000
	s_nop 0
	global_load_lds_dwordx4 v[216:217], off
	s_mov_b32 m0, s16
	v_lshl_add_u64 v[216:217], v[220:221], 0, s[0:1]
	global_load_lds_dwordx4 v[216:217], off
	v_lshl_add_u64 v[216:217], v[222:223], 0, s[0:1]
	s_mov_b32 m0, s17
	s_nop 0
	global_load_lds_dwordx4 v[216:217], off
	s_add_u32 s20, s20, 0x200080
	s_addc_u32 s21, s21, 0
	s_add_i32 s4, s24, s27
	v_lshl_add_u64 v[216:217], s[20:21], 0, v[146:147]
	s_mov_b32 m0, s4
	s_nop 0
	global_load_lds_dwordx4 v[216:217], off
	v_lshl_add_u64 v[216:217], s[20:21], 0, v[144:145]
	s_add_i32 m0, s4, 0x2000
	s_nop 0
	global_load_lds_dwordx4 v[216:217], off
	s_waitcnt vmcnt(8)
	s_waitcnt lgkmcnt(0)
	s_barrier
	s_setprio 1
	v_mfma_f32_16x16x32_bf16 v[60:63], v[104:107], v[152:155], v[60:63]
	v_mfma_f32_16x16x32_bf16 v[56:59], v[116:119], v[152:155], v[56:59]
	v_mfma_f32_16x16x32_bf16 v[44:47], v[104:107], v[164:167], v[44:47]
	v_mfma_f32_16x16x32_bf16 v[40:43], v[116:119], v[164:167], v[40:43]
	v_mfma_f32_16x16x32_bf16 v[28:31], v[104:107], v[172:175], v[28:31]
	v_mfma_f32_16x16x32_bf16 v[24:27], v[116:119], v[172:175], v[24:27]
	v_mfma_f32_16x16x32_bf16 v[12:15], v[104:107], v[180:183], v[12:15]
	v_mfma_f32_16x16x32_bf16 v[8:11], v[116:119], v[180:183], v[8:11]
	v_mfma_f32_16x16x32_bf16 v[60:63], v[108:111], v[156:159], v[60:63]
	v_mfma_f32_16x16x32_bf16 v[56:59], v[124:127], v[156:159], v[56:59]
	v_mfma_f32_16x16x32_bf16 v[44:47], v[108:111], v[168:171], v[44:47]
	v_mfma_f32_16x16x32_bf16 v[40:43], v[124:127], v[168:171], v[40:43]
	v_mfma_f32_16x16x32_bf16 v[28:31], v[108:111], v[176:179], v[28:31]
	v_mfma_f32_16x16x32_bf16 v[24:27], v[124:127], v[176:179], v[24:27]
	v_mfma_f32_16x16x32_bf16 v[12:15], v[108:111], v[196:199], v[12:15]
	v_mfma_f32_16x16x32_bf16 v[8:11], v[124:127], v[196:199], v[8:11]
	v_mfma_f32_16x16x32_bf16 v[52:55], v[200:203], v[152:155], v[52:55]
	v_mfma_f32_16x16x32_bf16 v[48:51], v[208:211], v[152:155], v[48:51]
	v_mfma_f32_16x16x32_bf16 v[36:39], v[200:203], v[164:167], v[36:39]
	v_mfma_f32_16x16x32_bf16 v[32:35], v[208:211], v[164:167], v[32:35]
	v_mfma_f32_16x16x32_bf16 v[20:23], v[200:203], v[172:175], v[20:23]
	v_mfma_f32_16x16x32_bf16 v[16:19], v[208:211], v[172:175], v[16:19]
	v_mfma_f32_16x16x32_bf16 v[4:7], v[200:203], v[180:183], v[4:7]
	v_mfma_f32_16x16x32_bf16 v[0:3], v[208:211], v[180:183], v[0:3]
	v_mfma_f32_16x16x32_bf16 v[52:55], v[204:207], v[156:159], v[52:55]
	v_mfma_f32_16x16x32_bf16 v[48:51], v[212:215], v[156:159], v[48:51]
	v_mfma_f32_16x16x32_bf16 v[36:39], v[204:207], v[168:171], v[36:39]
	v_mfma_f32_16x16x32_bf16 v[32:35], v[212:215], v[168:171], v[32:35]
	v_mfma_f32_16x16x32_bf16 v[20:23], v[204:207], v[176:179], v[20:23]
	v_mfma_f32_16x16x32_bf16 v[16:19], v[212:215], v[176:179], v[16:19]
	v_mfma_f32_16x16x32_bf16 v[4:7], v[204:207], v[196:199], v[4:7]
	v_mfma_f32_16x16x32_bf16 v[0:3], v[212:215], v[196:199], v[0:3]
	s_setprio 0
	s_add_i32 vcc_hi, vcc_hi, 2
	s_add_u32 s12, s12, 0x100
	s_addc_u32 s13, s13, 0
	s_add_u32 s69, s69, 0x100
	s_addc_u32 vcc_lo, vcc_lo, 0
	s_cmpk_gt_u32 vcc_hi, 0x7d
	s_barrier
	s_cbranch_scc0 .LBB0_889
	s_lshl_b32 s4, s56, 8
	s_add_i32 s4, s4, s35
	s_min_i32 s12, s4, 0x4000
	s_ashr_i32 s12, s12, 11
	s_mul_hi_i32 s13, s12, 0xc000
	s_mul_i32 s12, s12, 0xc000
	v_lshl_or_b32 v154, s53, 8, v162
	s_add_u32 s12, s8, s12
	s_addc_u32 s13, s9, s13
	v_ashrrev_i32_e32 v155, 31, v154
	v_lshl_add_u64 v[104:105], v[154:155], 2, s[12:13]
	global_load_dwordx4 v[124:127], v[104:105], off
	global_load_dwordx4 v[116:119], v[104:105], off offset:64
	global_load_dwordx4 v[108:111], v[104:105], off offset:512
	s_nop 0
	global_load_dwordx4 v[104:107], v[104:105], off offset:576
	v_add_u32_e32 v152, s4, v160
	s_movk_i32 s4, 0x3fff
	v_cmp_lt_i32_e32 vcc, s4, v152
	s_and_saveexec_b64 s[12:13], vcc
	s_xor_b64 s[12:13], exec, s[12:13]
	v_add_u32_e32 v186, 0xffffc000, v152
	v_lshlrev_b64 v[156:157], 13, v[186:187]
	v_mov_b32_e32 v153, v187
	v_lshl_add_u64 v[158:159], s[10:11], 0, v[156:157]
	v_lshlrev_b64 v[156:157], 13, v[152:153]
	s_andn2_saveexec_b64 s[12:13], s[12:13]
	v_ashrrev_i32_e32 v153, 31, v152
	v_lshlrev_b64 v[156:157], 13, v[152:153]
	v_lshl_add_u64 v[158:159], s[66:67], 0, v[156:157]
	s_or_b64 exec, exec, s[12:13]
	v_lshlrev_b64 v[154:155], 2, v[154:155]
	v_lshl_add_u64 v[158:159], v[158:159], 0, v[154:155]
	global_load_dwordx4 v[164:167], v[158:159], off
	v_lshl_add_u64 v[156:157], s[66:67], 0, v[156:157]
	v_lshl_add_u64 v[156:157], v[156:157], 0, v[154:155]
	s_movk_i32 s4, 0x3fef
	v_cmp_lt_i32_e32 vcc, s4, v152
	s_waitcnt vmcnt(0)
	v_pk_fma_f32 v[142:143], v[142:143], v[126:127], v[166:167]
	v_pk_fma_f32 v[140:141], v[140:141], v[124:125], v[164:165]
	global_store_dwordx4 v[156:157], v[140:143], off
	global_load_dwordx4 v[140:143], v[158:159], off offset:64
	s_waitcnt vmcnt(0)
	v_pk_fma_f32 v[138:139], v[138:139], v[118:119], v[142:143]
	v_pk_fma_f32 v[136:137], v[136:137], v[116:117], v[140:141]
	global_store_dwordx4 v[156:157], v[136:139], off offset:64
	global_load_dwordx4 v[136:139], v[158:159], off offset:512
	s_waitcnt vmcnt(0)
	v_pk_fma_f32 v[134:135], v[134:135], v[110:111], v[138:139]
	v_pk_fma_f32 v[132:133], v[132:133], v[108:109], v[136:137]
	global_store_dwordx4 v[156:157], v[132:135], off offset:512
	global_load_dwordx4 v[134:137], v[158:159], off offset:576
	s_waitcnt vmcnt(0)
	v_pk_fma_f32 v[130:131], v[130:131], v[106:107], v[136:137]
	v_or_b32_e32 v132, 16, v152
	v_pk_fma_f32 v[128:129], v[128:129], v[104:105], v[134:135]
	global_store_dwordx4 v[156:157], v[128:131], off offset:576
	s_and_saveexec_b64 s[12:13], vcc
	s_xor_b64 s[12:13], exec, s[12:13]
	v_add_u32_e32 v186, 0xffffc010, v152
	v_lshlrev_b64 v[128:129], 13, v[186:187]
	v_mov_b32_e32 v133, v187
	v_lshl_add_u64 v[130:131], s[10:11], 0, v[128:129]
	v_lshlrev_b64 v[128:129], 13, v[132:133]
	s_andn2_saveexec_b64 s[12:13], s[12:13]
	v_ashrrev_i32_e32 v133, 31, v132
	v_lshlrev_b64 v[128:129], 13, v[132:133]
	v_lshl_add_u64 v[130:131], s[66:67], 0, v[128:129]
	s_or_b64 exec, exec, s[12:13]
	v_lshl_add_u64 v[134:135], v[130:131], 0, v[154:155]
	global_load_dwordx4 v[130:133], v[134:135], off
	v_lshl_add_u64 v[128:129], s[66:67], 0, v[128:129]
	v_lshl_add_u64 v[128:129], v[128:129], 0, v[154:155]
	s_movk_i32 s4, 0x3fdf
	v_cmp_lt_i32_e32 vcc, s4, v152
	s_waitcnt vmcnt(0)
	v_pk_fma_f32 v[122:123], v[122:123], v[126:127], v[132:133]
	v_pk_fma_f32 v[120:121], v[120:121], v[124:125], v[130:131]
	global_store_dwordx4 v[128:129], v[120:123], off
	global_load_dwordx4 v[120:123], v[134:135], off offset:64
	s_waitcnt vmcnt(0)
	v_pk_fma_f32 v[114:115], v[114:115], v[118:119], v[122:123]
	v_pk_fma_f32 v[112:113], v[112:113], v[116:117], v[120:121]
	global_store_dwordx4 v[128:129], v[112:115], off offset:64
	global_load_dwordx4 v[112:115], v[134:135], off offset:512
	s_waitcnt vmcnt(0)
	v_pk_fma_f32 v[102:103], v[102:103], v[110:111], v[114:115]
	v_pk_fma_f32 v[100:101], v[100:101], v[108:109], v[112:113]
	global_store_dwordx4 v[128:129], v[100:103], off offset:512
	global_load_dwordx4 v[112:115], v[134:135], off offset:576
	s_waitcnt vmcnt(0)
	v_pk_fma_f32 v[98:99], v[98:99], v[106:107], v[114:115]
	v_or_b32_e32 v100, 32, v152
	v_pk_fma_f32 v[96:97], v[96:97], v[104:105], v[112:113]
	global_store_dwordx4 v[128:129], v[96:99], off offset:576
	s_and_saveexec_b64 s[12:13], vcc
	s_xor_b64 s[12:13], exec, s[12:13]
	v_add_u32_e32 v186, 0xffffc020, v152
	v_lshlrev_b64 v[96:97], 13, v[186:187]
	v_mov_b32_e32 v101, v187
	v_lshl_add_u64 v[98:99], s[10:11], 0, v[96:97]
	v_lshlrev_b64 v[96:97], 13, v[100:101]
	s_andn2_saveexec_b64 s[12:13], s[12:13]
	v_ashrrev_i32_e32 v101, 31, v100
	v_lshlrev_b64 v[96:97], 13, v[100:101]
	v_lshl_add_u64 v[98:99], s[66:67], 0, v[96:97]
	s_or_b64 exec, exec, s[12:13]
	v_lshl_add_u64 v[102:103], v[98:99], 0, v[154:155]
	global_load_dwordx4 v[98:101], v[102:103], off
	v_lshl_add_u64 v[96:97], s[66:67], 0, v[96:97]
	v_lshl_add_u64 v[96:97], v[96:97], 0, v[154:155]
	s_movk_i32 s4, 0x3fcf
	v_cmp_lt_i32_e32 vcc, s4, v152
	s_waitcnt vmcnt(0)
	v_pk_fma_f32 v[94:95], v[94:95], v[126:127], v[100:101]
	v_pk_fma_f32 v[92:93], v[92:93], v[124:125], v[98:99]
	global_store_dwordx4 v[96:97], v[92:95], off
	global_load_dwordx4 v[92:95], v[102:103], off offset:64
	s_waitcnt vmcnt(0)
	v_pk_fma_f32 v[90:91], v[90:91], v[118:119], v[94:95]
	v_pk_fma_f32 v[88:89], v[88:89], v[116:117], v[92:93]
	global_store_dwordx4 v[96:97], v[88:91], off offset:64
	global_load_dwordx4 v[88:91], v[102:103], off offset:512
	s_waitcnt vmcnt(0)
	v_pk_fma_f32 v[86:87], v[86:87], v[110:111], v[90:91]
	v_pk_fma_f32 v[84:85], v[84:85], v[108:109], v[88:89]
	global_store_dwordx4 v[96:97], v[84:87], off offset:512
	global_load_dwordx4 v[86:89], v[102:103], off offset:576
	s_waitcnt vmcnt(0)
	v_pk_fma_f32 v[82:83], v[82:83], v[106:107], v[88:89]
	v_or_b32_e32 v84, 48, v152
	v_pk_fma_f32 v[80:81], v[80:81], v[104:105], v[86:87]
	global_store_dwordx4 v[96:97], v[80:83], off offset:576
	s_and_saveexec_b64 s[12:13], vcc
	s_xor_b64 s[12:13], exec, s[12:13]
	v_add_u32_e32 v186, 0xffffc030, v152
	v_lshlrev_b64 v[80:81], 13, v[186:187]
	v_mov_b32_e32 v85, v187
	v_lshl_add_u64 v[82:83], s[10:11], 0, v[80:81]
	v_lshlrev_b64 v[80:81], 13, v[84:85]
	s_andn2_saveexec_b64 s[12:13], s[12:13]
	v_ashrrev_i32_e32 v85, 31, v84
	v_lshlrev_b64 v[80:81], 13, v[84:85]
	v_lshl_add_u64 v[82:83], s[66:67], 0, v[80:81]
	s_or_b64 exec, exec, s[12:13]
	v_lshl_add_u64 v[86:87], v[82:83], 0, v[154:155]
	global_load_dwordx4 v[82:85], v[86:87], off
	v_lshl_add_u64 v[80:81], s[66:67], 0, v[80:81]
	v_lshl_add_u64 v[80:81], v[80:81], 0, v[154:155]
	s_movk_i32 s4, 0x3f7f
	v_cmp_lt_i32_e32 vcc, s4, v152
	s_waitcnt vmcnt(0)
	v_pk_fma_f32 v[78:79], v[78:79], v[126:127], v[84:85]
	v_pk_fma_f32 v[76:77], v[76:77], v[124:125], v[82:83]
	global_store_dwordx4 v[80:81], v[76:79], off
	global_load_dwordx4 v[76:79], v[86:87], off offset:64
	s_waitcnt vmcnt(0)
	v_pk_fma_f32 v[74:75], v[74:75], v[118:119], v[78:79]
	v_pk_fma_f32 v[72:73], v[72:73], v[116:117], v[76:77]
	global_store_dwordx4 v[80:81], v[72:75], off offset:64
	global_load_dwordx4 v[72:75], v[86:87], off offset:512
	s_waitcnt vmcnt(0)
	v_pk_fma_f32 v[70:71], v[70:71], v[110:111], v[74:75]
	v_pk_fma_f32 v[68:69], v[68:69], v[108:109], v[72:73]
	global_store_dwordx4 v[80:81], v[68:71], off offset:512
	global_load_dwordx4 v[70:73], v[86:87], off offset:576
	s_waitcnt vmcnt(0)
	v_pk_fma_f32 v[66:67], v[66:67], v[106:107], v[72:73]
	v_add_u32_e32 v68, 0x80, v152
	v_pk_fma_f32 v[64:65], v[64:65], v[104:105], v[70:71]
	global_store_dwordx4 v[80:81], v[64:67], off offset:576
	s_and_saveexec_b64 s[12:13], vcc
	s_xor_b64 s[12:13], exec, s[12:13]
	v_add_u32_e32 v186, 0xffffc080, v152
	v_lshlrev_b64 v[64:65], 13, v[186:187]
	v_mov_b32_e32 v69, v187
	v_lshl_add_u64 v[66:67], s[10:11], 0, v[64:65]
	v_lshlrev_b64 v[64:65], 13, v[68:69]
	s_andn2_saveexec_b64 s[12:13], s[12:13]
	v_ashrrev_i32_e32 v69, 31, v68
	v_lshlrev_b64 v[64:65], 13, v[68:69]
	v_lshl_add_u64 v[66:67], s[66:67], 0, v[64:65]
	s_or_b64 exec, exec, s[12:13]
	v_lshl_add_u64 v[70:71], v[66:67], 0, v[154:155]
	global_load_dwordx4 v[66:69], v[70:71], off
	v_lshl_add_u64 v[64:65], s[66:67], 0, v[64:65]
	v_lshl_add_u64 v[64:65], v[64:65], 0, v[154:155]
	s_movk_i32 s4, 0x3f6f
	v_cmp_lt_i32_e32 vcc, s4, v152
	s_waitcnt vmcnt(0)
	v_pk_fma_f32 v[62:63], v[62:63], v[126:127], v[68:69]
	v_pk_fma_f32 v[60:61], v[60:61], v[124:125], v[66:67]
	global_store_dwordx4 v[64:65], v[60:63], off
	global_load_dwordx4 v[60:63], v[70:71], off offset:64
	s_waitcnt vmcnt(0)
	v_pk_fma_f32 v[58:59], v[58:59], v[118:119], v[62:63]
	v_pk_fma_f32 v[56:57], v[56:57], v[116:117], v[60:61]
	global_store_dwordx4 v[64:65], v[56:59], off offset:64
	global_load_dwordx4 v[56:59], v[70:71], off offset:512
	s_waitcnt vmcnt(0)
	v_pk_fma_f32 v[54:55], v[54:55], v[110:111], v[58:59]
	v_pk_fma_f32 v[52:53], v[52:53], v[108:109], v[56:57]
	global_store_dwordx4 v[64:65], v[52:55], off offset:512
	global_load_dwordx4 v[54:57], v[70:71], off offset:576
	s_waitcnt vmcnt(0)
	v_pk_fma_f32 v[50:51], v[50:51], v[106:107], v[56:57]
	v_add_u32_e32 v52, 0x90, v152
	v_pk_fma_f32 v[48:49], v[48:49], v[104:105], v[54:55]
	global_store_dwordx4 v[64:65], v[48:51], off offset:576
	s_and_saveexec_b64 s[12:13], vcc
	s_xor_b64 s[12:13], exec, s[12:13]
	v_add_u32_e32 v186, 0xffffc090, v152
	v_lshlrev_b64 v[48:49], 13, v[186:187]
	v_mov_b32_e32 v53, v187
	v_lshl_add_u64 v[50:51], s[10:11], 0, v[48:49]
	v_lshlrev_b64 v[48:49], 13, v[52:53]
	s_andn2_saveexec_b64 s[12:13], s[12:13]
	v_ashrrev_i32_e32 v53, 31, v52
	v_lshlrev_b64 v[48:49], 13, v[52:53]
	v_lshl_add_u64 v[50:51], s[66:67], 0, v[48:49]
	s_or_b64 exec, exec, s[12:13]
	v_lshl_add_u64 v[54:55], v[50:51], 0, v[154:155]
	global_load_dwordx4 v[50:53], v[54:55], off
	v_lshl_add_u64 v[48:49], s[66:67], 0, v[48:49]
	v_lshl_add_u64 v[48:49], v[48:49], 0, v[154:155]
	s_movk_i32 s4, 0x3f5f
	v_cmp_lt_i32_e32 vcc, s4, v152
	s_waitcnt vmcnt(0)
	v_pk_fma_f32 v[46:47], v[46:47], v[126:127], v[52:53]
	v_pk_fma_f32 v[44:45], v[44:45], v[124:125], v[50:51]
	global_store_dwordx4 v[48:49], v[44:47], off
	global_load_dwordx4 v[44:47], v[54:55], off offset:64
	s_waitcnt vmcnt(0)
	v_pk_fma_f32 v[42:43], v[42:43], v[118:119], v[46:47]
	v_pk_fma_f32 v[40:41], v[40:41], v[116:117], v[44:45]
	global_store_dwordx4 v[48:49], v[40:43], off offset:64
	global_load_dwordx4 v[40:43], v[54:55], off offset:512
	s_waitcnt vmcnt(0)
	v_pk_fma_f32 v[38:39], v[38:39], v[110:111], v[42:43]
	v_pk_fma_f32 v[36:37], v[36:37], v[108:109], v[40:41]
	global_store_dwordx4 v[48:49], v[36:39], off offset:512
	global_load_dwordx4 v[38:41], v[54:55], off offset:576
	s_waitcnt vmcnt(0)
	v_pk_fma_f32 v[34:35], v[34:35], v[106:107], v[40:41]
	v_add_u32_e32 v36, 0xa0, v152
	v_pk_fma_f32 v[32:33], v[32:33], v[104:105], v[38:39]
	global_store_dwordx4 v[48:49], v[32:35], off offset:576
	s_and_saveexec_b64 s[12:13], vcc
	s_xor_b64 s[12:13], exec, s[12:13]
	v_add_u32_e32 v186, 0xffffc0a0, v152
	v_lshlrev_b64 v[32:33], 13, v[186:187]
	v_mov_b32_e32 v37, v187
	v_lshl_add_u64 v[34:35], s[10:11], 0, v[32:33]
	v_lshlrev_b64 v[32:33], 13, v[36:37]
	s_andn2_saveexec_b64 s[12:13], s[12:13]
	v_ashrrev_i32_e32 v37, 31, v36
	v_lshlrev_b64 v[32:33], 13, v[36:37]
	v_lshl_add_u64 v[34:35], s[66:67], 0, v[32:33]
	s_or_b64 exec, exec, s[12:13]
	v_lshl_add_u64 v[38:39], v[34:35], 0, v[154:155]
	global_load_dwordx4 v[34:37], v[38:39], off
	v_lshl_add_u64 v[32:33], s[66:67], 0, v[32:33]
	v_lshl_add_u64 v[32:33], v[32:33], 0, v[154:155]
	s_movk_i32 s4, 0x3f4f
	v_cmp_lt_i32_e32 vcc, s4, v152
	s_waitcnt vmcnt(0)
	v_pk_fma_f32 v[30:31], v[30:31], v[126:127], v[36:37]
	v_pk_fma_f32 v[28:29], v[28:29], v[124:125], v[34:35]
	global_store_dwordx4 v[32:33], v[28:31], off
	global_load_dwordx4 v[28:31], v[38:39], off offset:64
	s_waitcnt vmcnt(0)
	v_pk_fma_f32 v[26:27], v[26:27], v[118:119], v[30:31]
	v_pk_fma_f32 v[24:25], v[24:25], v[116:117], v[28:29]
	global_store_dwordx4 v[32:33], v[24:27], off offset:64
	global_load_dwordx4 v[24:27], v[38:39], off offset:512
	s_waitcnt vmcnt(0)
	v_pk_fma_f32 v[22:23], v[22:23], v[110:111], v[26:27]
	v_pk_fma_f32 v[20:21], v[20:21], v[108:109], v[24:25]
	global_store_dwordx4 v[32:33], v[20:23], off offset:512
	global_load_dwordx4 v[22:25], v[38:39], off offset:576
	s_waitcnt vmcnt(0)
	v_pk_fma_f32 v[18:19], v[18:19], v[106:107], v[24:25]
	v_add_u32_e32 v20, 0xb0, v152
	v_pk_fma_f32 v[16:17], v[16:17], v[104:105], v[22:23]
	global_store_dwordx4 v[32:33], v[16:19], off offset:576
	s_and_saveexec_b64 s[12:13], vcc
	s_xor_b64 s[12:13], exec, s[12:13]
	v_add_u32_e32 v186, 0xffffc0b0, v152
	v_lshlrev_b64 v[16:17], 13, v[186:187]
	v_mov_b32_e32 v21, v187
	v_lshl_add_u64 v[16:17], s[10:11], 0, v[16:17]
	v_lshlrev_b64 v[18:19], 13, v[20:21]
	s_andn2_saveexec_b64 s[12:13], s[12:13]
	s_cbranch_execz .LBB0_881
	v_ashrrev_i32_e32 v21, 31, v20
	v_lshlrev_b64 v[18:19], 13, v[20:21]
	v_lshl_add_u64 v[16:17], s[66:67], 0, v[18:19]
	s_branch .LBB0_881

.LBB0_940:
	s_add_i32 s63, 0, 0x10000
	v_add_u32_e32 v152, s63, v138
	ds_read_b128 v[140:143], v152
	ds_read_b128 v[144:147], v152 offset:1024
	ds_read_b128 v[148:151], v152 offset:2048
	ds_read_b128 v[152:155], v152 offset:3072
	ds_read_b128 v[156:159], v139
	ds_read_b128 v[162:165], v139 offset:1024
	ds_read_b128 v[166:169], v139 offset:2048
	ds_read_b128 v[170:173], v139 offset:3072
	ds_read_b128 v[174:177], v139 offset:4096
	ds_read_b128 v[178:181], v139 offset:5120
	ds_read_b128 v[196:199], v139 offset:6144
	ds_read_b128 v[200:203], v139 offset:7168
	s_add_u32 s24, s2, vcc_lo
	s_addc_u32 s25, s3, vcc_hi
	s_add_u32 s24, s24, 0x100
	s_addc_u32 s25, s25, 0
	s_add_u32 s61, s19, vcc_lo
	s_addc_u32 s62, s4, vcc_hi
	s_cmpk_eq_i32 vcc_lo, 0x3f00
	s_cselect_b32 s27, s39, s25
	s_cselect_b32 s26, s58, s24
	s_cselect_b32 s25, s29, s62
	s_cselect_b32 s24, s59, s61
	v_lshl_add_u64 v[182:183], v[134:135], 0, vcc
	s_add_i32 m0, s23, 0xc000
	global_load_lds_dwordx4 v[182:183], off
	v_lshl_add_u64 v[182:183], v[136:137], 0, vcc
	s_add_i32 m0, s23, 0xe000
	s_nop 0
	global_load_lds_dwordx4 v[182:183], off
	v_add_u32_e32 v216, 0x14000, v138
	ds_read_b128 v[204:207], v216
	ds_read_b128 v[208:211], v216 offset:1024
	ds_read_b128 v[212:215], v216 offset:2048
	ds_read_b128 v[216:219], v216 offset:3072
	s_waitcnt vmcnt(8)
	s_waitcnt lgkmcnt(0)
	s_barrier
	s_setprio 1
	v_mfma_f32_16x16x32_bf16 v[124:127], v[140:143], v[156:159], v[124:127]
	v_mfma_f32_16x16x32_bf16 v[120:123], v[148:151], v[156:159], v[120:123]
	v_mfma_f32_16x16x32_bf16 v[108:111], v[140:143], v[166:169], v[108:111]
	v_mfma_f32_16x16x32_bf16 v[104:107], v[148:151], v[166:169], v[104:107]
	v_mfma_f32_16x16x32_bf16 v[92:95], v[140:143], v[174:177], v[92:95]
	v_mfma_f32_16x16x32_bf16 v[88:91], v[148:151], v[174:177], v[88:91]
	v_mfma_f32_16x16x32_bf16 v[76:79], v[140:143], v[196:199], v[76:79]
	v_mfma_f32_16x16x32_bf16 v[72:75], v[148:151], v[196:199], v[72:75]
	v_mfma_f32_16x16x32_bf16 v[124:127], v[144:147], v[162:165], v[124:127]
	v_mfma_f32_16x16x32_bf16 v[120:123], v[152:155], v[162:165], v[120:123]
	v_mfma_f32_16x16x32_bf16 v[108:111], v[144:147], v[170:173], v[108:111]
	v_mfma_f32_16x16x32_bf16 v[104:107], v[152:155], v[170:173], v[104:107]
	v_mfma_f32_16x16x32_bf16 v[92:95], v[144:147], v[178:181], v[92:95]
	v_mfma_f32_16x16x32_bf16 v[88:91], v[152:155], v[178:181], v[88:91]
	v_mfma_f32_16x16x32_bf16 v[76:79], v[144:147], v[200:203], v[76:79]
	v_mfma_f32_16x16x32_bf16 v[72:75], v[152:155], v[200:203], v[72:75]
	v_mfma_f32_16x16x32_bf16 v[116:119], v[204:207], v[156:159], v[116:119]
	v_mfma_f32_16x16x32_bf16 v[112:115], v[212:215], v[156:159], v[112:115]
	v_mfma_f32_16x16x32_bf16 v[100:103], v[204:207], v[166:169], v[100:103]
	v_mfma_f32_16x16x32_bf16 v[96:99], v[212:215], v[166:169], v[96:99]
	v_mfma_f32_16x16x32_bf16 v[84:87], v[204:207], v[174:177], v[84:87]
	v_mfma_f32_16x16x32_bf16 v[80:83], v[212:215], v[174:177], v[80:83]
	v_mfma_f32_16x16x32_bf16 v[68:71], v[204:207], v[196:199], v[68:71]
	v_mfma_f32_16x16x32_bf16 v[64:67], v[212:215], v[196:199], v[64:67]
	v_mfma_f32_16x16x32_bf16 v[116:119], v[208:211], v[162:165], v[116:119]
	v_mfma_f32_16x16x32_bf16 v[112:115], v[216:219], v[162:165], v[112:115]
	v_mfma_f32_16x16x32_bf16 v[100:103], v[208:211], v[170:173], v[100:103]
	v_mfma_f32_16x16x32_bf16 v[96:99], v[216:219], v[170:173], v[96:99]
	v_mfma_f32_16x16x32_bf16 v[84:87], v[208:211], v[178:181], v[84:87]
	v_mfma_f32_16x16x32_bf16 v[80:83], v[216:219], v[178:181], v[80:83]
	v_mfma_f32_16x16x32_bf16 v[68:71], v[208:211], v[200:203], v[68:71]
	v_mfma_f32_16x16x32_bf16 v[64:67], v[216:219], v[200:203], v[64:67]
	s_setprio 0
	s_barrier
	ds_read_b128 v[156:159], v139 offset:16384
	ds_read_b128 v[162:165], v139 offset:17408
	ds_read_b128 v[166:169], v139 offset:18432
	ds_read_b128 v[170:173], v139 offset:19456
	ds_read_b128 v[174:177], v139 offset:20480
	ds_read_b128 v[178:181], v139 offset:21504
	ds_read_b128 v[196:199], v139 offset:22528
	ds_read_b128 v[200:203], v139 offset:23552
	s_add_i32 s61, 0, 0x14000
	s_add_i32 s62, s63, s17
	v_lshl_add_u64 v[182:183], s[24:25], 0, v[186:187]
	s_mov_b32 m0, s62
	global_load_lds_dwordx4 v[182:183], off
	v_lshl_add_u64 v[220:221], s[24:25], 0, v[128:129]
	s_add_i32 m0, s62, 0x2000
	s_nop 0
	global_load_lds_dwordx4 v[220:221], off
	s_mov_b32 m0, s23
	v_lshl_add_u64 v[222:223], s[26:27], 0, v[186:187]
	global_load_lds_dwordx4 v[222:223], off
	v_lshl_add_u64 v[224:225], s[26:27], 0, v[128:129]
	s_mov_b32 m0, s30
	s_nop 0
	global_load_lds_dwordx4 v[224:225], off
	s_waitcnt vmcnt(6)
	s_waitcnt lgkmcnt(0)
	s_barrier
	s_setprio 1
	v_mfma_f32_16x16x32_bf16 v[60:63], v[140:143], v[156:159], v[60:63]
	v_mfma_f32_16x16x32_bf16 v[56:59], v[148:151], v[156:159], v[56:59]
	v_mfma_f32_16x16x32_bf16 v[44:47], v[140:143], v[166:169], v[44:47]
	v_mfma_f32_16x16x32_bf16 v[40:43], v[148:151], v[166:169], v[40:43]
	v_mfma_f32_16x16x32_bf16 v[32:35], v[140:143], v[174:177], v[32:35]
	v_mfma_f32_16x16x32_bf16 v[24:27], v[148:151], v[174:177], v[24:27]
	v_mfma_f32_16x16x32_bf16 v[16:19], v[140:143], v[196:199], v[16:19]
	v_mfma_f32_16x16x32_bf16 v[8:11], v[148:151], v[196:199], v[8:11]
	v_mfma_f32_16x16x32_bf16 v[60:63], v[144:147], v[162:165], v[60:63]
	v_mfma_f32_16x16x32_bf16 v[56:59], v[152:155], v[162:165], v[56:59]
	v_mfma_f32_16x16x32_bf16 v[44:47], v[144:147], v[170:173], v[44:47]
	v_mfma_f32_16x16x32_bf16 v[40:43], v[152:155], v[170:173], v[40:43]
	v_mfma_f32_16x16x32_bf16 v[32:35], v[144:147], v[178:181], v[32:35]
	v_mfma_f32_16x16x32_bf16 v[24:27], v[152:155], v[178:181], v[24:27]
	v_mfma_f32_16x16x32_bf16 v[16:19], v[144:147], v[200:203], v[16:19]
	v_mfma_f32_16x16x32_bf16 v[8:11], v[152:155], v[200:203], v[8:11]
	v_mfma_f32_16x16x32_bf16 v[52:55], v[204:207], v[156:159], v[52:55]
	v_mfma_f32_16x16x32_bf16 v[48:51], v[212:215], v[156:159], v[48:51]
	v_mfma_f32_16x16x32_bf16 v[36:39], v[204:207], v[166:169], v[36:39]
	v_mfma_f32_16x16x32_bf16 v[28:31], v[212:215], v[166:169], v[28:31]
	v_mfma_f32_16x16x32_bf16 v[20:23], v[204:207], v[174:177], v[20:23]
	v_mfma_f32_16x16x32_bf16 v[12:15], v[212:215], v[174:177], v[12:15]
	v_mfma_f32_16x16x32_bf16 v[4:7], v[204:207], v[196:199], v[4:7]
	v_mfma_f32_16x16x32_bf16 v[0:3], v[212:215], v[196:199], v[0:3]
	v_mfma_f32_16x16x32_bf16 v[52:55], v[208:211], v[162:165], v[52:55]
	v_mfma_f32_16x16x32_bf16 v[48:51], v[216:219], v[162:165], v[48:51]
	v_mfma_f32_16x16x32_bf16 v[36:39], v[208:211], v[170:173], v[36:39]
	v_mfma_f32_16x16x32_bf16 v[28:31], v[216:219], v[170:173], v[28:31]
	v_mfma_f32_16x16x32_bf16 v[20:23], v[208:211], v[178:181], v[20:23]
	v_mfma_f32_16x16x32_bf16 v[12:15], v[216:219], v[178:181], v[12:15]
	v_mfma_f32_16x16x32_bf16 v[4:7], v[208:211], v[200:203], v[4:7]
	v_mfma_f32_16x16x32_bf16 v[0:3], v[216:219], v[200:203], v[0:3]
	s_setprio 0
	s_barrier
	s_add_u32 s62, s24, 0x200000
	s_addc_u32 s63, s25, 0
	s_add_i32 s61, s61, s17
	v_lshl_add_u64 v[140:141], s[62:63], 0, v[186:187]
	s_mov_b32 m0, s61
	s_nop 0
	global_load_lds_dwordx4 v[140:141], off
	v_lshl_add_u64 v[140:141], s[62:63], 0, v[128:129]
	s_add_i32 m0, s61, 0x2000
	s_nop 0
	global_load_lds_dwordx4 v[140:141], off
	s_add_i32 s61, 0, 0x18000
	v_add_u32_e32 v152, s61, v138
	ds_read_b128 v[140:143], v152
	ds_read_b128 v[144:147], v152 offset:1024
	ds_read_b128 v[148:151], v152 offset:2048
	ds_read_b128 v[152:155], v152 offset:3072
	ds_read_b128 v[156:159], v139 offset:32768
	ds_read_b128 v[162:165], v139 offset:33792
	ds_read_b128 v[166:169], v139 offset:34816
	ds_read_b128 v[170:173], v139 offset:35840
	ds_read_b128 v[174:177], v139 offset:36864
	ds_read_b128 v[178:181], v139 offset:37888
	ds_read_b128 v[196:199], v139 offset:38912
	ds_read_b128 v[200:203], v139 offset:39936
	s_add_u32 s26, s26, 0x200000
	s_addc_u32 s27, s27, 0
	s_mov_b32 m0, s31
	v_lshl_add_u64 v[204:205], s[26:27], 0, v[186:187]
	global_load_lds_dwordx4 v[204:205], off
	v_lshl_add_u64 v[204:205], s[26:27], 0, v[128:129]
	s_mov_b32 m0, s52
	s_nop 0
	global_load_lds_dwordx4 v[204:205], off
	v_add_u32_e32 v216, 0x1c000, v138
	ds_read_b128 v[204:207], v216
	ds_read_b128 v[208:211], v216 offset:1024
	ds_read_b128 v[212:215], v216 offset:2048
	ds_read_b128 v[216:219], v216 offset:3072
	s_waitcnt vmcnt(8)
	s_waitcnt lgkmcnt(0)
	s_barrier
	s_setprio 1
	v_mfma_f32_16x16x32_bf16 v[124:127], v[140:143], v[156:159], v[124:127]
	v_mfma_f32_16x16x32_bf16 v[120:123], v[148:151], v[156:159], v[120:123]
	v_mfma_f32_16x16x32_bf16 v[108:111], v[140:143], v[166:169], v[108:111]
	v_mfma_f32_16x16x32_bf16 v[104:107], v[148:151], v[166:169], v[104:107]
	v_mfma_f32_16x16x32_bf16 v[92:95], v[140:143], v[174:177], v[92:95]
	v_mfma_f32_16x16x32_bf16 v[88:91], v[148:151], v[174:177], v[88:91]
	v_mfma_f32_16x16x32_bf16 v[76:79], v[140:143], v[196:199], v[76:79]
	v_mfma_f32_16x16x32_bf16 v[72:75], v[148:151], v[196:199], v[72:75]
	v_mfma_f32_16x16x32_bf16 v[124:127], v[144:147], v[162:165], v[124:127]
	v_mfma_f32_16x16x32_bf16 v[120:123], v[152:155], v[162:165], v[120:123]
	v_mfma_f32_16x16x32_bf16 v[108:111], v[144:147], v[170:173], v[108:111]
	v_mfma_f32_16x16x32_bf16 v[104:107], v[152:155], v[170:173], v[104:107]
	v_mfma_f32_16x16x32_bf16 v[92:95], v[144:147], v[178:181], v[92:95]
	v_mfma_f32_16x16x32_bf16 v[88:91], v[152:155], v[178:181], v[88:91]
	v_mfma_f32_16x16x32_bf16 v[76:79], v[144:147], v[200:203], v[76:79]
	v_mfma_f32_16x16x32_bf16 v[72:75], v[152:155], v[200:203], v[72:75]
	v_mfma_f32_16x16x32_bf16 v[116:119], v[204:207], v[156:159], v[116:119]
	v_mfma_f32_16x16x32_bf16 v[112:115], v[212:215], v[156:159], v[112:115]
	v_mfma_f32_16x16x32_bf16 v[100:103], v[204:207], v[166:169], v[100:103]
	v_mfma_f32_16x16x32_bf16 v[96:99], v[212:215], v[166:169], v[96:99]
	v_mfma_f32_16x16x32_bf16 v[84:87], v[204:207], v[174:177], v[84:87]
	v_mfma_f32_16x16x32_bf16 v[80:83], v[212:215], v[174:177], v[80:83]
	v_mfma_f32_16x16x32_bf16 v[68:71], v[204:207], v[196:199], v[68:71]
	v_mfma_f32_16x16x32_bf16 v[64:67], v[212:215], v[196:199], v[64:67]
	v_mfma_f32_16x16x32_bf16 v[116:119], v[208:211], v[162:165], v[116:119]
	v_mfma_f32_16x16x32_bf16 v[112:115], v[216:219], v[162:165], v[112:115]
	v_mfma_f32_16x16x32_bf16 v[100:103], v[208:211], v[170:173], v[100:103]
	v_mfma_f32_16x16x32_bf16 v[96:99], v[216:219], v[170:173], v[96:99]
	v_mfma_f32_16x16x32_bf16 v[84:87], v[208:211], v[178:181], v[84:87]
	v_mfma_f32_16x16x32_bf16 v[80:83], v[216:219], v[178:181], v[80:83]
	v_mfma_f32_16x16x32_bf16 v[68:71], v[208:211], v[200:203], v[68:71]
	v_mfma_f32_16x16x32_bf16 v[64:67], v[216:219], v[200:203], v[64:67]
	s_setprio 0
	s_barrier
	ds_read_b128 v[156:159], v139 offset:49152
	ds_read_b128 v[162:165], v139 offset:50176
	ds_read_b128 v[166:169], v139 offset:51200
	ds_read_b128 v[170:173], v139 offset:52224
	ds_read_b128 v[174:177], v139 offset:53248
	ds_read_b128 v[178:181], v139 offset:54272
	ds_read_b128 v[196:199], v139 offset:55296
	ds_read_b128 v[200:203], v139 offset:56320
	s_add_i32 s26, 0, 0x1c000
	s_add_i32 s27, s61, s17
	v_lshl_add_u64 v[182:183], v[182:183], 0, s[0:1]
	s_mov_b32 m0, s27
	global_load_lds_dwordx4 v[182:183], off
	v_lshl_add_u64 v[182:183], v[220:221], 0, s[0:1]
	s_add_i32 m0, s27, 0x2000
	s_nop 0
	global_load_lds_dwordx4 v[182:183], off
	s_mov_b32 m0, s53
	v_lshl_add_u64 v[182:183], v[222:223], 0, s[0:1]
	global_load_lds_dwordx4 v[182:183], off
	v_lshl_add_u64 v[182:183], v[224:225], 0, s[0:1]
	s_mov_b32 m0, s68
	s_nop 0
	global_load_lds_dwordx4 v[182:183], off
	s_add_u32 s24, s24, 0x200080
	s_addc_u32 s25, s25, 0
	s_add_i32 s26, s26, s17
	v_lshl_add_u64 v[182:183], s[24:25], 0, v[186:187]
	s_mov_b32 m0, s26
	s_nop 0
	global_load_lds_dwordx4 v[182:183], off
	v_lshl_add_u64 v[182:183], s[24:25], 0, v[128:129]
	s_add_i32 m0, s26, 0x2000
	s_nop 0
	global_load_lds_dwordx4 v[182:183], off
	s_waitcnt vmcnt(8)
	s_waitcnt lgkmcnt(0)
	s_barrier
	s_setprio 1
	v_mfma_f32_16x16x32_bf16 v[60:63], v[140:143], v[156:159], v[60:63]
	v_mfma_f32_16x16x32_bf16 v[56:59], v[148:151], v[156:159], v[56:59]
	v_mfma_f32_16x16x32_bf16 v[44:47], v[140:143], v[166:169], v[44:47]
	v_mfma_f32_16x16x32_bf16 v[40:43], v[148:151], v[166:169], v[40:43]
	v_mfma_f32_16x16x32_bf16 v[32:35], v[140:143], v[174:177], v[32:35]
	v_mfma_f32_16x16x32_bf16 v[24:27], v[148:151], v[174:177], v[24:27]
	v_mfma_f32_16x16x32_bf16 v[16:19], v[140:143], v[196:199], v[16:19]
	v_mfma_f32_16x16x32_bf16 v[8:11], v[148:151], v[196:199], v[8:11]
	v_mfma_f32_16x16x32_bf16 v[60:63], v[144:147], v[162:165], v[60:63]
	v_mfma_f32_16x16x32_bf16 v[56:59], v[152:155], v[162:165], v[56:59]
	v_mfma_f32_16x16x32_bf16 v[44:47], v[144:147], v[170:173], v[44:47]
	v_mfma_f32_16x16x32_bf16 v[40:43], v[152:155], v[170:173], v[40:43]
	v_mfma_f32_16x16x32_bf16 v[32:35], v[144:147], v[178:181], v[32:35]
	v_mfma_f32_16x16x32_bf16 v[24:27], v[152:155], v[178:181], v[24:27]
	v_mfma_f32_16x16x32_bf16 v[16:19], v[144:147], v[200:203], v[16:19]
	v_mfma_f32_16x16x32_bf16 v[8:11], v[152:155], v[200:203], v[8:11]
	v_mfma_f32_16x16x32_bf16 v[52:55], v[204:207], v[156:159], v[52:55]
	v_mfma_f32_16x16x32_bf16 v[48:51], v[212:215], v[156:159], v[48:51]
	v_mfma_f32_16x16x32_bf16 v[36:39], v[204:207], v[166:169], v[36:39]
	v_mfma_f32_16x16x32_bf16 v[28:31], v[212:215], v[166:169], v[28:31]
	v_mfma_f32_16x16x32_bf16 v[20:23], v[204:207], v[174:177], v[20:23]
	v_mfma_f32_16x16x32_bf16 v[12:15], v[212:215], v[174:177], v[12:15]
	v_mfma_f32_16x16x32_bf16 v[4:7], v[204:207], v[196:199], v[4:7]
	v_mfma_f32_16x16x32_bf16 v[0:3], v[212:215], v[196:199], v[0:3]
	v_mfma_f32_16x16x32_bf16 v[52:55], v[208:211], v[162:165], v[52:55]
	v_mfma_f32_16x16x32_bf16 v[48:51], v[216:219], v[162:165], v[48:51]
	v_mfma_f32_16x16x32_bf16 v[36:39], v[208:211], v[170:173], v[36:39]
	v_mfma_f32_16x16x32_bf16 v[28:31], v[216:219], v[170:173], v[28:31]
	v_mfma_f32_16x16x32_bf16 v[20:23], v[208:211], v[178:181], v[20:23]
	v_mfma_f32_16x16x32_bf16 v[12:15], v[216:219], v[178:181], v[12:15]
	v_mfma_f32_16x16x32_bf16 v[4:7], v[208:211], v[200:203], v[4:7]
	v_mfma_f32_16x16x32_bf16 v[0:3], v[216:219], v[200:203], v[0:3]
	s_setprio 0
	s_add_i32 s60, s60, 2
	s_add_u32 vcc_lo, vcc_lo, 0x100
	s_addc_u32 vcc_hi, vcc_hi, 0
	s_cmpk_gt_u32 s60, 0x7d
	s_barrier
	s_cbranch_scc0 .LBB0_940
	s_add_u32 s24, s19, 0xffffff00
	s_addc_u32 s25, s4, -1
	s_andn2_b64 vcc, exec, s[44:45]
	s_cbranch_vccnz .LBB0_931
	v_mov_b32_e32 v0, 0
	s_mov_b32 s18, s28
	s_mov_b32 s56, s38
	s_mov_b64 s[2:3], s[20:21]
	s_mov_b32 s69, s57
	v_mov_b32_e32 v1, v0
	v_mov_b32_e32 v2, v0
	v_mov_b32_e32 v3, v0
	v_mov_b32_e32 v4, v0
	v_mov_b32_e32 v5, v0
	v_mov_b32_e32 v6, v0
	v_mov_b32_e32 v7, v0
	v_mov_b32_e32 v12, v0
	v_mov_b32_e32 v13, v0
	v_mov_b32_e32 v14, v0
	v_mov_b32_e32 v15, v0
	v_mov_b32_e32 v20, v0
	v_mov_b32_e32 v21, v0
	v_mov_b32_e32 v22, v0
	v_mov_b32_e32 v23, v0
	v_mov_b32_e32 v28, v0
	v_mov_b32_e32 v29, v0
	v_mov_b32_e32 v30, v0
	v_mov_b32_e32 v31, v0
	v_mov_b32_e32 v36, v0
	v_mov_b32_e32 v37, v0
	v_mov_b32_e32 v38, v0
	v_mov_b32_e32 v39, v0
	v_mov_b32_e32 v48, v0
	v_mov_b32_e32 v49, v0
	v_mov_b32_e32 v50, v0
	v_mov_b32_e32 v51, v0
	v_mov_b32_e32 v52, v0
	v_mov_b32_e32 v53, v0
	v_mov_b32_e32 v54, v0
	v_mov_b32_e32 v55, v0
	v_mov_b32_e32 v8, v0
	v_mov_b32_e32 v9, v0
	v_mov_b32_e32 v10, v0
	v_mov_b32_e32 v11, v0
	v_mov_b32_e32 v16, v0
	v_mov_b32_e32 v17, v0
	v_mov_b32_e32 v18, v0
	v_mov_b32_e32 v19, v0
	v_mov_b32_e32 v24, v0
	v_mov_b32_e32 v25, v0
	v_mov_b32_e32 v26, v0
	v_mov_b32_e32 v27, v0
	v_mov_b32_e32 v32, v0
	v_mov_b32_e32 v33, v0
	v_mov_b32_e32 v34, v0
	v_mov_b32_e32 v35, v0
	v_mov_b32_e32 v40, v0
	v_mov_b32_e32 v41, v0
	v_mov_b32_e32 v42, v0
	v_mov_b32_e32 v43, v0
	v_mov_b32_e32 v44, v0
	v_mov_b32_e32 v45, v0
	v_mov_b32_e32 v46, v0
	v_mov_b32_e32 v47, v0
	v_mov_b32_e32 v56, v0
	v_mov_b32_e32 v57, v0
	v_mov_b32_e32 v58, v0
	v_mov_b32_e32 v59, v0
	v_mov_b32_e32 v60, v0
	v_mov_b32_e32 v61, v0
	v_mov_b32_e32 v62, v0
	v_mov_b32_e32 v63, v0
	v_mov_b32_e32 v64, v0
	v_mov_b32_e32 v65, v0
	v_mov_b32_e32 v66, v0
	v_mov_b32_e32 v67, v0
	v_mov_b32_e32 v68, v0
	v_mov_b32_e32 v69, v0
	v_mov_b32_e32 v70, v0
	v_mov_b32_e32 v71, v0
	v_mov_b32_e32 v80, v0
	v_mov_b32_e32 v81, v0
	v_mov_b32_e32 v82, v0
	v_mov_b32_e32 v83, v0
	v_mov_b32_e32 v84, v0
	v_mov_b32_e32 v85, v0
	v_mov_b32_e32 v86, v0
	v_mov_b32_e32 v87, v0
	v_mov_b32_e32 v96, v0
	v_mov_b32_e32 v97, v0
	v_mov_b32_e32 v98, v0
	v_mov_b32_e32 v99, v0
	v_mov_b32_e32 v100, v0
	v_mov_b32_e32 v101, v0
	v_mov_b32_e32 v102, v0
	v_mov_b32_e32 v103, v0
	v_mov_b32_e32 v112, v0
	v_mov_b32_e32 v113, v0
	v_mov_b32_e32 v114, v0
	v_mov_b32_e32 v115, v0
	v_mov_b32_e32 v116, v0
	v_mov_b32_e32 v117, v0
	v_mov_b32_e32 v118, v0
	v_mov_b32_e32 v119, v0
	v_mov_b32_e32 v72, v0
	v_mov_b32_e32 v73, v0
	v_mov_b32_e32 v74, v0
	v_mov_b32_e32 v75, v0
	v_mov_b32_e32 v76, v0
	v_mov_b32_e32 v77, v0
	v_mov_b32_e32 v78, v0
	v_mov_b32_e32 v79, v0
	v_mov_b32_e32 v88, v0
	v_mov_b32_e32 v89, v0
	v_mov_b32_e32 v90, v0
	v_mov_b32_e32 v91, v0
	v_mov_b32_e32 v92, v0
	v_mov_b32_e32 v93, v0
	v_mov_b32_e32 v94, v0
	v_mov_b32_e32 v95, v0
	v_mov_b32_e32 v104, v0
	v_mov_b32_e32 v105, v0
	v_mov_b32_e32 v106, v0
	v_mov_b32_e32 v107, v0
	v_mov_b32_e32 v108, v0
	v_mov_b32_e32 v109, v0
	v_mov_b32_e32 v110, v0
	v_mov_b32_e32 v111, v0
	v_mov_b32_e32 v120, v0
	v_mov_b32_e32 v121, v0
	v_mov_b32_e32 v122, v0
	v_mov_b32_e32 v123, v0
	v_mov_b32_e32 v124, v0
	v_mov_b32_e32 v125, v0
	v_mov_b32_e32 v126, v0
	v_mov_b32_e32 v127, v0
	s_andn2_b64 vcc, exec, s[42:43]
	s_cbranch_vccnz .LBB0_932
